# Strategy: back-edge rotation (docs 7.11) generalised - scalar bookkeeping behind each post-MFMA barrier of the GEMM K-loops moved in front of the barrier
# baseline (speedup 1.0000x reference)
.LBB0_163:
	ds_read_b128 v[144:147], v151
	ds_read_b128 v[156:159], v151 offset:1024
	ds_read_b128 v[160:163], v151 offset:2048
	ds_read_b128 v[164:167], v151 offset:3072
	ds_read_b128 v[168:171], v152
	ds_read_b128 v[172:175], v152 offset:1024
	ds_read_b128 v[176:179], v152 offset:2048
	ds_read_b128 v[180:183], v152 offset:3072
	s_add_u32 s26, s24, 0xfffc0080
	s_addc_u32 s27, s25, -1
	s_cmp_eq_u32 s55, 12
	s_cselect_b32 s29, s19, s27
	s_cselect_b32 s28, s51, s26
	s_cselect_b32 s27, s17, s54
	s_cselect_b32 s26, s52, s53
	s_add_i32 m0, s38, 0xc000
	ds_read_b128 v[184:187], v153
	ds_read_b128 v[188:191], v153 offset:1024
	ds_read_b128 v[192:195], v153 offset:2048
	ds_read_b128 v[196:199], v153 offset:3072
	ds_read_b128 v[200:203], v153 offset:4096
	ds_read_b128 v[208:211], v153 offset:5120
	ds_read_b128 v[212:215], v153 offset:6144
	ds_read_b128 v[216:219], v153 offset:7168
	global_load_lds_dwordx4 v138, s[24:25]
	s_add_i32 m0, s38, 0xe000
	s_nop 0
	global_load_lds_dwordx4 v136, s[24:25]
	s_waitcnt vmcnt(8)
	s_waitcnt lgkmcnt(0)
	s_barrier
	s_waitcnt lgkmcnt(0)
	v_mfma_f32_16x16x32_bf16 v[124:127], v[144:147], v[184:187], v[124:127]
	v_mfma_f32_16x16x32_bf16 v[120:123], v[160:163], v[184:187], v[120:123]
	v_mfma_f32_16x16x32_bf16 v[108:111], v[144:147], v[192:195], v[108:111]
	v_mfma_f32_16x16x32_bf16 v[104:107], v[160:163], v[192:195], v[104:107]
	v_mfma_f32_16x16x32_bf16 v[92:95], v[144:147], v[200:203], v[92:95]
	v_mfma_f32_16x16x32_bf16 v[88:91], v[160:163], v[200:203], v[88:91]
	v_mfma_f32_16x16x32_bf16 v[76:79], v[144:147], v[212:215], v[76:79]
	v_mfma_f32_16x16x32_bf16 v[72:75], v[160:163], v[212:215], v[72:75]
	v_mfma_f32_16x16x32_bf16 v[124:127], v[156:159], v[188:191], v[124:127]
	v_mfma_f32_16x16x32_bf16 v[120:123], v[164:167], v[188:191], v[120:123]
	v_mfma_f32_16x16x32_bf16 v[108:111], v[156:159], v[196:199], v[108:111]
	v_mfma_f32_16x16x32_bf16 v[104:107], v[164:167], v[196:199], v[104:107]
	v_mfma_f32_16x16x32_bf16 v[92:95], v[156:159], v[208:211], v[92:95]
	v_mfma_f32_16x16x32_bf16 v[88:91], v[164:167], v[208:211], v[88:91]
	v_mfma_f32_16x16x32_bf16 v[76:79], v[156:159], v[216:219], v[76:79]
	v_mfma_f32_16x16x32_bf16 v[72:75], v[164:167], v[216:219], v[72:75]
	v_mfma_f32_16x16x32_bf16 v[116:119], v[168:171], v[184:187], v[116:119]
	v_mfma_f32_16x16x32_bf16 v[112:115], v[176:179], v[184:187], v[112:115]
	v_mfma_f32_16x16x32_bf16 v[100:103], v[168:171], v[192:195], v[100:103]
	v_mfma_f32_16x16x32_bf16 v[96:99], v[176:179], v[192:195], v[96:99]
	v_mfma_f32_16x16x32_bf16 v[84:87], v[168:171], v[200:203], v[84:87]
	v_mfma_f32_16x16x32_bf16 v[80:83], v[176:179], v[200:203], v[80:83]
	v_mfma_f32_16x16x32_bf16 v[68:71], v[168:171], v[212:215], v[68:71]
	v_mfma_f32_16x16x32_bf16 v[64:67], v[176:179], v[212:215], v[64:67]
	v_mfma_f32_16x16x32_bf16 v[116:119], v[172:175], v[188:191], v[116:119]
	v_mfma_f32_16x16x32_bf16 v[112:115], v[180:183], v[188:191], v[112:115]
	v_mfma_f32_16x16x32_bf16 v[100:103], v[172:175], v[196:199], v[100:103]
	v_mfma_f32_16x16x32_bf16 v[96:99], v[180:183], v[196:199], v[96:99]
	v_mfma_f32_16x16x32_bf16 v[84:87], v[172:175], v[208:211], v[84:87]
	v_mfma_f32_16x16x32_bf16 v[80:83], v[180:183], v[208:211], v[80:83]
	v_mfma_f32_16x16x32_bf16 v[68:71], v[172:175], v[216:219], v[68:71]
	v_mfma_f32_16x16x32_bf16 v[64:67], v[180:183], v[216:219], v[64:67]
	s_add_i32 s56, s48, s35
	s_mov_b32 m0, s56
	s_barrier
	ds_read_b128 v[184:187], v153 offset:16384
	ds_read_b128 v[188:191], v153 offset:17408
	ds_read_b128 v[192:195], v153 offset:18432
	ds_read_b128 v[196:199], v153 offset:19456
	ds_read_b128 v[200:203], v153 offset:20480
	ds_read_b128 v[208:211], v153 offset:21504
	ds_read_b128 v[212:215], v153 offset:22528
	ds_read_b128 v[216:219], v153 offset:23552
	global_load_lds_dwordx4 v132, s[26:27]
	s_add_i32 m0, s56, 0x2000
	s_add_u32 s56, s26, 0x40000
	s_mov_b64 s[98:99], s[26:27]
	s_addc_u32 s57, s27, 0
	s_add_i32 s58, s49, s35
	global_load_lds_dwordx4 v128, s[26:27]
	s_mov_b32 m0, s58
	s_mov_b64 s[100:101], s[28:29]
	global_load_lds_dwordx4 v132, s[56:57]
	s_add_i32 m0, s58, 0x2000
	s_nop 0
	global_load_lds_dwordx4 v128, s[56:57]
	s_mov_b32 m0, s38
	s_nop 0
	global_load_lds_dwordx4 v134, s[28:29]
	s_mov_b32 m0, s39
	s_nop 0
	global_load_lds_dwordx4 v130, s[28:29]
	s_waitcnt vmcnt(8)
	s_waitcnt lgkmcnt(0)
	s_barrier
	s_waitcnt lgkmcnt(0)
	v_mfma_f32_16x16x32_bf16 v[60:63], v[144:147], v[184:187], v[60:63]
	v_mfma_f32_16x16x32_bf16 v[56:59], v[160:163], v[184:187], v[56:59]
	v_mfma_f32_16x16x32_bf16 v[44:47], v[144:147], v[192:195], v[44:47]
	v_mfma_f32_16x16x32_bf16 v[40:43], v[160:163], v[192:195], v[40:43]
	v_mfma_f32_16x16x32_bf16 v[28:31], v[144:147], v[200:203], v[28:31]
	v_mfma_f32_16x16x32_bf16 v[24:27], v[160:163], v[200:203], v[24:27]
	v_mfma_f32_16x16x32_bf16 v[12:15], v[144:147], v[212:215], v[12:15]
	v_mfma_f32_16x16x32_bf16 v[8:11], v[160:163], v[212:215], v[8:11]
	v_mfma_f32_16x16x32_bf16 v[60:63], v[156:159], v[188:191], v[60:63]
	v_mfma_f32_16x16x32_bf16 v[56:59], v[164:167], v[188:191], v[56:59]
	v_mfma_f32_16x16x32_bf16 v[44:47], v[156:159], v[196:199], v[44:47]
	v_mfma_f32_16x16x32_bf16 v[40:43], v[164:167], v[196:199], v[40:43]
	v_mfma_f32_16x16x32_bf16 v[28:31], v[156:159], v[208:211], v[28:31]
	v_mfma_f32_16x16x32_bf16 v[24:27], v[164:167], v[208:211], v[24:27]
	v_mfma_f32_16x16x32_bf16 v[12:15], v[156:159], v[216:219], v[12:15]
	v_mfma_f32_16x16x32_bf16 v[8:11], v[164:167], v[216:219], v[8:11]
	v_mfma_f32_16x16x32_bf16 v[52:55], v[168:171], v[184:187], v[52:55]
	v_mfma_f32_16x16x32_bf16 v[48:51], v[176:179], v[184:187], v[48:51]
	v_mfma_f32_16x16x32_bf16 v[36:39], v[168:171], v[192:195], v[36:39]
	v_mfma_f32_16x16x32_bf16 v[32:35], v[176:179], v[192:195], v[32:35]
	v_mfma_f32_16x16x32_bf16 v[20:23], v[168:171], v[200:203], v[20:23]
	v_mfma_f32_16x16x32_bf16 v[16:19], v[176:179], v[200:203], v[16:19]
	v_mfma_f32_16x16x32_bf16 v[4:7], v[168:171], v[212:215], v[4:7]
	v_mfma_f32_16x16x32_bf16 v[0:3], v[176:179], v[212:215], v[0:3]
	v_mfma_f32_16x16x32_bf16 v[52:55], v[172:175], v[188:191], v[52:55]
	v_mfma_f32_16x16x32_bf16 v[48:51], v[180:183], v[188:191], v[48:51]
	v_mfma_f32_16x16x32_bf16 v[36:39], v[172:175], v[196:199], v[36:39]
	v_mfma_f32_16x16x32_bf16 v[32:35], v[180:183], v[196:199], v[32:35]
	v_mfma_f32_16x16x32_bf16 v[20:23], v[172:175], v[208:211], v[20:23]
	v_mfma_f32_16x16x32_bf16 v[16:19], v[180:183], v[208:211], v[16:19]
	v_mfma_f32_16x16x32_bf16 v[4:7], v[172:175], v[216:219], v[4:7]
	v_mfma_f32_16x16x32_bf16 v[0:3], v[180:183], v[216:219], v[0:3]
	s_add_i32 s56, 0, 0x18000
	s_add_i32 s57, 0, 0x1c000
	s_barrier
	v_add_u32_e32 v164, s56, v149
	v_add_u32_e32 v180, s57, v149
	ds_read_b128 v[144:147], v164
	ds_read_b128 v[156:159], v164 offset:1024
	ds_read_b128 v[160:163], v164 offset:2048
	ds_read_b128 v[164:167], v164 offset:3072
	ds_read_b128 v[168:171], v180
	ds_read_b128 v[172:175], v180 offset:1024
	ds_read_b128 v[176:179], v180 offset:2048
	ds_read_b128 v[180:183], v180 offset:3072
	s_add_u32 s28, s28, 0x40000
	s_addc_u32 s29, s29, 0
	s_mov_b32 m0, s40
	ds_read_b128 v[184:187], v153 offset:32768
	ds_read_b128 v[188:191], v153 offset:33792
	ds_read_b128 v[192:195], v153 offset:34816
	ds_read_b128 v[196:199], v153 offset:35840
	ds_read_b128 v[200:203], v153 offset:36864
	ds_read_b128 v[208:211], v153 offset:37888
	ds_read_b128 v[212:215], v153 offset:38912
	ds_read_b128 v[216:219], v153 offset:39936
	global_load_lds_dwordx4 v134, s[28:29]
	s_mov_b32 m0, s41
	s_nop 0
	global_load_lds_dwordx4 v130, s[28:29]
	s_waitcnt vmcnt(8)
	s_waitcnt lgkmcnt(0)
	s_barrier
	s_waitcnt lgkmcnt(0)
	v_mfma_f32_16x16x32_bf16 v[124:127], v[144:147], v[184:187], v[124:127]
	v_mfma_f32_16x16x32_bf16 v[120:123], v[160:163], v[184:187], v[120:123]
	v_mfma_f32_16x16x32_bf16 v[108:111], v[144:147], v[192:195], v[108:111]
	v_mfma_f32_16x16x32_bf16 v[104:107], v[160:163], v[192:195], v[104:107]
	v_mfma_f32_16x16x32_bf16 v[92:95], v[144:147], v[200:203], v[92:95]
	v_mfma_f32_16x16x32_bf16 v[88:91], v[160:163], v[200:203], v[88:91]
	v_mfma_f32_16x16x32_bf16 v[76:79], v[144:147], v[212:215], v[76:79]
	v_mfma_f32_16x16x32_bf16 v[72:75], v[160:163], v[212:215], v[72:75]
	v_mfma_f32_16x16x32_bf16 v[124:127], v[156:159], v[188:191], v[124:127]
	v_mfma_f32_16x16x32_bf16 v[120:123], v[164:167], v[188:191], v[120:123]
	v_mfma_f32_16x16x32_bf16 v[108:111], v[156:159], v[196:199], v[108:111]
	v_mfma_f32_16x16x32_bf16 v[104:107], v[164:167], v[196:199], v[104:107]
	v_mfma_f32_16x16x32_bf16 v[92:95], v[156:159], v[208:211], v[92:95]
	v_mfma_f32_16x16x32_bf16 v[88:91], v[164:167], v[208:211], v[88:91]
	v_mfma_f32_16x16x32_bf16 v[76:79], v[156:159], v[216:219], v[76:79]
	v_mfma_f32_16x16x32_bf16 v[72:75], v[164:167], v[216:219], v[72:75]
	v_mfma_f32_16x16x32_bf16 v[116:119], v[168:171], v[184:187], v[116:119]
	v_mfma_f32_16x16x32_bf16 v[112:115], v[176:179], v[184:187], v[112:115]
	v_mfma_f32_16x16x32_bf16 v[100:103], v[168:171], v[192:195], v[100:103]
	v_mfma_f32_16x16x32_bf16 v[96:99], v[176:179], v[192:195], v[96:99]
	v_mfma_f32_16x16x32_bf16 v[84:87], v[168:171], v[200:203], v[84:87]
	v_mfma_f32_16x16x32_bf16 v[80:83], v[176:179], v[200:203], v[80:83]
	v_mfma_f32_16x16x32_bf16 v[68:71], v[168:171], v[212:215], v[68:71]
	v_mfma_f32_16x16x32_bf16 v[64:67], v[176:179], v[212:215], v[64:67]
	v_mfma_f32_16x16x32_bf16 v[116:119], v[172:175], v[188:191], v[116:119]
	v_mfma_f32_16x16x32_bf16 v[112:115], v[180:183], v[188:191], v[112:115]
	v_mfma_f32_16x16x32_bf16 v[100:103], v[172:175], v[196:199], v[100:103]
	v_mfma_f32_16x16x32_bf16 v[96:99], v[180:183], v[196:199], v[96:99]
	v_mfma_f32_16x16x32_bf16 v[84:87], v[172:175], v[208:211], v[84:87]
	v_mfma_f32_16x16x32_bf16 v[80:83], v[180:183], v[208:211], v[80:83]
	v_mfma_f32_16x16x32_bf16 v[68:71], v[172:175], v[216:219], v[68:71]
	v_mfma_f32_16x16x32_bf16 v[64:67], v[180:183], v[216:219], v[64:67]
	s_add_i32 s28, s56, s35
	s_mov_b32 m0, s28
	s_barrier
	ds_read_b128 v[184:187], v153 offset:49152
	ds_read_b128 v[188:191], v153 offset:50176
	ds_read_b128 v[192:195], v153 offset:51200
	ds_read_b128 v[196:199], v153 offset:52224
	ds_read_b128 v[200:203], v153 offset:53248
	ds_read_b128 v[208:211], v153 offset:54272
	ds_read_b128 v[212:215], v153 offset:55296
	ds_read_b128 v[216:219], v153 offset:56320
	global_load_lds_dwordx4 v220, s[26:27]
	s_add_i32 m0, s28, 0x2000
	s_add_u32 s26, s26, 0x40080
	s_addc_u32 s27, s27, 0
	s_add_i32 s28, s57, s35
	global_load_lds_dwordx4 v204, s[98:99]
	s_mov_b32 m0, s28
	s_nop 0
	global_load_lds_dwordx4 v132, s[26:27]
	s_add_i32 m0, s28, 0x2000
	s_nop 0
	global_load_lds_dwordx4 v128, s[26:27]
	s_mov_b32 m0, s45
	s_nop 0
	global_load_lds_dwordx4 v221, s[100:101]
	s_mov_b32 m0, s46
	s_nop 0
	global_load_lds_dwordx4 v205, s[100:101]
	s_waitcnt vmcnt(8)
	s_waitcnt lgkmcnt(0)
	s_barrier
	s_waitcnt lgkmcnt(0)
	v_mfma_f32_16x16x32_bf16 v[60:63], v[144:147], v[184:187], v[60:63]
	v_mfma_f32_16x16x32_bf16 v[56:59], v[160:163], v[184:187], v[56:59]
	v_mfma_f32_16x16x32_bf16 v[44:47], v[144:147], v[192:195], v[44:47]
	v_mfma_f32_16x16x32_bf16 v[40:43], v[160:163], v[192:195], v[40:43]
	v_mfma_f32_16x16x32_bf16 v[28:31], v[144:147], v[200:203], v[28:31]
	v_mfma_f32_16x16x32_bf16 v[24:27], v[160:163], v[200:203], v[24:27]
	v_mfma_f32_16x16x32_bf16 v[12:15], v[144:147], v[212:215], v[12:15]
	v_mfma_f32_16x16x32_bf16 v[8:11], v[160:163], v[212:215], v[8:11]
	v_mfma_f32_16x16x32_bf16 v[60:63], v[156:159], v[188:191], v[60:63]
	v_mfma_f32_16x16x32_bf16 v[56:59], v[164:167], v[188:191], v[56:59]
	v_mfma_f32_16x16x32_bf16 v[44:47], v[156:159], v[196:199], v[44:47]
	v_mfma_f32_16x16x32_bf16 v[40:43], v[164:167], v[196:199], v[40:43]
	v_mfma_f32_16x16x32_bf16 v[28:31], v[156:159], v[208:211], v[28:31]
	v_mfma_f32_16x16x32_bf16 v[24:27], v[164:167], v[208:211], v[24:27]
	v_mfma_f32_16x16x32_bf16 v[12:15], v[156:159], v[216:219], v[12:15]
	v_mfma_f32_16x16x32_bf16 v[8:11], v[164:167], v[216:219], v[8:11]
	v_mfma_f32_16x16x32_bf16 v[52:55], v[168:171], v[184:187], v[52:55]
	v_mfma_f32_16x16x32_bf16 v[48:51], v[176:179], v[184:187], v[48:51]
	v_mfma_f32_16x16x32_bf16 v[36:39], v[168:171], v[192:195], v[36:39]
	v_mfma_f32_16x16x32_bf16 v[32:35], v[176:179], v[192:195], v[32:35]
	v_mfma_f32_16x16x32_bf16 v[20:23], v[168:171], v[200:203], v[20:23]
	v_mfma_f32_16x16x32_bf16 v[16:19], v[176:179], v[200:203], v[16:19]
	v_mfma_f32_16x16x32_bf16 v[4:7], v[168:171], v[212:215], v[4:7]
	v_mfma_f32_16x16x32_bf16 v[0:3], v[176:179], v[212:215], v[0:3]
	v_mfma_f32_16x16x32_bf16 v[52:55], v[172:175], v[188:191], v[52:55]
	v_mfma_f32_16x16x32_bf16 v[48:51], v[180:183], v[188:191], v[48:51]
	v_mfma_f32_16x16x32_bf16 v[36:39], v[172:175], v[196:199], v[36:39]
	v_mfma_f32_16x16x32_bf16 v[32:35], v[180:183], v[196:199], v[32:35]
	v_mfma_f32_16x16x32_bf16 v[20:23], v[172:175], v[208:211], v[20:23]
	v_mfma_f32_16x16x32_bf16 v[16:19], v[180:183], v[208:211], v[16:19]
	v_mfma_f32_16x16x32_bf16 v[4:7], v[172:175], v[216:219], v[4:7]
	v_mfma_f32_16x16x32_bf16 v[0:3], v[180:183], v[216:219], v[0:3]
	s_add_i32 s55, s55, 2
	s_add_u32 s53, s53, 0x100
	s_addc_u32 s54, s54, 0
	s_add_u32 s24, s24, 0x100
	s_addc_u32 s25, s25, 0
	s_cmp_gt_u32 s55, 13
	s_barrier
	s_cbranch_scc0 .LBB0_163
	s_setprio 0
	s_and_b64 vcc, exec, s[14:15]
	s_cbranch_vccz .LBB0_166
	s_barrier

.LBB0_606:
	ds_read_b128 v[140:143], v147
	ds_read_b128 v[150:153], v147 offset:1024
	ds_read_b128 v[154:157], v147 offset:2048
	ds_read_b128 v[158:161], v147 offset:3072
	ds_read_b128 v[162:165], v148
	ds_read_b128 v[166:169], v148 offset:1024
	ds_read_b128 v[170:173], v148 offset:2048
	ds_read_b128 v[174:177], v148 offset:3072
	s_add_u32 s30, s28, 0x100
	s_addc_u32 s31, s29, 0
	s_cmp_eq_u32 s58, 12
	s_cselect_b32 s37, s21, s31
	s_cselect_b32 s36, s27, s30
	s_cselect_b32 s35, s19, s57
	s_cselect_b32 s34, s55, s56
	s_add_i32 m0, s44, 0xc000
	ds_read_b128 v[178:181], v149
	ds_read_b128 v[182:185], v149 offset:1024
	ds_read_b128 v[186:189], v149 offset:2048
	ds_read_b128 v[190:193], v149 offset:3072
	ds_read_b128 v[194:197], v149 offset:4096
	ds_read_b128 v[198:201], v149 offset:5120
	ds_read_b128 v[202:205], v149 offset:6144
	ds_read_b128 v[208:211], v149 offset:7168
	global_load_lds_dwordx4 v134, s[28:29]
	s_add_i32 m0, s44, 0xe000
	s_nop 0
	global_load_lds_dwordx4 v132, s[28:29]
	s_waitcnt vmcnt(8)
	s_waitcnt lgkmcnt(0)
	s_barrier
	s_waitcnt lgkmcnt(0)
	v_mfma_f32_16x16x32_bf16 v[124:127], v[140:143], v[178:181], v[124:127]
	v_mfma_f32_16x16x32_bf16 v[120:123], v[154:157], v[178:181], v[120:123]
	v_mfma_f32_16x16x32_bf16 v[108:111], v[140:143], v[186:189], v[108:111]
	v_mfma_f32_16x16x32_bf16 v[104:107], v[154:157], v[186:189], v[104:107]
	v_mfma_f32_16x16x32_bf16 v[92:95], v[140:143], v[194:197], v[92:95]
	v_mfma_f32_16x16x32_bf16 v[88:91], v[154:157], v[194:197], v[88:91]
	v_mfma_f32_16x16x32_bf16 v[76:79], v[140:143], v[202:205], v[76:79]
	v_mfma_f32_16x16x32_bf16 v[72:75], v[154:157], v[202:205], v[72:75]
	v_mfma_f32_16x16x32_bf16 v[124:127], v[150:153], v[182:185], v[124:127]
	v_mfma_f32_16x16x32_bf16 v[120:123], v[158:161], v[182:185], v[120:123]
	v_mfma_f32_16x16x32_bf16 v[108:111], v[150:153], v[190:193], v[108:111]
	v_mfma_f32_16x16x32_bf16 v[104:107], v[158:161], v[190:193], v[104:107]
	v_mfma_f32_16x16x32_bf16 v[92:95], v[150:153], v[198:201], v[92:95]
	v_mfma_f32_16x16x32_bf16 v[88:91], v[158:161], v[198:201], v[88:91]
	v_mfma_f32_16x16x32_bf16 v[76:79], v[150:153], v[208:211], v[76:79]
	v_mfma_f32_16x16x32_bf16 v[72:75], v[158:161], v[208:211], v[72:75]
	v_mfma_f32_16x16x32_bf16 v[116:119], v[162:165], v[178:181], v[116:119]
	v_mfma_f32_16x16x32_bf16 v[112:115], v[170:173], v[178:181], v[112:115]
	v_mfma_f32_16x16x32_bf16 v[100:103], v[162:165], v[186:189], v[100:103]
	v_mfma_f32_16x16x32_bf16 v[96:99], v[170:173], v[186:189], v[96:99]
	v_mfma_f32_16x16x32_bf16 v[84:87], v[162:165], v[194:197], v[84:87]
	v_mfma_f32_16x16x32_bf16 v[80:83], v[170:173], v[194:197], v[80:83]
	v_mfma_f32_16x16x32_bf16 v[68:71], v[162:165], v[202:205], v[68:71]
	v_mfma_f32_16x16x32_bf16 v[64:67], v[170:173], v[202:205], v[64:67]
	v_mfma_f32_16x16x32_bf16 v[116:119], v[166:169], v[182:185], v[116:119]
	v_mfma_f32_16x16x32_bf16 v[112:115], v[174:177], v[182:185], v[112:115]
	v_mfma_f32_16x16x32_bf16 v[100:103], v[166:169], v[190:193], v[100:103]
	v_mfma_f32_16x16x32_bf16 v[96:99], v[174:177], v[190:193], v[96:99]
	v_mfma_f32_16x16x32_bf16 v[84:87], v[166:169], v[198:201], v[84:87]
	v_mfma_f32_16x16x32_bf16 v[80:83], v[174:177], v[198:201], v[80:83]
	v_mfma_f32_16x16x32_bf16 v[68:71], v[166:169], v[208:211], v[68:71]
	v_mfma_f32_16x16x32_bf16 v[64:67], v[174:177], v[208:211], v[64:67]
	s_add_i32 s28, s52, s43
	s_mov_b32 m0, s28
	s_barrier
	ds_read_b128 v[178:181], v149 offset:16384
	ds_read_b128 v[182:185], v149 offset:17408
	ds_read_b128 v[186:189], v149 offset:18432
	ds_read_b128 v[190:193], v149 offset:19456
	ds_read_b128 v[194:197], v149 offset:20480
	ds_read_b128 v[198:201], v149 offset:21504
	ds_read_b128 v[202:205], v149 offset:22528
	ds_read_b128 v[208:211], v149 offset:23552
	global_load_lds_dwordx4 v128, s[34:35]
	s_add_i32 m0, s28, 0x2000
	s_add_u32 s28, s34, 0x40000
	s_mov_b64 s[98:99], s[34:35]
	s_addc_u32 s29, s35, 0
	s_add_i32 s59, s53, s43
	global_load_lds_dwordx4 v130, s[34:35]
	s_mov_b32 m0, s59
	s_nop 0
	global_load_lds_dwordx4 v128, s[28:29]
	s_add_i32 m0, s59, 0x2000
	s_nop 0
	global_load_lds_dwordx4 v130, s[28:29]
	s_mov_b32 m0, s44
	s_nop 0
	global_load_lds_dwordx4 v128, s[36:37]
	s_mov_b32 m0, s45
	s_nop 0
	global_load_lds_dwordx4 v130, s[36:37]
	s_waitcnt vmcnt(8)
	s_waitcnt lgkmcnt(0)
	s_barrier
	s_waitcnt lgkmcnt(0)
	v_mfma_f32_16x16x32_bf16 v[60:63], v[140:143], v[178:181], v[60:63]
	v_mfma_f32_16x16x32_bf16 v[56:59], v[154:157], v[178:181], v[56:59]
	v_mfma_f32_16x16x32_bf16 v[44:47], v[140:143], v[186:189], v[44:47]
	v_mfma_f32_16x16x32_bf16 v[40:43], v[154:157], v[186:189], v[40:43]
	v_mfma_f32_16x16x32_bf16 v[28:31], v[140:143], v[194:197], v[28:31]
	v_mfma_f32_16x16x32_bf16 v[24:27], v[154:157], v[194:197], v[24:27]
	v_mfma_f32_16x16x32_bf16 v[12:15], v[140:143], v[202:205], v[12:15]
	v_mfma_f32_16x16x32_bf16 v[8:11], v[154:157], v[202:205], v[8:11]
	v_mfma_f32_16x16x32_bf16 v[60:63], v[150:153], v[182:185], v[60:63]
	v_mfma_f32_16x16x32_bf16 v[56:59], v[158:161], v[182:185], v[56:59]
	v_mfma_f32_16x16x32_bf16 v[44:47], v[150:153], v[190:193], v[44:47]
	v_mfma_f32_16x16x32_bf16 v[40:43], v[158:161], v[190:193], v[40:43]
	v_mfma_f32_16x16x32_bf16 v[28:31], v[150:153], v[198:201], v[28:31]
	v_mfma_f32_16x16x32_bf16 v[24:27], v[158:161], v[198:201], v[24:27]
	v_mfma_f32_16x16x32_bf16 v[12:15], v[150:153], v[208:211], v[12:15]
	v_mfma_f32_16x16x32_bf16 v[8:11], v[158:161], v[208:211], v[8:11]
	v_mfma_f32_16x16x32_bf16 v[52:55], v[162:165], v[178:181], v[52:55]
	v_mfma_f32_16x16x32_bf16 v[48:51], v[170:173], v[178:181], v[48:51]
	v_mfma_f32_16x16x32_bf16 v[36:39], v[162:165], v[186:189], v[36:39]
	v_mfma_f32_16x16x32_bf16 v[32:35], v[170:173], v[186:189], v[32:35]
	v_mfma_f32_16x16x32_bf16 v[20:23], v[162:165], v[194:197], v[20:23]
	v_mfma_f32_16x16x32_bf16 v[16:19], v[170:173], v[194:197], v[16:19]
	v_mfma_f32_16x16x32_bf16 v[4:7], v[162:165], v[202:205], v[4:7]
	v_mfma_f32_16x16x32_bf16 v[0:3], v[170:173], v[202:205], v[0:3]
	v_mfma_f32_16x16x32_bf16 v[52:55], v[166:169], v[182:185], v[52:55]
	v_mfma_f32_16x16x32_bf16 v[48:51], v[174:177], v[182:185], v[48:51]
	v_mfma_f32_16x16x32_bf16 v[36:39], v[166:169], v[190:193], v[36:39]
	v_mfma_f32_16x16x32_bf16 v[32:35], v[174:177], v[190:193], v[32:35]
	v_mfma_f32_16x16x32_bf16 v[20:23], v[166:169], v[198:201], v[20:23]
	v_mfma_f32_16x16x32_bf16 v[16:19], v[174:177], v[198:201], v[16:19]
	v_mfma_f32_16x16x32_bf16 v[4:7], v[166:169], v[208:211], v[4:7]
	v_mfma_f32_16x16x32_bf16 v[0:3], v[174:177], v[208:211], v[0:3]
	s_add_i32 s59, 0, 0x18000
	s_add_i32 s60, 0, 0x1c000
	s_barrier
	v_add_u32_e32 v158, s59, v145
	v_add_u32_e32 v174, s60, v145
	ds_read_b128 v[140:143], v158
	ds_read_b128 v[150:153], v158 offset:1024
	ds_read_b128 v[154:157], v158 offset:2048
	ds_read_b128 v[158:161], v158 offset:3072
	ds_read_b128 v[162:165], v174
	ds_read_b128 v[166:169], v174 offset:1024
	ds_read_b128 v[170:173], v174 offset:2048
	ds_read_b128 v[174:177], v174 offset:3072
	s_add_u32 s28, s36, 0x40000
	s_addc_u32 s29, s37, 0
	s_mov_b32 m0, s46
	ds_read_b128 v[178:181], v149 offset:32768
	ds_read_b128 v[182:185], v149 offset:33792
	ds_read_b128 v[186:189], v149 offset:34816
	ds_read_b128 v[190:193], v149 offset:35840
	ds_read_b128 v[194:197], v149 offset:36864
	ds_read_b128 v[198:201], v149 offset:37888
	ds_read_b128 v[202:205], v149 offset:38912
	ds_read_b128 v[208:211], v149 offset:39936
	global_load_lds_dwordx4 v128, s[28:29]
	s_mov_b32 m0, s47
	s_nop 0
	global_load_lds_dwordx4 v130, s[28:29]
	s_waitcnt vmcnt(8)
	s_waitcnt lgkmcnt(0)
	s_barrier
	s_waitcnt lgkmcnt(0)
	v_mfma_f32_16x16x32_bf16 v[124:127], v[140:143], v[178:181], v[124:127]
	v_mfma_f32_16x16x32_bf16 v[120:123], v[154:157], v[178:181], v[120:123]
	v_mfma_f32_16x16x32_bf16 v[108:111], v[140:143], v[186:189], v[108:111]
	v_mfma_f32_16x16x32_bf16 v[104:107], v[154:157], v[186:189], v[104:107]
	v_mfma_f32_16x16x32_bf16 v[92:95], v[140:143], v[194:197], v[92:95]
	v_mfma_f32_16x16x32_bf16 v[88:91], v[154:157], v[194:197], v[88:91]
	v_mfma_f32_16x16x32_bf16 v[76:79], v[140:143], v[202:205], v[76:79]
	v_mfma_f32_16x16x32_bf16 v[72:75], v[154:157], v[202:205], v[72:75]
	v_mfma_f32_16x16x32_bf16 v[124:127], v[150:153], v[182:185], v[124:127]
	v_mfma_f32_16x16x32_bf16 v[120:123], v[158:161], v[182:185], v[120:123]
	v_mfma_f32_16x16x32_bf16 v[108:111], v[150:153], v[190:193], v[108:111]
	v_mfma_f32_16x16x32_bf16 v[104:107], v[158:161], v[190:193], v[104:107]
	v_mfma_f32_16x16x32_bf16 v[92:95], v[150:153], v[198:201], v[92:95]
	v_mfma_f32_16x16x32_bf16 v[88:91], v[158:161], v[198:201], v[88:91]
	v_mfma_f32_16x16x32_bf16 v[76:79], v[150:153], v[208:211], v[76:79]
	v_mfma_f32_16x16x32_bf16 v[72:75], v[158:161], v[208:211], v[72:75]
	v_mfma_f32_16x16x32_bf16 v[116:119], v[162:165], v[178:181], v[116:119]
	v_mfma_f32_16x16x32_bf16 v[112:115], v[170:173], v[178:181], v[112:115]
	v_mfma_f32_16x16x32_bf16 v[100:103], v[162:165], v[186:189], v[100:103]
	v_mfma_f32_16x16x32_bf16 v[96:99], v[170:173], v[186:189], v[96:99]
	v_mfma_f32_16x16x32_bf16 v[84:87], v[162:165], v[194:197], v[84:87]
	v_mfma_f32_16x16x32_bf16 v[80:83], v[170:173], v[194:197], v[80:83]
	v_mfma_f32_16x16x32_bf16 v[68:71], v[162:165], v[202:205], v[68:71]
	v_mfma_f32_16x16x32_bf16 v[64:67], v[170:173], v[202:205], v[64:67]
	v_mfma_f32_16x16x32_bf16 v[116:119], v[166:169], v[182:185], v[116:119]
	v_mfma_f32_16x16x32_bf16 v[112:115], v[174:177], v[182:185], v[112:115]
	v_mfma_f32_16x16x32_bf16 v[100:103], v[166:169], v[190:193], v[100:103]
	v_mfma_f32_16x16x32_bf16 v[96:99], v[174:177], v[190:193], v[96:99]
	v_mfma_f32_16x16x32_bf16 v[84:87], v[166:169], v[198:201], v[84:87]
	v_mfma_f32_16x16x32_bf16 v[80:83], v[174:177], v[198:201], v[80:83]
	v_mfma_f32_16x16x32_bf16 v[68:71], v[166:169], v[208:211], v[68:71]
	v_mfma_f32_16x16x32_bf16 v[64:67], v[174:177], v[208:211], v[64:67]
	s_add_i32 s28, s59, s43
	s_mov_b32 m0, s28
	s_barrier
	ds_read_b128 v[178:181], v149 offset:49152
	ds_read_b128 v[182:185], v149 offset:50176
	ds_read_b128 v[186:189], v149 offset:51200
	ds_read_b128 v[190:193], v149 offset:52224
	ds_read_b128 v[194:197], v149 offset:53248
	ds_read_b128 v[198:201], v149 offset:54272
	ds_read_b128 v[202:205], v149 offset:55296
	ds_read_b128 v[208:211], v149 offset:56320
	global_load_lds_dwordx4 v212, s[34:35]
	s_add_i32 m0, s28, 0x2000
	s_add_u32 s28, s34, 0x40080
	s_addc_u32 s29, s35, 0
	s_add_i32 s34, s60, s43
	global_load_lds_dwordx4 v213, s[98:99]
	s_mov_b32 m0, s34
	s_nop 0
	global_load_lds_dwordx4 v128, s[28:29]
	s_add_i32 m0, s34, 0x2000
	s_nop 0
	global_load_lds_dwordx4 v130, s[28:29]
	s_mov_b32 m0, s49
	s_nop 0
	global_load_lds_dwordx4 v212, s[36:37]
	s_mov_b32 m0, s50
	s_nop 0
	global_load_lds_dwordx4 v213, s[36:37]
	s_waitcnt vmcnt(8)
	s_waitcnt lgkmcnt(0)
	s_barrier
	s_waitcnt lgkmcnt(0)
	v_mfma_f32_16x16x32_bf16 v[60:63], v[140:143], v[178:181], v[60:63]
	v_mfma_f32_16x16x32_bf16 v[56:59], v[154:157], v[178:181], v[56:59]
	v_mfma_f32_16x16x32_bf16 v[44:47], v[140:143], v[186:189], v[44:47]
	v_mfma_f32_16x16x32_bf16 v[40:43], v[154:157], v[186:189], v[40:43]
	v_mfma_f32_16x16x32_bf16 v[28:31], v[140:143], v[194:197], v[28:31]
	v_mfma_f32_16x16x32_bf16 v[24:27], v[154:157], v[194:197], v[24:27]
	v_mfma_f32_16x16x32_bf16 v[12:15], v[140:143], v[202:205], v[12:15]
	v_mfma_f32_16x16x32_bf16 v[8:11], v[154:157], v[202:205], v[8:11]
	v_mfma_f32_16x16x32_bf16 v[60:63], v[150:153], v[182:185], v[60:63]
	v_mfma_f32_16x16x32_bf16 v[56:59], v[158:161], v[182:185], v[56:59]
	v_mfma_f32_16x16x32_bf16 v[44:47], v[150:153], v[190:193], v[44:47]
	v_mfma_f32_16x16x32_bf16 v[40:43], v[158:161], v[190:193], v[40:43]
	v_mfma_f32_16x16x32_bf16 v[28:31], v[150:153], v[198:201], v[28:31]
	v_mfma_f32_16x16x32_bf16 v[24:27], v[158:161], v[198:201], v[24:27]
	v_mfma_f32_16x16x32_bf16 v[12:15], v[150:153], v[208:211], v[12:15]
	v_mfma_f32_16x16x32_bf16 v[8:11], v[158:161], v[208:211], v[8:11]
	v_mfma_f32_16x16x32_bf16 v[52:55], v[162:165], v[178:181], v[52:55]
	v_mfma_f32_16x16x32_bf16 v[48:51], v[170:173], v[178:181], v[48:51]
	v_mfma_f32_16x16x32_bf16 v[36:39], v[162:165], v[186:189], v[36:39]
	v_mfma_f32_16x16x32_bf16 v[32:35], v[170:173], v[186:189], v[32:35]
	v_mfma_f32_16x16x32_bf16 v[20:23], v[162:165], v[194:197], v[20:23]
	v_mfma_f32_16x16x32_bf16 v[16:19], v[170:173], v[194:197], v[16:19]
	v_mfma_f32_16x16x32_bf16 v[4:7], v[162:165], v[202:205], v[4:7]
	v_mfma_f32_16x16x32_bf16 v[0:3], v[170:173], v[202:205], v[0:3]
	v_mfma_f32_16x16x32_bf16 v[52:55], v[166:169], v[182:185], v[52:55]
	v_mfma_f32_16x16x32_bf16 v[48:51], v[174:177], v[182:185], v[48:51]
	v_mfma_f32_16x16x32_bf16 v[36:39], v[166:169], v[190:193], v[36:39]
	v_mfma_f32_16x16x32_bf16 v[32:35], v[174:177], v[190:193], v[32:35]
	v_mfma_f32_16x16x32_bf16 v[20:23], v[166:169], v[198:201], v[20:23]
	v_mfma_f32_16x16x32_bf16 v[16:19], v[174:177], v[198:201], v[16:19]
	v_mfma_f32_16x16x32_bf16 v[4:7], v[166:169], v[208:211], v[4:7]
	v_mfma_f32_16x16x32_bf16 v[0:3], v[174:177], v[208:211], v[0:3]
	s_add_i32 s58, s58, 2
	s_add_u32 s56, s56, 0x100
	s_addc_u32 s57, s57, 0
	s_cmp_gt_u32 s58, 13
	s_mov_b64 s[28:29], s[30:31]
	s_barrier
	s_cbranch_scc0 .LBB0_606
	s_setprio 0
	s_and_b64 vcc, exec, s[16:17]
	s_cbranch_vccz .LBB0_609
	s_barrier

.LBB0_699:
	ds_read_b128 v[144:147], v151
	ds_read_b128 v[156:159], v151 offset:1024
	ds_read_b128 v[160:163], v151 offset:2048
	ds_read_b128 v[164:167], v151 offset:3072
	ds_read_b128 v[168:171], v152
	ds_read_b128 v[172:175], v152 offset:1024
	ds_read_b128 v[176:179], v152 offset:2048
	ds_read_b128 v[180:183], v152 offset:3072
	s_add_u32 s28, s26, 0xfffc0080
	s_addc_u32 s29, s27, -1
	s_cmp_eq_u32 s53, 12
	s_cselect_b32 s31, s21, s29
	s_cselect_b32 s30, s49, s28
	s_cselect_b32 s29, s19, s52
	s_cselect_b32 s28, s50, s51
	s_add_i32 m0, s39, 0xc000
	ds_read_b128 v[184:187], v153
	ds_read_b128 v[188:191], v153 offset:1024
	ds_read_b128 v[192:195], v153 offset:2048
	ds_read_b128 v[196:199], v153 offset:3072
	ds_read_b128 v[200:203], v153 offset:4096
	ds_read_b128 v[208:211], v153 offset:5120
	ds_read_b128 v[212:215], v153 offset:6144
	ds_read_b128 v[216:219], v153 offset:7168
	global_load_lds_dwordx4 v138, s[26:27]
	s_add_i32 m0, s39, 0xe000
	s_nop 0
	global_load_lds_dwordx4 v136, s[26:27]
	s_waitcnt vmcnt(8)
	s_waitcnt lgkmcnt(0)
	s_barrier
	s_waitcnt lgkmcnt(0)
	v_mfma_f32_16x16x32_bf16 v[124:127], v[144:147], v[184:187], v[124:127]
	v_mfma_f32_16x16x32_bf16 v[120:123], v[160:163], v[184:187], v[120:123]
	v_mfma_f32_16x16x32_bf16 v[108:111], v[144:147], v[192:195], v[108:111]
	v_mfma_f32_16x16x32_bf16 v[104:107], v[160:163], v[192:195], v[104:107]
	v_mfma_f32_16x16x32_bf16 v[92:95], v[144:147], v[200:203], v[92:95]
	v_mfma_f32_16x16x32_bf16 v[88:91], v[160:163], v[200:203], v[88:91]
	v_mfma_f32_16x16x32_bf16 v[76:79], v[144:147], v[212:215], v[76:79]
	v_mfma_f32_16x16x32_bf16 v[72:75], v[160:163], v[212:215], v[72:75]
	v_mfma_f32_16x16x32_bf16 v[124:127], v[156:159], v[188:191], v[124:127]
	v_mfma_f32_16x16x32_bf16 v[120:123], v[164:167], v[188:191], v[120:123]
	v_mfma_f32_16x16x32_bf16 v[108:111], v[156:159], v[196:199], v[108:111]
	v_mfma_f32_16x16x32_bf16 v[104:107], v[164:167], v[196:199], v[104:107]
	v_mfma_f32_16x16x32_bf16 v[92:95], v[156:159], v[208:211], v[92:95]
	v_mfma_f32_16x16x32_bf16 v[88:91], v[164:167], v[208:211], v[88:91]
	v_mfma_f32_16x16x32_bf16 v[76:79], v[156:159], v[216:219], v[76:79]
	v_mfma_f32_16x16x32_bf16 v[72:75], v[164:167], v[216:219], v[72:75]
	v_mfma_f32_16x16x32_bf16 v[116:119], v[168:171], v[184:187], v[116:119]
	v_mfma_f32_16x16x32_bf16 v[112:115], v[176:179], v[184:187], v[112:115]
	v_mfma_f32_16x16x32_bf16 v[100:103], v[168:171], v[192:195], v[100:103]
	v_mfma_f32_16x16x32_bf16 v[96:99], v[176:179], v[192:195], v[96:99]
	v_mfma_f32_16x16x32_bf16 v[84:87], v[168:171], v[200:203], v[84:87]
	v_mfma_f32_16x16x32_bf16 v[80:83], v[176:179], v[200:203], v[80:83]
	v_mfma_f32_16x16x32_bf16 v[68:71], v[168:171], v[212:215], v[68:71]
	v_mfma_f32_16x16x32_bf16 v[64:67], v[176:179], v[212:215], v[64:67]
	v_mfma_f32_16x16x32_bf16 v[116:119], v[172:175], v[188:191], v[116:119]
	v_mfma_f32_16x16x32_bf16 v[112:115], v[180:183], v[188:191], v[112:115]
	v_mfma_f32_16x16x32_bf16 v[100:103], v[172:175], v[196:199], v[100:103]
	v_mfma_f32_16x16x32_bf16 v[96:99], v[180:183], v[196:199], v[96:99]
	v_mfma_f32_16x16x32_bf16 v[84:87], v[172:175], v[208:211], v[84:87]
	v_mfma_f32_16x16x32_bf16 v[80:83], v[180:183], v[208:211], v[80:83]
	v_mfma_f32_16x16x32_bf16 v[68:71], v[172:175], v[216:219], v[68:71]
	v_mfma_f32_16x16x32_bf16 v[64:67], v[180:183], v[216:219], v[64:67]
	s_add_i32 s54, s46, s38
	s_mov_b32 m0, s54
	s_barrier
	ds_read_b128 v[184:187], v153 offset:16384
	ds_read_b128 v[188:191], v153 offset:17408
	ds_read_b128 v[192:195], v153 offset:18432
	ds_read_b128 v[196:199], v153 offset:19456
	ds_read_b128 v[200:203], v153 offset:20480
	ds_read_b128 v[208:211], v153 offset:21504
	ds_read_b128 v[212:215], v153 offset:22528
	ds_read_b128 v[216:219], v153 offset:23552
	global_load_lds_dwordx4 v130, s[28:29]
	s_add_i32 m0, s54, 0x2000
	s_add_u32 s54, s28, 0x40000
	s_mov_b64 s[98:99], s[28:29]
	s_addc_u32 s55, s29, 0
	s_add_i32 s56, s47, s38
	global_load_lds_dwordx4 v134, s[28:29]
	s_mov_b32 m0, s56
	s_mov_b64 s[100:101], s[30:31]
	global_load_lds_dwordx4 v130, s[54:55]
	s_add_i32 m0, s56, 0x2000
	s_nop 0
	global_load_lds_dwordx4 v134, s[54:55]
	s_mov_b32 m0, s39
	s_nop 0
	global_load_lds_dwordx4 v128, s[30:31]
	s_mov_b32 m0, s40
	s_nop 0
	global_load_lds_dwordx4 v132, s[30:31]
	s_waitcnt vmcnt(8)
	s_waitcnt lgkmcnt(0)
	s_barrier
	s_waitcnt lgkmcnt(0)
	v_mfma_f32_16x16x32_bf16 v[60:63], v[144:147], v[184:187], v[60:63]
	v_mfma_f32_16x16x32_bf16 v[56:59], v[160:163], v[184:187], v[56:59]
	v_mfma_f32_16x16x32_bf16 v[44:47], v[144:147], v[192:195], v[44:47]
	v_mfma_f32_16x16x32_bf16 v[40:43], v[160:163], v[192:195], v[40:43]
	v_mfma_f32_16x16x32_bf16 v[28:31], v[144:147], v[200:203], v[28:31]
	v_mfma_f32_16x16x32_bf16 v[24:27], v[160:163], v[200:203], v[24:27]
	v_mfma_f32_16x16x32_bf16 v[12:15], v[144:147], v[212:215], v[12:15]
	v_mfma_f32_16x16x32_bf16 v[8:11], v[160:163], v[212:215], v[8:11]
	v_mfma_f32_16x16x32_bf16 v[60:63], v[156:159], v[188:191], v[60:63]
	v_mfma_f32_16x16x32_bf16 v[56:59], v[164:167], v[188:191], v[56:59]
	v_mfma_f32_16x16x32_bf16 v[44:47], v[156:159], v[196:199], v[44:47]
	v_mfma_f32_16x16x32_bf16 v[40:43], v[164:167], v[196:199], v[40:43]
	v_mfma_f32_16x16x32_bf16 v[28:31], v[156:159], v[208:211], v[28:31]
	v_mfma_f32_16x16x32_bf16 v[24:27], v[164:167], v[208:211], v[24:27]
	v_mfma_f32_16x16x32_bf16 v[12:15], v[156:159], v[216:219], v[12:15]
	v_mfma_f32_16x16x32_bf16 v[8:11], v[164:167], v[216:219], v[8:11]
	v_mfma_f32_16x16x32_bf16 v[52:55], v[168:171], v[184:187], v[52:55]
	v_mfma_f32_16x16x32_bf16 v[48:51], v[176:179], v[184:187], v[48:51]
	v_mfma_f32_16x16x32_bf16 v[36:39], v[168:171], v[192:195], v[36:39]
	v_mfma_f32_16x16x32_bf16 v[32:35], v[176:179], v[192:195], v[32:35]
	v_mfma_f32_16x16x32_bf16 v[20:23], v[168:171], v[200:203], v[20:23]
	v_mfma_f32_16x16x32_bf16 v[16:19], v[176:179], v[200:203], v[16:19]
	v_mfma_f32_16x16x32_bf16 v[4:7], v[168:171], v[212:215], v[4:7]
	v_mfma_f32_16x16x32_bf16 v[0:3], v[176:179], v[212:215], v[0:3]
	v_mfma_f32_16x16x32_bf16 v[52:55], v[172:175], v[188:191], v[52:55]
	v_mfma_f32_16x16x32_bf16 v[48:51], v[180:183], v[188:191], v[48:51]
	v_mfma_f32_16x16x32_bf16 v[36:39], v[172:175], v[196:199], v[36:39]
	v_mfma_f32_16x16x32_bf16 v[32:35], v[180:183], v[196:199], v[32:35]
	v_mfma_f32_16x16x32_bf16 v[20:23], v[172:175], v[208:211], v[20:23]
	v_mfma_f32_16x16x32_bf16 v[16:19], v[180:183], v[208:211], v[16:19]
	v_mfma_f32_16x16x32_bf16 v[4:7], v[172:175], v[216:219], v[4:7]
	v_mfma_f32_16x16x32_bf16 v[0:3], v[180:183], v[216:219], v[0:3]
	s_add_i32 s54, 0, 0x18000
	s_barrier
	v_add_u32_e32 v155, s54, v149
	s_add_i32 s55, 0, 0x1c000
	ds_read_b128 v[144:147], v155
	ds_read_b128 v[156:159], v155 offset:1024
	ds_read_b128 v[160:163], v155 offset:2048
	ds_read_b128 v[164:167], v155 offset:3072
	v_add_u32_e32 v155, s55, v149
	ds_read_b128 v[168:171], v155
	ds_read_b128 v[172:175], v155 offset:1024
	ds_read_b128 v[176:179], v155 offset:2048
	ds_read_b128 v[180:183], v155 offset:3072
	s_add_u32 s30, s30, 0x40000
	s_addc_u32 s31, s31, 0
	s_mov_b32 m0, s41
	ds_read_b128 v[184:187], v153 offset:32768
	ds_read_b128 v[188:191], v153 offset:33792
	ds_read_b128 v[192:195], v153 offset:34816
	ds_read_b128 v[196:199], v153 offset:35840
	ds_read_b128 v[200:203], v153 offset:36864
	ds_read_b128 v[208:211], v153 offset:37888
	ds_read_b128 v[212:215], v153 offset:38912
	ds_read_b128 v[216:219], v153 offset:39936
	global_load_lds_dwordx4 v128, s[30:31]
	s_mov_b32 m0, s42
	s_nop 0
	global_load_lds_dwordx4 v132, s[30:31]
	s_waitcnt vmcnt(8)
	s_waitcnt lgkmcnt(0)
	s_barrier
	s_waitcnt lgkmcnt(0)
	v_mfma_f32_16x16x32_bf16 v[124:127], v[144:147], v[184:187], v[124:127]
	v_mfma_f32_16x16x32_bf16 v[120:123], v[160:163], v[184:187], v[120:123]
	v_mfma_f32_16x16x32_bf16 v[108:111], v[144:147], v[192:195], v[108:111]
	v_mfma_f32_16x16x32_bf16 v[104:107], v[160:163], v[192:195], v[104:107]
	v_mfma_f32_16x16x32_bf16 v[92:95], v[144:147], v[200:203], v[92:95]
	v_mfma_f32_16x16x32_bf16 v[88:91], v[160:163], v[200:203], v[88:91]
	v_mfma_f32_16x16x32_bf16 v[76:79], v[144:147], v[212:215], v[76:79]
	v_mfma_f32_16x16x32_bf16 v[72:75], v[160:163], v[212:215], v[72:75]
	v_mfma_f32_16x16x32_bf16 v[124:127], v[156:159], v[188:191], v[124:127]
	v_mfma_f32_16x16x32_bf16 v[120:123], v[164:167], v[188:191], v[120:123]
	v_mfma_f32_16x16x32_bf16 v[108:111], v[156:159], v[196:199], v[108:111]
	v_mfma_f32_16x16x32_bf16 v[104:107], v[164:167], v[196:199], v[104:107]
	v_mfma_f32_16x16x32_bf16 v[92:95], v[156:159], v[208:211], v[92:95]
	v_mfma_f32_16x16x32_bf16 v[88:91], v[164:167], v[208:211], v[88:91]
	v_mfma_f32_16x16x32_bf16 v[76:79], v[156:159], v[216:219], v[76:79]
	v_mfma_f32_16x16x32_bf16 v[72:75], v[164:167], v[216:219], v[72:75]
	v_mfma_f32_16x16x32_bf16 v[116:119], v[168:171], v[184:187], v[116:119]
	v_mfma_f32_16x16x32_bf16 v[112:115], v[176:179], v[184:187], v[112:115]
	v_mfma_f32_16x16x32_bf16 v[100:103], v[168:171], v[192:195], v[100:103]
	v_mfma_f32_16x16x32_bf16 v[96:99], v[176:179], v[192:195], v[96:99]
	v_mfma_f32_16x16x32_bf16 v[84:87], v[168:171], v[200:203], v[84:87]
	v_mfma_f32_16x16x32_bf16 v[80:83], v[176:179], v[200:203], v[80:83]
	v_mfma_f32_16x16x32_bf16 v[68:71], v[168:171], v[212:215], v[68:71]
	v_mfma_f32_16x16x32_bf16 v[64:67], v[176:179], v[212:215], v[64:67]
	v_mfma_f32_16x16x32_bf16 v[116:119], v[172:175], v[188:191], v[116:119]
	v_mfma_f32_16x16x32_bf16 v[112:115], v[180:183], v[188:191], v[112:115]
	v_mfma_f32_16x16x32_bf16 v[100:103], v[172:175], v[196:199], v[100:103]
	v_mfma_f32_16x16x32_bf16 v[96:99], v[180:183], v[196:199], v[96:99]
	v_mfma_f32_16x16x32_bf16 v[84:87], v[172:175], v[208:211], v[84:87]
	v_mfma_f32_16x16x32_bf16 v[80:83], v[180:183], v[208:211], v[80:83]
	v_mfma_f32_16x16x32_bf16 v[68:71], v[172:175], v[216:219], v[68:71]
	v_mfma_f32_16x16x32_bf16 v[64:67], v[180:183], v[216:219], v[64:67]
	s_add_i32 s30, s54, s38
	s_mov_b32 m0, s30
	s_barrier
	ds_read_b128 v[184:187], v153 offset:49152
	ds_read_b128 v[188:191], v153 offset:50176
	ds_read_b128 v[192:195], v153 offset:51200
	ds_read_b128 v[196:199], v153 offset:52224
	ds_read_b128 v[200:203], v153 offset:53248
	ds_read_b128 v[208:211], v153 offset:54272
	ds_read_b128 v[212:215], v153 offset:55296
	ds_read_b128 v[216:219], v153 offset:56320
	global_load_lds_dwordx4 v205, s[28:29]
	s_add_i32 m0, s30, 0x2000
	s_add_u32 s28, s28, 0x40080
	s_addc_u32 s29, s29, 0
	s_add_i32 s30, s55, s38
	global_load_lds_dwordx4 v221, s[98:99]
	s_mov_b32 m0, s30
	s_nop 0
	global_load_lds_dwordx4 v130, s[28:29]
	s_add_i32 m0, s30, 0x2000
	s_nop 0
	global_load_lds_dwordx4 v134, s[28:29]
	s_mov_b32 m0, s44
	s_nop 0
	global_load_lds_dwordx4 v204, s[100:101]
	s_mov_b32 m0, s45
	s_nop 0
	global_load_lds_dwordx4 v220, s[100:101]
	s_waitcnt vmcnt(8)
	s_waitcnt lgkmcnt(0)
	s_barrier
	s_waitcnt lgkmcnt(0)
	v_mfma_f32_16x16x32_bf16 v[60:63], v[144:147], v[184:187], v[60:63]
	v_mfma_f32_16x16x32_bf16 v[56:59], v[160:163], v[184:187], v[56:59]
	v_mfma_f32_16x16x32_bf16 v[44:47], v[144:147], v[192:195], v[44:47]
	v_mfma_f32_16x16x32_bf16 v[40:43], v[160:163], v[192:195], v[40:43]
	v_mfma_f32_16x16x32_bf16 v[28:31], v[144:147], v[200:203], v[28:31]
	v_mfma_f32_16x16x32_bf16 v[24:27], v[160:163], v[200:203], v[24:27]
	v_mfma_f32_16x16x32_bf16 v[12:15], v[144:147], v[212:215], v[12:15]
	v_mfma_f32_16x16x32_bf16 v[8:11], v[160:163], v[212:215], v[8:11]
	v_mfma_f32_16x16x32_bf16 v[60:63], v[156:159], v[188:191], v[60:63]
	v_mfma_f32_16x16x32_bf16 v[56:59], v[164:167], v[188:191], v[56:59]
	v_mfma_f32_16x16x32_bf16 v[44:47], v[156:159], v[196:199], v[44:47]
	v_mfma_f32_16x16x32_bf16 v[40:43], v[164:167], v[196:199], v[40:43]
	v_mfma_f32_16x16x32_bf16 v[28:31], v[156:159], v[208:211], v[28:31]
	v_mfma_f32_16x16x32_bf16 v[24:27], v[164:167], v[208:211], v[24:27]
	v_mfma_f32_16x16x32_bf16 v[12:15], v[156:159], v[216:219], v[12:15]
	v_mfma_f32_16x16x32_bf16 v[8:11], v[164:167], v[216:219], v[8:11]
	v_mfma_f32_16x16x32_bf16 v[52:55], v[168:171], v[184:187], v[52:55]
	v_mfma_f32_16x16x32_bf16 v[48:51], v[176:179], v[184:187], v[48:51]
	v_mfma_f32_16x16x32_bf16 v[36:39], v[168:171], v[192:195], v[36:39]
	v_mfma_f32_16x16x32_bf16 v[32:35], v[176:179], v[192:195], v[32:35]
	v_mfma_f32_16x16x32_bf16 v[20:23], v[168:171], v[200:203], v[20:23]
	v_mfma_f32_16x16x32_bf16 v[16:19], v[176:179], v[200:203], v[16:19]
	v_mfma_f32_16x16x32_bf16 v[4:7], v[168:171], v[212:215], v[4:7]
	v_mfma_f32_16x16x32_bf16 v[0:3], v[176:179], v[212:215], v[0:3]
	v_mfma_f32_16x16x32_bf16 v[52:55], v[172:175], v[188:191], v[52:55]
	v_mfma_f32_16x16x32_bf16 v[48:51], v[180:183], v[188:191], v[48:51]
	v_mfma_f32_16x16x32_bf16 v[36:39], v[172:175], v[196:199], v[36:39]
	v_mfma_f32_16x16x32_bf16 v[32:35], v[180:183], v[196:199], v[32:35]
	v_mfma_f32_16x16x32_bf16 v[20:23], v[172:175], v[208:211], v[20:23]
	v_mfma_f32_16x16x32_bf16 v[16:19], v[180:183], v[208:211], v[16:19]
	v_mfma_f32_16x16x32_bf16 v[4:7], v[172:175], v[216:219], v[4:7]
	v_mfma_f32_16x16x32_bf16 v[0:3], v[180:183], v[216:219], v[0:3]
	s_add_i32 s53, s53, 2
	s_add_u32 s51, s51, 0x100
	s_addc_u32 s52, s52, 0
	s_add_u32 s26, s26, 0x100
	s_addc_u32 s27, s27, 0
	s_cmp_gt_u32 s53, 13
	s_barrier
	s_cbranch_scc0 .LBB0_699
	s_setprio 0
	s_and_b64 vcc, exec, s[16:17]
	s_cbranch_vccz .LBB0_702
	s_barrier

.LBB0_778:
	ds_read_b128 v[140:143], v147
	ds_read_b128 v[150:153], v147 offset:1024
	ds_read_b128 v[154:157], v147 offset:2048
	ds_read_b128 v[158:161], v147 offset:3072
	ds_read_b128 v[162:165], v148
	ds_read_b128 v[166:169], v148 offset:1024
	ds_read_b128 v[170:173], v148 offset:2048
	ds_read_b128 v[174:177], v148 offset:3072
	s_add_u32 s30, s28, 0x100
	s_addc_u32 s31, s29, 0
	s_cmp_eq_u32 s58, 60
	s_cselect_b32 s37, s21, s31
	s_cselect_b32 s36, s27, s30
	s_cselect_b32 s35, s19, s57
	s_cselect_b32 s34, s55, s56
	s_add_i32 m0, s44, 0xc000
	ds_read_b128 v[178:181], v149
	ds_read_b128 v[182:185], v149 offset:1024
	ds_read_b128 v[186:189], v149 offset:2048
	ds_read_b128 v[190:193], v149 offset:3072
	ds_read_b128 v[194:197], v149 offset:4096
	ds_read_b128 v[198:201], v149 offset:5120
	ds_read_b128 v[202:205], v149 offset:6144
	ds_read_b128 v[208:211], v149 offset:7168
	global_load_lds_dwordx4 v134, s[28:29]
	s_add_i32 m0, s44, 0xe000
	s_nop 0
	global_load_lds_dwordx4 v132, s[28:29]
	s_waitcnt vmcnt(8)
	s_waitcnt lgkmcnt(0)
	s_barrier
	s_waitcnt lgkmcnt(0)
	v_mfma_f32_16x16x32_bf16 v[124:127], v[140:143], v[178:181], v[124:127]
	v_mfma_f32_16x16x32_bf16 v[120:123], v[154:157], v[178:181], v[120:123]
	v_mfma_f32_16x16x32_bf16 v[108:111], v[140:143], v[186:189], v[108:111]
	v_mfma_f32_16x16x32_bf16 v[104:107], v[154:157], v[186:189], v[104:107]
	v_mfma_f32_16x16x32_bf16 v[92:95], v[140:143], v[194:197], v[92:95]
	v_mfma_f32_16x16x32_bf16 v[88:91], v[154:157], v[194:197], v[88:91]
	v_mfma_f32_16x16x32_bf16 v[76:79], v[140:143], v[202:205], v[76:79]
	v_mfma_f32_16x16x32_bf16 v[72:75], v[154:157], v[202:205], v[72:75]
	v_mfma_f32_16x16x32_bf16 v[124:127], v[150:153], v[182:185], v[124:127]
	v_mfma_f32_16x16x32_bf16 v[120:123], v[158:161], v[182:185], v[120:123]
	v_mfma_f32_16x16x32_bf16 v[108:111], v[150:153], v[190:193], v[108:111]
	v_mfma_f32_16x16x32_bf16 v[104:107], v[158:161], v[190:193], v[104:107]
	v_mfma_f32_16x16x32_bf16 v[92:95], v[150:153], v[198:201], v[92:95]
	v_mfma_f32_16x16x32_bf16 v[88:91], v[158:161], v[198:201], v[88:91]
	v_mfma_f32_16x16x32_bf16 v[76:79], v[150:153], v[208:211], v[76:79]
	v_mfma_f32_16x16x32_bf16 v[72:75], v[158:161], v[208:211], v[72:75]
	v_mfma_f32_16x16x32_bf16 v[116:119], v[162:165], v[178:181], v[116:119]
	v_mfma_f32_16x16x32_bf16 v[112:115], v[170:173], v[178:181], v[112:115]
	v_mfma_f32_16x16x32_bf16 v[100:103], v[162:165], v[186:189], v[100:103]
	v_mfma_f32_16x16x32_bf16 v[96:99], v[170:173], v[186:189], v[96:99]
	v_mfma_f32_16x16x32_bf16 v[84:87], v[162:165], v[194:197], v[84:87]
	v_mfma_f32_16x16x32_bf16 v[80:83], v[170:173], v[194:197], v[80:83]
	v_mfma_f32_16x16x32_bf16 v[68:71], v[162:165], v[202:205], v[68:71]
	v_mfma_f32_16x16x32_bf16 v[64:67], v[170:173], v[202:205], v[64:67]
	v_mfma_f32_16x16x32_bf16 v[116:119], v[166:169], v[182:185], v[116:119]
	v_mfma_f32_16x16x32_bf16 v[112:115], v[174:177], v[182:185], v[112:115]
	v_mfma_f32_16x16x32_bf16 v[100:103], v[166:169], v[190:193], v[100:103]
	v_mfma_f32_16x16x32_bf16 v[96:99], v[174:177], v[190:193], v[96:99]
	v_mfma_f32_16x16x32_bf16 v[84:87], v[166:169], v[198:201], v[84:87]
	v_mfma_f32_16x16x32_bf16 v[80:83], v[174:177], v[198:201], v[80:83]
	v_mfma_f32_16x16x32_bf16 v[68:71], v[166:169], v[208:211], v[68:71]
	v_mfma_f32_16x16x32_bf16 v[64:67], v[174:177], v[208:211], v[64:67]
	s_add_i32 s28, s52, s43
	s_mov_b32 m0, s28
	s_barrier
	ds_read_b128 v[178:181], v149 offset:16384
	ds_read_b128 v[182:185], v149 offset:17408
	ds_read_b128 v[186:189], v149 offset:18432
	ds_read_b128 v[190:193], v149 offset:19456
	ds_read_b128 v[194:197], v149 offset:20480
	ds_read_b128 v[198:201], v149 offset:21504
	ds_read_b128 v[202:205], v149 offset:22528
	ds_read_b128 v[208:211], v149 offset:23552
	global_load_lds_dwordx4 v128, s[34:35]
	s_add_i32 m0, s28, 0x2000
	s_add_u32 s28, s34, 0x100000
	s_mov_b64 s[98:99], s[34:35]
	s_addc_u32 s29, s35, 0
	s_add_i32 s59, s53, s43
	global_load_lds_dwordx4 v130, s[34:35]
	s_mov_b32 m0, s59
	s_nop 0
	global_load_lds_dwordx4 v128, s[28:29]
	s_add_i32 m0, s59, 0x2000
	s_nop 0
	global_load_lds_dwordx4 v130, s[28:29]
	s_mov_b32 m0, s44
	s_nop 0
	global_load_lds_dwordx4 v128, s[36:37]
	s_mov_b32 m0, s45
	s_nop 0
	global_load_lds_dwordx4 v130, s[36:37]
	s_waitcnt vmcnt(8)
	s_waitcnt lgkmcnt(0)
	s_barrier
	s_waitcnt lgkmcnt(0)
	v_mfma_f32_16x16x32_bf16 v[60:63], v[140:143], v[178:181], v[60:63]
	v_mfma_f32_16x16x32_bf16 v[56:59], v[154:157], v[178:181], v[56:59]
	v_mfma_f32_16x16x32_bf16 v[44:47], v[140:143], v[186:189], v[44:47]
	v_mfma_f32_16x16x32_bf16 v[40:43], v[154:157], v[186:189], v[40:43]
	v_mfma_f32_16x16x32_bf16 v[28:31], v[140:143], v[194:197], v[28:31]
	v_mfma_f32_16x16x32_bf16 v[24:27], v[154:157], v[194:197], v[24:27]
	v_mfma_f32_16x16x32_bf16 v[12:15], v[140:143], v[202:205], v[12:15]
	v_mfma_f32_16x16x32_bf16 v[8:11], v[154:157], v[202:205], v[8:11]
	v_mfma_f32_16x16x32_bf16 v[60:63], v[150:153], v[182:185], v[60:63]
	v_mfma_f32_16x16x32_bf16 v[56:59], v[158:161], v[182:185], v[56:59]
	v_mfma_f32_16x16x32_bf16 v[44:47], v[150:153], v[190:193], v[44:47]
	v_mfma_f32_16x16x32_bf16 v[40:43], v[158:161], v[190:193], v[40:43]
	v_mfma_f32_16x16x32_bf16 v[28:31], v[150:153], v[198:201], v[28:31]
	v_mfma_f32_16x16x32_bf16 v[24:27], v[158:161], v[198:201], v[24:27]
	v_mfma_f32_16x16x32_bf16 v[12:15], v[150:153], v[208:211], v[12:15]
	v_mfma_f32_16x16x32_bf16 v[8:11], v[158:161], v[208:211], v[8:11]
	v_mfma_f32_16x16x32_bf16 v[52:55], v[162:165], v[178:181], v[52:55]
	v_mfma_f32_16x16x32_bf16 v[48:51], v[170:173], v[178:181], v[48:51]
	v_mfma_f32_16x16x32_bf16 v[36:39], v[162:165], v[186:189], v[36:39]
	v_mfma_f32_16x16x32_bf16 v[32:35], v[170:173], v[186:189], v[32:35]
	v_mfma_f32_16x16x32_bf16 v[20:23], v[162:165], v[194:197], v[20:23]
	v_mfma_f32_16x16x32_bf16 v[16:19], v[170:173], v[194:197], v[16:19]
	v_mfma_f32_16x16x32_bf16 v[4:7], v[162:165], v[202:205], v[4:7]
	v_mfma_f32_16x16x32_bf16 v[0:3], v[170:173], v[202:205], v[0:3]
	v_mfma_f32_16x16x32_bf16 v[52:55], v[166:169], v[182:185], v[52:55]
	v_mfma_f32_16x16x32_bf16 v[48:51], v[174:177], v[182:185], v[48:51]
	v_mfma_f32_16x16x32_bf16 v[36:39], v[166:169], v[190:193], v[36:39]
	v_mfma_f32_16x16x32_bf16 v[32:35], v[174:177], v[190:193], v[32:35]
	v_mfma_f32_16x16x32_bf16 v[20:23], v[166:169], v[198:201], v[20:23]
	v_mfma_f32_16x16x32_bf16 v[16:19], v[174:177], v[198:201], v[16:19]
	v_mfma_f32_16x16x32_bf16 v[4:7], v[166:169], v[208:211], v[4:7]
	v_mfma_f32_16x16x32_bf16 v[0:3], v[174:177], v[208:211], v[0:3]
	s_add_i32 s59, 0, 0x18000
	s_add_i32 s60, 0, 0x1c000
	s_barrier
	v_add_u32_e32 v158, s59, v145
	v_add_u32_e32 v174, s60, v145
	ds_read_b128 v[140:143], v158
	ds_read_b128 v[150:153], v158 offset:1024
	ds_read_b128 v[154:157], v158 offset:2048
	ds_read_b128 v[158:161], v158 offset:3072
	ds_read_b128 v[162:165], v174
	ds_read_b128 v[166:169], v174 offset:1024
	ds_read_b128 v[170:173], v174 offset:2048
	ds_read_b128 v[174:177], v174 offset:3072
	s_add_u32 s28, s36, 0x100000
	s_addc_u32 s29, s37, 0
	s_mov_b32 m0, s46
	ds_read_b128 v[178:181], v149 offset:32768
	ds_read_b128 v[182:185], v149 offset:33792
	ds_read_b128 v[186:189], v149 offset:34816
	ds_read_b128 v[190:193], v149 offset:35840
	ds_read_b128 v[194:197], v149 offset:36864
	ds_read_b128 v[198:201], v149 offset:37888
	ds_read_b128 v[202:205], v149 offset:38912
	ds_read_b128 v[208:211], v149 offset:39936
	global_load_lds_dwordx4 v128, s[28:29]
	s_mov_b32 m0, s47
	s_nop 0
	global_load_lds_dwordx4 v130, s[28:29]
	s_waitcnt vmcnt(8)
	s_waitcnt lgkmcnt(0)
	s_barrier
	s_waitcnt lgkmcnt(0)
	v_mfma_f32_16x16x32_bf16 v[124:127], v[140:143], v[178:181], v[124:127]
	v_mfma_f32_16x16x32_bf16 v[120:123], v[154:157], v[178:181], v[120:123]
	v_mfma_f32_16x16x32_bf16 v[108:111], v[140:143], v[186:189], v[108:111]
	v_mfma_f32_16x16x32_bf16 v[104:107], v[154:157], v[186:189], v[104:107]
	v_mfma_f32_16x16x32_bf16 v[92:95], v[140:143], v[194:197], v[92:95]
	v_mfma_f32_16x16x32_bf16 v[88:91], v[154:157], v[194:197], v[88:91]
	v_mfma_f32_16x16x32_bf16 v[76:79], v[140:143], v[202:205], v[76:79]
	v_mfma_f32_16x16x32_bf16 v[72:75], v[154:157], v[202:205], v[72:75]
	v_mfma_f32_16x16x32_bf16 v[124:127], v[150:153], v[182:185], v[124:127]
	v_mfma_f32_16x16x32_bf16 v[120:123], v[158:161], v[182:185], v[120:123]
	v_mfma_f32_16x16x32_bf16 v[108:111], v[150:153], v[190:193], v[108:111]
	v_mfma_f32_16x16x32_bf16 v[104:107], v[158:161], v[190:193], v[104:107]
	v_mfma_f32_16x16x32_bf16 v[92:95], v[150:153], v[198:201], v[92:95]
	v_mfma_f32_16x16x32_bf16 v[88:91], v[158:161], v[198:201], v[88:91]
	v_mfma_f32_16x16x32_bf16 v[76:79], v[150:153], v[208:211], v[76:79]
	v_mfma_f32_16x16x32_bf16 v[72:75], v[158:161], v[208:211], v[72:75]
	v_mfma_f32_16x16x32_bf16 v[116:119], v[162:165], v[178:181], v[116:119]
	v_mfma_f32_16x16x32_bf16 v[112:115], v[170:173], v[178:181], v[112:115]
	v_mfma_f32_16x16x32_bf16 v[100:103], v[162:165], v[186:189], v[100:103]
	v_mfma_f32_16x16x32_bf16 v[96:99], v[170:173], v[186:189], v[96:99]
	v_mfma_f32_16x16x32_bf16 v[84:87], v[162:165], v[194:197], v[84:87]
	v_mfma_f32_16x16x32_bf16 v[80:83], v[170:173], v[194:197], v[80:83]
	v_mfma_f32_16x16x32_bf16 v[68:71], v[162:165], v[202:205], v[68:71]
	v_mfma_f32_16x16x32_bf16 v[64:67], v[170:173], v[202:205], v[64:67]
	v_mfma_f32_16x16x32_bf16 v[116:119], v[166:169], v[182:185], v[116:119]
	v_mfma_f32_16x16x32_bf16 v[112:115], v[174:177], v[182:185], v[112:115]
	v_mfma_f32_16x16x32_bf16 v[100:103], v[166:169], v[190:193], v[100:103]
	v_mfma_f32_16x16x32_bf16 v[96:99], v[174:177], v[190:193], v[96:99]
	v_mfma_f32_16x16x32_bf16 v[84:87], v[166:169], v[198:201], v[84:87]
	v_mfma_f32_16x16x32_bf16 v[80:83], v[174:177], v[198:201], v[80:83]
	v_mfma_f32_16x16x32_bf16 v[68:71], v[166:169], v[208:211], v[68:71]
	v_mfma_f32_16x16x32_bf16 v[64:67], v[174:177], v[208:211], v[64:67]
	s_add_i32 s28, s59, s43
	s_mov_b32 m0, s28
	s_barrier
	ds_read_b128 v[178:181], v149 offset:49152
	ds_read_b128 v[182:185], v149 offset:50176
	ds_read_b128 v[186:189], v149 offset:51200
	ds_read_b128 v[190:193], v149 offset:52224
	ds_read_b128 v[194:197], v149 offset:53248
	ds_read_b128 v[198:201], v149 offset:54272
	ds_read_b128 v[202:205], v149 offset:55296
	ds_read_b128 v[208:211], v149 offset:56320
	global_load_lds_dwordx4 v212, s[34:35]
	s_add_i32 m0, s28, 0x2000
	s_add_u32 s28, s34, 0x100080
	s_addc_u32 s29, s35, 0
	s_add_i32 s34, s60, s43
	global_load_lds_dwordx4 v213, s[98:99]
	s_mov_b32 m0, s34
	s_nop 0
	global_load_lds_dwordx4 v128, s[28:29]
	s_add_i32 m0, s34, 0x2000
	s_nop 0
	global_load_lds_dwordx4 v130, s[28:29]
	s_mov_b32 m0, s49
	s_nop 0
	global_load_lds_dwordx4 v212, s[36:37]
	s_mov_b32 m0, s50
	s_nop 0
	global_load_lds_dwordx4 v213, s[36:37]
	s_waitcnt vmcnt(8)
	s_waitcnt lgkmcnt(0)
	s_barrier
	s_waitcnt lgkmcnt(0)
	v_mfma_f32_16x16x32_bf16 v[60:63], v[140:143], v[178:181], v[60:63]
	v_mfma_f32_16x16x32_bf16 v[56:59], v[154:157], v[178:181], v[56:59]
	v_mfma_f32_16x16x32_bf16 v[44:47], v[140:143], v[186:189], v[44:47]
	v_mfma_f32_16x16x32_bf16 v[40:43], v[154:157], v[186:189], v[40:43]
	v_mfma_f32_16x16x32_bf16 v[28:31], v[140:143], v[194:197], v[28:31]
	v_mfma_f32_16x16x32_bf16 v[24:27], v[154:157], v[194:197], v[24:27]
	v_mfma_f32_16x16x32_bf16 v[12:15], v[140:143], v[202:205], v[12:15]
	v_mfma_f32_16x16x32_bf16 v[8:11], v[154:157], v[202:205], v[8:11]
	v_mfma_f32_16x16x32_bf16 v[60:63], v[150:153], v[182:185], v[60:63]
	v_mfma_f32_16x16x32_bf16 v[56:59], v[158:161], v[182:185], v[56:59]
	v_mfma_f32_16x16x32_bf16 v[44:47], v[150:153], v[190:193], v[44:47]
	v_mfma_f32_16x16x32_bf16 v[40:43], v[158:161], v[190:193], v[40:43]
	v_mfma_f32_16x16x32_bf16 v[28:31], v[150:153], v[198:201], v[28:31]
	v_mfma_f32_16x16x32_bf16 v[24:27], v[158:161], v[198:201], v[24:27]
	v_mfma_f32_16x16x32_bf16 v[12:15], v[150:153], v[208:211], v[12:15]
	v_mfma_f32_16x16x32_bf16 v[8:11], v[158:161], v[208:211], v[8:11]
	v_mfma_f32_16x16x32_bf16 v[52:55], v[162:165], v[178:181], v[52:55]
	v_mfma_f32_16x16x32_bf16 v[48:51], v[170:173], v[178:181], v[48:51]
	v_mfma_f32_16x16x32_bf16 v[36:39], v[162:165], v[186:189], v[36:39]
	v_mfma_f32_16x16x32_bf16 v[32:35], v[170:173], v[186:189], v[32:35]
	v_mfma_f32_16x16x32_bf16 v[20:23], v[162:165], v[194:197], v[20:23]
	v_mfma_f32_16x16x32_bf16 v[16:19], v[170:173], v[194:197], v[16:19]
	v_mfma_f32_16x16x32_bf16 v[4:7], v[162:165], v[202:205], v[4:7]
	v_mfma_f32_16x16x32_bf16 v[0:3], v[170:173], v[202:205], v[0:3]
	v_mfma_f32_16x16x32_bf16 v[52:55], v[166:169], v[182:185], v[52:55]
	v_mfma_f32_16x16x32_bf16 v[48:51], v[174:177], v[182:185], v[48:51]
	v_mfma_f32_16x16x32_bf16 v[36:39], v[166:169], v[190:193], v[36:39]
	v_mfma_f32_16x16x32_bf16 v[32:35], v[174:177], v[190:193], v[32:35]
	v_mfma_f32_16x16x32_bf16 v[20:23], v[166:169], v[198:201], v[20:23]
	v_mfma_f32_16x16x32_bf16 v[16:19], v[174:177], v[198:201], v[16:19]
	v_mfma_f32_16x16x32_bf16 v[4:7], v[166:169], v[208:211], v[4:7]
	v_mfma_f32_16x16x32_bf16 v[0:3], v[174:177], v[208:211], v[0:3]
	s_add_i32 s58, s58, 2
	s_add_u32 s56, s56, 0x100
	s_addc_u32 s57, s57, 0
	s_cmp_gt_u32 s58, 61
	s_mov_b64 s[28:29], s[30:31]
	s_barrier
	s_cbranch_scc0 .LBB0_778
	s_setprio 0
	s_and_b64 vcc, exec, s[16:17]
	s_cbranch_vccz .LBB0_781
	s_barrier

.LBB0_895:
	ds_read_b128 v[140:143], v153
	ds_read_b128 v[144:147], v153 offset:1024
	ds_read_b128 v[158:161], v153 offset:2048
	ds_read_b128 v[162:165], v153 offset:3072
	ds_read_b128 v[166:169], v154
	ds_read_b128 v[170:173], v154 offset:1024
	ds_read_b128 v[174:177], v154 offset:2048
	ds_read_b128 v[178:181], v154 offset:3072
	s_add_u32 s38, s36, 0xfffc0080
	s_addc_u32 s39, s37, -1
	s_cmp_eq_u32 s61, 12
	s_cselect_b32 s41, s3, s39
	s_cselect_b32 s40, s29, s38
	s_cselect_b32 s39, s27, s60
	s_cselect_b32 s38, s58, s59
	s_add_i32 m0, s46, 0xc000
	ds_read_b128 v[182:185], v155
	ds_read_b128 v[186:189], v155 offset:1024
	ds_read_b128 v[190:193], v155 offset:2048
	ds_read_b128 v[194:197], v155 offset:3072
	ds_read_b128 v[198:201], v155 offset:4096
	ds_read_b128 v[202:205], v155 offset:5120
	ds_read_b128 v[208:211], v155 offset:6144
	ds_read_b128 v[212:215], v155 offset:7168
	global_load_lds_dwordx4 v134, s[36:37]
	s_add_i32 m0, s46, 0xe000
	s_nop 0
	global_load_lds_dwordx4 v132, s[36:37]
	s_waitcnt vmcnt(8)
	s_waitcnt lgkmcnt(0)
	s_barrier
	s_waitcnt lgkmcnt(0)
	v_mfma_f32_16x16x32_bf16 v[124:127], v[140:143], v[182:185], v[124:127]
	v_mfma_f32_16x16x32_bf16 v[120:123], v[158:161], v[182:185], v[120:123]
	v_mfma_f32_16x16x32_bf16 v[108:111], v[140:143], v[190:193], v[108:111]
	v_mfma_f32_16x16x32_bf16 v[104:107], v[158:161], v[190:193], v[104:107]
	v_mfma_f32_16x16x32_bf16 v[92:95], v[140:143], v[198:201], v[92:95]
	v_mfma_f32_16x16x32_bf16 v[88:91], v[158:161], v[198:201], v[88:91]
	v_mfma_f32_16x16x32_bf16 v[76:79], v[140:143], v[208:211], v[76:79]
	v_mfma_f32_16x16x32_bf16 v[72:75], v[158:161], v[208:211], v[72:75]
	v_mfma_f32_16x16x32_bf16 v[124:127], v[144:147], v[186:189], v[124:127]
	v_mfma_f32_16x16x32_bf16 v[120:123], v[162:165], v[186:189], v[120:123]
	v_mfma_f32_16x16x32_bf16 v[108:111], v[144:147], v[194:197], v[108:111]
	v_mfma_f32_16x16x32_bf16 v[104:107], v[162:165], v[194:197], v[104:107]
	v_mfma_f32_16x16x32_bf16 v[92:95], v[144:147], v[202:205], v[92:95]
	v_mfma_f32_16x16x32_bf16 v[88:91], v[162:165], v[202:205], v[88:91]
	v_mfma_f32_16x16x32_bf16 v[76:79], v[144:147], v[212:215], v[76:79]
	v_mfma_f32_16x16x32_bf16 v[72:75], v[162:165], v[212:215], v[72:75]
	v_mfma_f32_16x16x32_bf16 v[116:119], v[166:169], v[182:185], v[116:119]
	v_mfma_f32_16x16x32_bf16 v[112:115], v[174:177], v[182:185], v[112:115]
	v_mfma_f32_16x16x32_bf16 v[100:103], v[166:169], v[190:193], v[100:103]
	v_mfma_f32_16x16x32_bf16 v[96:99], v[174:177], v[190:193], v[96:99]
	v_mfma_f32_16x16x32_bf16 v[84:87], v[166:169], v[198:201], v[84:87]
	v_mfma_f32_16x16x32_bf16 v[80:83], v[174:177], v[198:201], v[80:83]
	v_mfma_f32_16x16x32_bf16 v[68:71], v[166:169], v[208:211], v[68:71]
	v_mfma_f32_16x16x32_bf16 v[64:67], v[174:177], v[208:211], v[64:67]
	v_mfma_f32_16x16x32_bf16 v[116:119], v[170:173], v[186:189], v[116:119]
	v_mfma_f32_16x16x32_bf16 v[112:115], v[178:181], v[186:189], v[112:115]
	v_mfma_f32_16x16x32_bf16 v[100:103], v[170:173], v[194:197], v[100:103]
	v_mfma_f32_16x16x32_bf16 v[96:99], v[178:181], v[194:197], v[96:99]
	v_mfma_f32_16x16x32_bf16 v[84:87], v[170:173], v[202:205], v[84:87]
	v_mfma_f32_16x16x32_bf16 v[80:83], v[178:181], v[202:205], v[80:83]
	v_mfma_f32_16x16x32_bf16 v[68:71], v[170:173], v[212:215], v[68:71]
	v_mfma_f32_16x16x32_bf16 v[64:67], v[178:181], v[212:215], v[64:67]
	s_add_i32 s62, s54, s45
	s_mov_b32 m0, s62
	s_barrier
	ds_read_b128 v[182:185], v155 offset:16384
	ds_read_b128 v[186:189], v155 offset:17408
	ds_read_b128 v[190:193], v155 offset:18432
	ds_read_b128 v[194:197], v155 offset:19456
	ds_read_b128 v[198:201], v155 offset:20480
	ds_read_b128 v[202:205], v155 offset:21504
	ds_read_b128 v[208:211], v155 offset:22528
	ds_read_b128 v[212:215], v155 offset:23552
	global_load_lds_dwordx4 v128, s[38:39]
	s_add_i32 m0, s62, 0x2000
	s_add_u32 s62, s38, 0x40000
	s_mov_b64 s[98:99], s[38:39]
	s_addc_u32 s63, s39, 0
	s_add_i32 s64, s55, s45
	global_load_lds_dwordx4 v130, s[38:39]
	s_mov_b32 m0, s64
	s_mov_b64 s[100:101], s[40:41]
	global_load_lds_dwordx4 v128, s[62:63]
	s_add_i32 m0, s64, 0x2000
	s_nop 0
	global_load_lds_dwordx4 v130, s[62:63]
	s_mov_b32 m0, s46
	s_nop 0
	global_load_lds_dwordx4 v128, s[40:41]
	s_mov_b32 m0, s47
	s_nop 0
	global_load_lds_dwordx4 v130, s[40:41]
	s_waitcnt vmcnt(8)
	s_waitcnt lgkmcnt(0)
	s_barrier
	s_waitcnt lgkmcnt(0)
	v_mfma_f32_16x16x32_bf16 v[60:63], v[140:143], v[182:185], v[60:63]
	v_mfma_f32_16x16x32_bf16 v[56:59], v[158:161], v[182:185], v[56:59]
	v_mfma_f32_16x16x32_bf16 v[44:47], v[140:143], v[190:193], v[44:47]
	v_mfma_f32_16x16x32_bf16 v[40:43], v[158:161], v[190:193], v[40:43]
	v_mfma_f32_16x16x32_bf16 v[28:31], v[140:143], v[198:201], v[28:31]
	v_mfma_f32_16x16x32_bf16 v[24:27], v[158:161], v[198:201], v[24:27]
	v_mfma_f32_16x16x32_bf16 v[12:15], v[140:143], v[208:211], v[12:15]
	v_mfma_f32_16x16x32_bf16 v[8:11], v[158:161], v[208:211], v[8:11]
	v_mfma_f32_16x16x32_bf16 v[60:63], v[144:147], v[186:189], v[60:63]
	v_mfma_f32_16x16x32_bf16 v[56:59], v[162:165], v[186:189], v[56:59]
	v_mfma_f32_16x16x32_bf16 v[44:47], v[144:147], v[194:197], v[44:47]
	v_mfma_f32_16x16x32_bf16 v[40:43], v[162:165], v[194:197], v[40:43]
	v_mfma_f32_16x16x32_bf16 v[28:31], v[144:147], v[202:205], v[28:31]
	v_mfma_f32_16x16x32_bf16 v[24:27], v[162:165], v[202:205], v[24:27]
	v_mfma_f32_16x16x32_bf16 v[12:15], v[144:147], v[212:215], v[12:15]
	v_mfma_f32_16x16x32_bf16 v[8:11], v[162:165], v[212:215], v[8:11]
	v_mfma_f32_16x16x32_bf16 v[52:55], v[166:169], v[182:185], v[52:55]
	v_mfma_f32_16x16x32_bf16 v[48:51], v[174:177], v[182:185], v[48:51]
	v_mfma_f32_16x16x32_bf16 v[36:39], v[166:169], v[190:193], v[36:39]
	v_mfma_f32_16x16x32_bf16 v[32:35], v[174:177], v[190:193], v[32:35]
	v_mfma_f32_16x16x32_bf16 v[20:23], v[166:169], v[198:201], v[20:23]
	v_mfma_f32_16x16x32_bf16 v[16:19], v[174:177], v[198:201], v[16:19]
	v_mfma_f32_16x16x32_bf16 v[4:7], v[166:169], v[208:211], v[4:7]
	v_mfma_f32_16x16x32_bf16 v[0:3], v[174:177], v[208:211], v[0:3]
	v_mfma_f32_16x16x32_bf16 v[52:55], v[170:173], v[186:189], v[52:55]
	v_mfma_f32_16x16x32_bf16 v[48:51], v[178:181], v[186:189], v[48:51]
	v_mfma_f32_16x16x32_bf16 v[36:39], v[170:173], v[194:197], v[36:39]
	v_mfma_f32_16x16x32_bf16 v[32:35], v[178:181], v[194:197], v[32:35]
	v_mfma_f32_16x16x32_bf16 v[20:23], v[170:173], v[202:205], v[20:23]
	v_mfma_f32_16x16x32_bf16 v[16:19], v[178:181], v[202:205], v[16:19]
	v_mfma_f32_16x16x32_bf16 v[4:7], v[170:173], v[212:215], v[4:7]
	v_mfma_f32_16x16x32_bf16 v[0:3], v[178:181], v[212:215], v[0:3]
	s_add_i32 s62, 0, 0x18000
	s_barrier
	v_add_u32_e32 v157, s62, v151
	s_add_i32 s63, 0, 0x1c000
	ds_read_b128 v[140:143], v157
	ds_read_b128 v[144:147], v157 offset:1024
	ds_read_b128 v[158:161], v157 offset:2048
	ds_read_b128 v[162:165], v157 offset:3072
	v_add_u32_e32 v157, s63, v151
	ds_read_b128 v[166:169], v157
	ds_read_b128 v[170:173], v157 offset:1024
	ds_read_b128 v[174:177], v157 offset:2048
	ds_read_b128 v[178:181], v157 offset:3072
	s_add_u32 s40, s40, 0x40000
	s_addc_u32 s41, s41, 0
	s_mov_b32 m0, s48
	ds_read_b128 v[182:185], v155 offset:32768
	ds_read_b128 v[186:189], v155 offset:33792
	ds_read_b128 v[190:193], v155 offset:34816
	ds_read_b128 v[194:197], v155 offset:35840
	ds_read_b128 v[198:201], v155 offset:36864
	ds_read_b128 v[202:205], v155 offset:37888
	ds_read_b128 v[208:211], v155 offset:38912
	ds_read_b128 v[212:215], v155 offset:39936
	global_load_lds_dwordx4 v128, s[40:41]
	s_mov_b32 m0, s49
	s_nop 0
	global_load_lds_dwordx4 v130, s[40:41]
	s_waitcnt vmcnt(8)
	s_waitcnt lgkmcnt(0)
	s_barrier
	s_waitcnt lgkmcnt(0)
	v_mfma_f32_16x16x32_bf16 v[124:127], v[140:143], v[182:185], v[124:127]
	v_mfma_f32_16x16x32_bf16 v[120:123], v[158:161], v[182:185], v[120:123]
	v_mfma_f32_16x16x32_bf16 v[108:111], v[140:143], v[190:193], v[108:111]
	v_mfma_f32_16x16x32_bf16 v[104:107], v[158:161], v[190:193], v[104:107]
	v_mfma_f32_16x16x32_bf16 v[92:95], v[140:143], v[198:201], v[92:95]
	v_mfma_f32_16x16x32_bf16 v[88:91], v[158:161], v[198:201], v[88:91]
	v_mfma_f32_16x16x32_bf16 v[76:79], v[140:143], v[208:211], v[76:79]
	v_mfma_f32_16x16x32_bf16 v[72:75], v[158:161], v[208:211], v[72:75]
	v_mfma_f32_16x16x32_bf16 v[124:127], v[144:147], v[186:189], v[124:127]
	v_mfma_f32_16x16x32_bf16 v[120:123], v[162:165], v[186:189], v[120:123]
	v_mfma_f32_16x16x32_bf16 v[108:111], v[144:147], v[194:197], v[108:111]
	v_mfma_f32_16x16x32_bf16 v[104:107], v[162:165], v[194:197], v[104:107]
	v_mfma_f32_16x16x32_bf16 v[92:95], v[144:147], v[202:205], v[92:95]
	v_mfma_f32_16x16x32_bf16 v[88:91], v[162:165], v[202:205], v[88:91]
	v_mfma_f32_16x16x32_bf16 v[76:79], v[144:147], v[212:215], v[76:79]
	v_mfma_f32_16x16x32_bf16 v[72:75], v[162:165], v[212:215], v[72:75]
	v_mfma_f32_16x16x32_bf16 v[116:119], v[166:169], v[182:185], v[116:119]
	v_mfma_f32_16x16x32_bf16 v[112:115], v[174:177], v[182:185], v[112:115]
	v_mfma_f32_16x16x32_bf16 v[100:103], v[166:169], v[190:193], v[100:103]
	v_mfma_f32_16x16x32_bf16 v[96:99], v[174:177], v[190:193], v[96:99]
	v_mfma_f32_16x16x32_bf16 v[84:87], v[166:169], v[198:201], v[84:87]
	v_mfma_f32_16x16x32_bf16 v[80:83], v[174:177], v[198:201], v[80:83]
	v_mfma_f32_16x16x32_bf16 v[68:71], v[166:169], v[208:211], v[68:71]
	v_mfma_f32_16x16x32_bf16 v[64:67], v[174:177], v[208:211], v[64:67]
	v_mfma_f32_16x16x32_bf16 v[116:119], v[170:173], v[186:189], v[116:119]
	v_mfma_f32_16x16x32_bf16 v[112:115], v[178:181], v[186:189], v[112:115]
	v_mfma_f32_16x16x32_bf16 v[100:103], v[170:173], v[194:197], v[100:103]
	v_mfma_f32_16x16x32_bf16 v[96:99], v[178:181], v[194:197], v[96:99]
	v_mfma_f32_16x16x32_bf16 v[84:87], v[170:173], v[202:205], v[84:87]
	v_mfma_f32_16x16x32_bf16 v[80:83], v[178:181], v[202:205], v[80:83]
	v_mfma_f32_16x16x32_bf16 v[68:71], v[170:173], v[212:215], v[68:71]
	v_mfma_f32_16x16x32_bf16 v[64:67], v[178:181], v[212:215], v[64:67]
	s_add_i32 s40, s62, s45
	s_mov_b32 m0, s40
	s_barrier
	ds_read_b128 v[182:185], v155 offset:49152
	ds_read_b128 v[186:189], v155 offset:50176
	ds_read_b128 v[190:193], v155 offset:51200
	ds_read_b128 v[194:197], v155 offset:52224
	ds_read_b128 v[198:201], v155 offset:53248
	ds_read_b128 v[202:205], v155 offset:54272
	ds_read_b128 v[208:211], v155 offset:55296
	ds_read_b128 v[212:215], v155 offset:56320
	global_load_lds_dwordx4 v148, s[38:39]
	s_add_i32 m0, s40, 0x2000
	s_add_u32 s38, s38, 0x40080
	s_addc_u32 s39, s39, 0
	s_add_i32 s40, s63, s45
	global_load_lds_dwordx4 v149, s[98:99]
	s_mov_b32 m0, s40
	s_nop 0
	global_load_lds_dwordx4 v128, s[38:39]
	s_add_i32 m0, s40, 0x2000
	s_nop 0
	global_load_lds_dwordx4 v130, s[38:39]
	s_mov_b32 m0, s51
	s_nop 0
	global_load_lds_dwordx4 v148, s[100:101]
	s_mov_b32 m0, s52
	s_nop 0
	global_load_lds_dwordx4 v149, s[100:101]
	s_waitcnt vmcnt(8)
	s_waitcnt lgkmcnt(0)
	s_barrier
	s_waitcnt lgkmcnt(0)
	v_mfma_f32_16x16x32_bf16 v[60:63], v[140:143], v[182:185], v[60:63]
	v_mfma_f32_16x16x32_bf16 v[56:59], v[158:161], v[182:185], v[56:59]
	v_mfma_f32_16x16x32_bf16 v[44:47], v[140:143], v[190:193], v[44:47]
	v_mfma_f32_16x16x32_bf16 v[40:43], v[158:161], v[190:193], v[40:43]
	v_mfma_f32_16x16x32_bf16 v[28:31], v[140:143], v[198:201], v[28:31]
	v_mfma_f32_16x16x32_bf16 v[24:27], v[158:161], v[198:201], v[24:27]
	v_mfma_f32_16x16x32_bf16 v[12:15], v[140:143], v[208:211], v[12:15]
	v_mfma_f32_16x16x32_bf16 v[8:11], v[158:161], v[208:211], v[8:11]
	v_mfma_f32_16x16x32_bf16 v[60:63], v[144:147], v[186:189], v[60:63]
	v_mfma_f32_16x16x32_bf16 v[56:59], v[162:165], v[186:189], v[56:59]
	v_mfma_f32_16x16x32_bf16 v[44:47], v[144:147], v[194:197], v[44:47]
	v_mfma_f32_16x16x32_bf16 v[40:43], v[162:165], v[194:197], v[40:43]
	v_mfma_f32_16x16x32_bf16 v[28:31], v[144:147], v[202:205], v[28:31]
	v_mfma_f32_16x16x32_bf16 v[24:27], v[162:165], v[202:205], v[24:27]
	v_mfma_f32_16x16x32_bf16 v[12:15], v[144:147], v[212:215], v[12:15]
	v_mfma_f32_16x16x32_bf16 v[8:11], v[162:165], v[212:215], v[8:11]
	v_mfma_f32_16x16x32_bf16 v[52:55], v[166:169], v[182:185], v[52:55]
	v_mfma_f32_16x16x32_bf16 v[48:51], v[174:177], v[182:185], v[48:51]
	v_mfma_f32_16x16x32_bf16 v[36:39], v[166:169], v[190:193], v[36:39]
	v_mfma_f32_16x16x32_bf16 v[32:35], v[174:177], v[190:193], v[32:35]
	v_mfma_f32_16x16x32_bf16 v[20:23], v[166:169], v[198:201], v[20:23]
	v_mfma_f32_16x16x32_bf16 v[16:19], v[174:177], v[198:201], v[16:19]
	v_mfma_f32_16x16x32_bf16 v[4:7], v[166:169], v[208:211], v[4:7]
	v_mfma_f32_16x16x32_bf16 v[0:3], v[174:177], v[208:211], v[0:3]
	v_mfma_f32_16x16x32_bf16 v[52:55], v[170:173], v[186:189], v[52:55]
	v_mfma_f32_16x16x32_bf16 v[48:51], v[178:181], v[186:189], v[48:51]
	v_mfma_f32_16x16x32_bf16 v[36:39], v[170:173], v[194:197], v[36:39]
	v_mfma_f32_16x16x32_bf16 v[32:35], v[178:181], v[194:197], v[32:35]
	v_mfma_f32_16x16x32_bf16 v[20:23], v[170:173], v[202:205], v[20:23]
	v_mfma_f32_16x16x32_bf16 v[16:19], v[178:181], v[202:205], v[16:19]
	v_mfma_f32_16x16x32_bf16 v[4:7], v[170:173], v[212:215], v[4:7]
	v_mfma_f32_16x16x32_bf16 v[0:3], v[178:181], v[212:215], v[0:3]
	s_add_i32 s61, s61, 2
	s_add_u32 s59, s59, 0x100
	s_addc_u32 s60, s60, 0
	s_add_u32 s36, s36, 0x100
	s_addc_u32 s37, s37, 0
	s_cmp_gt_u32 s61, 13
	s_barrier
	s_cbranch_scc0 .LBB0_895
	s_setprio 0
	s_and_b64 vcc, exec, s[24:25]
	s_cbranch_vccz .LBB0_898
	s_barrier

.LBB0_988:
	ds_read_b128 v[144:147], v151
	ds_read_b128 v[156:159], v151 offset:1024
	ds_read_b128 v[160:163], v151 offset:2048
	ds_read_b128 v[164:167], v151 offset:3072
	ds_read_b128 v[168:171], v152
	ds_read_b128 v[172:175], v152 offset:1024
	ds_read_b128 v[176:179], v152 offset:2048
	ds_read_b128 v[180:183], v152 offset:3072
	s_add_u32 s26, s6, 0xfffc0080
	s_addc_u32 s27, s7, -1
	s_cmp_eq_u32 s53, 12
	s_cselect_b32 s29, s19, s27
	s_cselect_b32 s28, s49, s26
	s_cselect_b32 s27, s17, s52
	s_cselect_b32 s26, s50, s51
	s_add_i32 m0, s25, 0xc000
	ds_read_b128 v[184:187], v153
	ds_read_b128 v[188:191], v153 offset:1024
	ds_read_b128 v[192:195], v153 offset:2048
	ds_read_b128 v[196:199], v153 offset:3072
	ds_read_b128 v[200:203], v153 offset:4096
	ds_read_b128 v[208:211], v153 offset:5120
	ds_read_b128 v[212:215], v153 offset:6144
	ds_read_b128 v[216:219], v153 offset:7168
	global_load_lds_dwordx4 v138, s[6:7]
	s_add_i32 m0, s25, 0xe000
	s_nop 0
	global_load_lds_dwordx4 v136, s[6:7]
	s_waitcnt vmcnt(8)
	s_waitcnt lgkmcnt(0)
	s_barrier
	s_waitcnt lgkmcnt(0)
	v_mfma_f32_16x16x32_bf16 v[124:127], v[144:147], v[184:187], v[124:127]
	v_mfma_f32_16x16x32_bf16 v[120:123], v[160:163], v[184:187], v[120:123]
	v_mfma_f32_16x16x32_bf16 v[108:111], v[144:147], v[192:195], v[108:111]
	v_mfma_f32_16x16x32_bf16 v[104:107], v[160:163], v[192:195], v[104:107]
	v_mfma_f32_16x16x32_bf16 v[92:95], v[144:147], v[200:203], v[92:95]
	v_mfma_f32_16x16x32_bf16 v[88:91], v[160:163], v[200:203], v[88:91]
	v_mfma_f32_16x16x32_bf16 v[76:79], v[144:147], v[212:215], v[76:79]
	v_mfma_f32_16x16x32_bf16 v[72:75], v[160:163], v[212:215], v[72:75]
	v_mfma_f32_16x16x32_bf16 v[124:127], v[156:159], v[188:191], v[124:127]
	v_mfma_f32_16x16x32_bf16 v[120:123], v[164:167], v[188:191], v[120:123]
	v_mfma_f32_16x16x32_bf16 v[108:111], v[156:159], v[196:199], v[108:111]
	v_mfma_f32_16x16x32_bf16 v[104:107], v[164:167], v[196:199], v[104:107]
	v_mfma_f32_16x16x32_bf16 v[92:95], v[156:159], v[208:211], v[92:95]
	v_mfma_f32_16x16x32_bf16 v[88:91], v[164:167], v[208:211], v[88:91]
	v_mfma_f32_16x16x32_bf16 v[76:79], v[156:159], v[216:219], v[76:79]
	v_mfma_f32_16x16x32_bf16 v[72:75], v[164:167], v[216:219], v[72:75]
	v_mfma_f32_16x16x32_bf16 v[116:119], v[168:171], v[184:187], v[116:119]
	v_mfma_f32_16x16x32_bf16 v[112:115], v[176:179], v[184:187], v[112:115]
	v_mfma_f32_16x16x32_bf16 v[100:103], v[168:171], v[192:195], v[100:103]
	v_mfma_f32_16x16x32_bf16 v[96:99], v[176:179], v[192:195], v[96:99]
	v_mfma_f32_16x16x32_bf16 v[84:87], v[168:171], v[200:203], v[84:87]
	v_mfma_f32_16x16x32_bf16 v[80:83], v[176:179], v[200:203], v[80:83]
	v_mfma_f32_16x16x32_bf16 v[68:71], v[168:171], v[212:215], v[68:71]
	v_mfma_f32_16x16x32_bf16 v[64:67], v[176:179], v[212:215], v[64:67]
	v_mfma_f32_16x16x32_bf16 v[116:119], v[172:175], v[188:191], v[116:119]
	v_mfma_f32_16x16x32_bf16 v[112:115], v[180:183], v[188:191], v[112:115]
	v_mfma_f32_16x16x32_bf16 v[100:103], v[172:175], v[196:199], v[100:103]
	v_mfma_f32_16x16x32_bf16 v[96:99], v[180:183], v[196:199], v[96:99]
	v_mfma_f32_16x16x32_bf16 v[84:87], v[172:175], v[208:211], v[84:87]
	v_mfma_f32_16x16x32_bf16 v[80:83], v[180:183], v[208:211], v[80:83]
	v_mfma_f32_16x16x32_bf16 v[68:71], v[172:175], v[216:219], v[68:71]
	v_mfma_f32_16x16x32_bf16 v[64:67], v[180:183], v[216:219], v[64:67]
	s_add_i32 s54, s45, s38
	s_mov_b32 m0, s54
	s_barrier
	ds_read_b128 v[184:187], v153 offset:16384
	ds_read_b128 v[188:191], v153 offset:17408
	ds_read_b128 v[192:195], v153 offset:18432
	ds_read_b128 v[196:199], v153 offset:19456
	ds_read_b128 v[200:203], v153 offset:20480
	ds_read_b128 v[208:211], v153 offset:21504
	ds_read_b128 v[212:215], v153 offset:22528
	ds_read_b128 v[216:219], v153 offset:23552
	global_load_lds_dwordx4 v130, s[26:27]
	s_add_i32 m0, s54, 0x2000
	s_add_u32 s54, s26, 0x40000
	s_mov_b64 s[98:99], s[26:27]
	s_addc_u32 s55, s27, 0
	s_add_i32 s56, s46, s38
	global_load_lds_dwordx4 v134, s[26:27]
	s_mov_b32 m0, s56
	s_mov_b64 s[100:101], s[28:29]
	global_load_lds_dwordx4 v130, s[54:55]
	s_add_i32 m0, s56, 0x2000
	s_nop 0
	global_load_lds_dwordx4 v134, s[54:55]
	s_mov_b32 m0, s25
	s_nop 0
	global_load_lds_dwordx4 v128, s[28:29]
	s_mov_b32 m0, s39
	s_nop 0
	global_load_lds_dwordx4 v132, s[28:29]
	s_waitcnt vmcnt(8)
	s_waitcnt lgkmcnt(0)
	s_barrier
	s_waitcnt lgkmcnt(0)
	v_mfma_f32_16x16x32_bf16 v[60:63], v[144:147], v[184:187], v[60:63]
	v_mfma_f32_16x16x32_bf16 v[56:59], v[160:163], v[184:187], v[56:59]
	v_mfma_f32_16x16x32_bf16 v[44:47], v[144:147], v[192:195], v[44:47]
	v_mfma_f32_16x16x32_bf16 v[40:43], v[160:163], v[192:195], v[40:43]
	v_mfma_f32_16x16x32_bf16 v[28:31], v[144:147], v[200:203], v[28:31]
	v_mfma_f32_16x16x32_bf16 v[24:27], v[160:163], v[200:203], v[24:27]
	v_mfma_f32_16x16x32_bf16 v[12:15], v[144:147], v[212:215], v[12:15]
	v_mfma_f32_16x16x32_bf16 v[8:11], v[160:163], v[212:215], v[8:11]
	v_mfma_f32_16x16x32_bf16 v[60:63], v[156:159], v[188:191], v[60:63]
	v_mfma_f32_16x16x32_bf16 v[56:59], v[164:167], v[188:191], v[56:59]
	v_mfma_f32_16x16x32_bf16 v[44:47], v[156:159], v[196:199], v[44:47]
	v_mfma_f32_16x16x32_bf16 v[40:43], v[164:167], v[196:199], v[40:43]
	v_mfma_f32_16x16x32_bf16 v[28:31], v[156:159], v[208:211], v[28:31]
	v_mfma_f32_16x16x32_bf16 v[24:27], v[164:167], v[208:211], v[24:27]
	v_mfma_f32_16x16x32_bf16 v[12:15], v[156:159], v[216:219], v[12:15]
	v_mfma_f32_16x16x32_bf16 v[8:11], v[164:167], v[216:219], v[8:11]
	v_mfma_f32_16x16x32_bf16 v[52:55], v[168:171], v[184:187], v[52:55]
	v_mfma_f32_16x16x32_bf16 v[48:51], v[176:179], v[184:187], v[48:51]
	v_mfma_f32_16x16x32_bf16 v[36:39], v[168:171], v[192:195], v[36:39]
	v_mfma_f32_16x16x32_bf16 v[32:35], v[176:179], v[192:195], v[32:35]
	v_mfma_f32_16x16x32_bf16 v[20:23], v[168:171], v[200:203], v[20:23]
	v_mfma_f32_16x16x32_bf16 v[16:19], v[176:179], v[200:203], v[16:19]
	v_mfma_f32_16x16x32_bf16 v[4:7], v[168:171], v[212:215], v[4:7]
	v_mfma_f32_16x16x32_bf16 v[0:3], v[176:179], v[212:215], v[0:3]
	v_mfma_f32_16x16x32_bf16 v[52:55], v[172:175], v[188:191], v[52:55]
	v_mfma_f32_16x16x32_bf16 v[48:51], v[180:183], v[188:191], v[48:51]
	v_mfma_f32_16x16x32_bf16 v[36:39], v[172:175], v[196:199], v[36:39]
	v_mfma_f32_16x16x32_bf16 v[32:35], v[180:183], v[196:199], v[32:35]
	v_mfma_f32_16x16x32_bf16 v[20:23], v[172:175], v[208:211], v[20:23]
	v_mfma_f32_16x16x32_bf16 v[16:19], v[180:183], v[208:211], v[16:19]
	v_mfma_f32_16x16x32_bf16 v[4:7], v[172:175], v[216:219], v[4:7]
	v_mfma_f32_16x16x32_bf16 v[0:3], v[180:183], v[216:219], v[0:3]
	s_add_i32 s54, 0, 0x18000
	s_barrier
	v_add_u32_e32 v155, s54, v149
	s_add_i32 s55, 0, 0x1c000
	ds_read_b128 v[144:147], v155
	ds_read_b128 v[156:159], v155 offset:1024
	ds_read_b128 v[160:163], v155 offset:2048
	ds_read_b128 v[164:167], v155 offset:3072
	v_add_u32_e32 v155, s55, v149
	ds_read_b128 v[168:171], v155
	ds_read_b128 v[172:175], v155 offset:1024
	ds_read_b128 v[176:179], v155 offset:2048
	ds_read_b128 v[180:183], v155 offset:3072
	s_add_u32 s28, s28, 0x40000
	s_addc_u32 s29, s29, 0
	s_mov_b32 m0, s40
	ds_read_b128 v[184:187], v153 offset:32768
	ds_read_b128 v[188:191], v153 offset:33792
	ds_read_b128 v[192:195], v153 offset:34816
	ds_read_b128 v[196:199], v153 offset:35840
	ds_read_b128 v[200:203], v153 offset:36864
	ds_read_b128 v[208:211], v153 offset:37888
	ds_read_b128 v[212:215], v153 offset:38912
	ds_read_b128 v[216:219], v153 offset:39936
	global_load_lds_dwordx4 v128, s[28:29]
	s_mov_b32 m0, s41
	s_nop 0
	global_load_lds_dwordx4 v132, s[28:29]
	s_waitcnt vmcnt(8)
	s_waitcnt lgkmcnt(0)
	s_barrier
	s_waitcnt lgkmcnt(0)
	v_mfma_f32_16x16x32_bf16 v[124:127], v[144:147], v[184:187], v[124:127]
	v_mfma_f32_16x16x32_bf16 v[120:123], v[160:163], v[184:187], v[120:123]
	v_mfma_f32_16x16x32_bf16 v[108:111], v[144:147], v[192:195], v[108:111]
	v_mfma_f32_16x16x32_bf16 v[104:107], v[160:163], v[192:195], v[104:107]
	v_mfma_f32_16x16x32_bf16 v[92:95], v[144:147], v[200:203], v[92:95]
	v_mfma_f32_16x16x32_bf16 v[88:91], v[160:163], v[200:203], v[88:91]
	v_mfma_f32_16x16x32_bf16 v[76:79], v[144:147], v[212:215], v[76:79]
	v_mfma_f32_16x16x32_bf16 v[72:75], v[160:163], v[212:215], v[72:75]
	v_mfma_f32_16x16x32_bf16 v[124:127], v[156:159], v[188:191], v[124:127]
	v_mfma_f32_16x16x32_bf16 v[120:123], v[164:167], v[188:191], v[120:123]
	v_mfma_f32_16x16x32_bf16 v[108:111], v[156:159], v[196:199], v[108:111]
	v_mfma_f32_16x16x32_bf16 v[104:107], v[164:167], v[196:199], v[104:107]
	v_mfma_f32_16x16x32_bf16 v[92:95], v[156:159], v[208:211], v[92:95]
	v_mfma_f32_16x16x32_bf16 v[88:91], v[164:167], v[208:211], v[88:91]
	v_mfma_f32_16x16x32_bf16 v[76:79], v[156:159], v[216:219], v[76:79]
	v_mfma_f32_16x16x32_bf16 v[72:75], v[164:167], v[216:219], v[72:75]
	v_mfma_f32_16x16x32_bf16 v[116:119], v[168:171], v[184:187], v[116:119]
	v_mfma_f32_16x16x32_bf16 v[112:115], v[176:179], v[184:187], v[112:115]
	v_mfma_f32_16x16x32_bf16 v[100:103], v[168:171], v[192:195], v[100:103]
	v_mfma_f32_16x16x32_bf16 v[96:99], v[176:179], v[192:195], v[96:99]
	v_mfma_f32_16x16x32_bf16 v[84:87], v[168:171], v[200:203], v[84:87]
	v_mfma_f32_16x16x32_bf16 v[80:83], v[176:179], v[200:203], v[80:83]
	v_mfma_f32_16x16x32_bf16 v[68:71], v[168:171], v[212:215], v[68:71]
	v_mfma_f32_16x16x32_bf16 v[64:67], v[176:179], v[212:215], v[64:67]
	v_mfma_f32_16x16x32_bf16 v[116:119], v[172:175], v[188:191], v[116:119]
	v_mfma_f32_16x16x32_bf16 v[112:115], v[180:183], v[188:191], v[112:115]
	v_mfma_f32_16x16x32_bf16 v[100:103], v[172:175], v[196:199], v[100:103]
	v_mfma_f32_16x16x32_bf16 v[96:99], v[180:183], v[196:199], v[96:99]
	v_mfma_f32_16x16x32_bf16 v[84:87], v[172:175], v[208:211], v[84:87]
	v_mfma_f32_16x16x32_bf16 v[80:83], v[180:183], v[208:211], v[80:83]
	v_mfma_f32_16x16x32_bf16 v[68:71], v[172:175], v[216:219], v[68:71]
	v_mfma_f32_16x16x32_bf16 v[64:67], v[180:183], v[216:219], v[64:67]
	s_add_i32 s28, s54, s38
	s_mov_b32 m0, s28
	s_barrier
	ds_read_b128 v[184:187], v153 offset:49152
	ds_read_b128 v[188:191], v153 offset:50176
	ds_read_b128 v[192:195], v153 offset:51200
	ds_read_b128 v[196:199], v153 offset:52224
	ds_read_b128 v[200:203], v153 offset:53248
	ds_read_b128 v[208:211], v153 offset:54272
	ds_read_b128 v[212:215], v153 offset:55296
	ds_read_b128 v[216:219], v153 offset:56320
	global_load_lds_dwordx4 v205, s[26:27]
	s_add_i32 m0, s28, 0x2000
	s_add_u32 s26, s26, 0x40080
	s_addc_u32 s27, s27, 0
	s_add_i32 s28, s55, s38
	global_load_lds_dwordx4 v221, s[98:99]
	s_mov_b32 m0, s28
	s_nop 0
	global_load_lds_dwordx4 v130, s[26:27]
	s_add_i32 m0, s28, 0x2000
	s_nop 0
	global_load_lds_dwordx4 v134, s[26:27]
	s_mov_b32 m0, s43
	s_nop 0
	global_load_lds_dwordx4 v204, s[100:101]
	s_mov_b32 m0, s44
	s_nop 0
	global_load_lds_dwordx4 v220, s[100:101]
	s_waitcnt vmcnt(8)
	s_waitcnt lgkmcnt(0)
	s_barrier
	s_waitcnt lgkmcnt(0)
	v_mfma_f32_16x16x32_bf16 v[60:63], v[144:147], v[184:187], v[60:63]
	v_mfma_f32_16x16x32_bf16 v[56:59], v[160:163], v[184:187], v[56:59]
	v_mfma_f32_16x16x32_bf16 v[44:47], v[144:147], v[192:195], v[44:47]
	v_mfma_f32_16x16x32_bf16 v[40:43], v[160:163], v[192:195], v[40:43]
	v_mfma_f32_16x16x32_bf16 v[28:31], v[144:147], v[200:203], v[28:31]
	v_mfma_f32_16x16x32_bf16 v[24:27], v[160:163], v[200:203], v[24:27]
	v_mfma_f32_16x16x32_bf16 v[12:15], v[144:147], v[212:215], v[12:15]
	v_mfma_f32_16x16x32_bf16 v[8:11], v[160:163], v[212:215], v[8:11]
	v_mfma_f32_16x16x32_bf16 v[60:63], v[156:159], v[188:191], v[60:63]
	v_mfma_f32_16x16x32_bf16 v[56:59], v[164:167], v[188:191], v[56:59]
	v_mfma_f32_16x16x32_bf16 v[44:47], v[156:159], v[196:199], v[44:47]
	v_mfma_f32_16x16x32_bf16 v[40:43], v[164:167], v[196:199], v[40:43]
	v_mfma_f32_16x16x32_bf16 v[28:31], v[156:159], v[208:211], v[28:31]
	v_mfma_f32_16x16x32_bf16 v[24:27], v[164:167], v[208:211], v[24:27]
	v_mfma_f32_16x16x32_bf16 v[12:15], v[156:159], v[216:219], v[12:15]
	v_mfma_f32_16x16x32_bf16 v[8:11], v[164:167], v[216:219], v[8:11]
	v_mfma_f32_16x16x32_bf16 v[52:55], v[168:171], v[184:187], v[52:55]
	v_mfma_f32_16x16x32_bf16 v[48:51], v[176:179], v[184:187], v[48:51]
	v_mfma_f32_16x16x32_bf16 v[36:39], v[168:171], v[192:195], v[36:39]
	v_mfma_f32_16x16x32_bf16 v[32:35], v[176:179], v[192:195], v[32:35]
	v_mfma_f32_16x16x32_bf16 v[20:23], v[168:171], v[200:203], v[20:23]
	v_mfma_f32_16x16x32_bf16 v[16:19], v[176:179], v[200:203], v[16:19]
	v_mfma_f32_16x16x32_bf16 v[4:7], v[168:171], v[212:215], v[4:7]
	v_mfma_f32_16x16x32_bf16 v[0:3], v[176:179], v[212:215], v[0:3]
	v_mfma_f32_16x16x32_bf16 v[52:55], v[172:175], v[188:191], v[52:55]
	v_mfma_f32_16x16x32_bf16 v[48:51], v[180:183], v[188:191], v[48:51]
	v_mfma_f32_16x16x32_bf16 v[36:39], v[172:175], v[196:199], v[36:39]
	v_mfma_f32_16x16x32_bf16 v[32:35], v[180:183], v[196:199], v[32:35]
	v_mfma_f32_16x16x32_bf16 v[20:23], v[172:175], v[208:211], v[20:23]
	v_mfma_f32_16x16x32_bf16 v[16:19], v[180:183], v[208:211], v[16:19]
	v_mfma_f32_16x16x32_bf16 v[4:7], v[172:175], v[216:219], v[4:7]
	v_mfma_f32_16x16x32_bf16 v[0:3], v[180:183], v[216:219], v[0:3]
	s_add_i32 s53, s53, 2
	s_add_u32 s51, s51, 0x100
	s_addc_u32 s52, s52, 0
	s_add_u32 s6, s6, 0x100
	s_addc_u32 s7, s7, 0
	s_cmp_gt_u32 s53, 13
	s_barrier
	s_cbranch_scc0 .LBB0_988
	s_setprio 0
	s_and_b64 vcc, exec, s[14:15]
	s_cbranch_vccz .LBB0_991
	s_barrier

.LBB0_1193:
	ds_read_b128 v[144:147], v151
	ds_read_b128 v[154:157], v151 offset:1024
	ds_read_b128 v[158:161], v151 offset:2048
	ds_read_b128 v[162:165], v151 offset:3072
	ds_read_b128 v[166:169], v152
	ds_read_b128 v[170:173], v152 offset:1024
	ds_read_b128 v[174:177], v152 offset:2048
	ds_read_b128 v[178:181], v152 offset:3072
	s_add_u32 s26, s24, 0xfffe0080
	s_addc_u32 s27, s25, -1
	s_cmp_eq_u32 s50, 4
	s_cselect_b32 s29, s17, s27
	s_cselect_b32 s28, s46, s26
	s_cselect_b32 s27, s15, s49
	s_cselect_b32 s26, s47, s48
	s_add_i32 m0, s23, 0xc000
	ds_read_b128 v[182:185], v153
	ds_read_b128 v[186:189], v153 offset:1024
	ds_read_b128 v[190:193], v153 offset:2048
	ds_read_b128 v[194:197], v153 offset:3072
	ds_read_b128 v[198:201], v153 offset:4096
	ds_read_b128 v[202:205], v153 offset:5120
	ds_read_b128 v[208:211], v153 offset:6144
	ds_read_b128 v[212:215], v153 offset:7168
	global_load_lds_dwordx4 v138, s[24:25]
	s_add_i32 m0, s23, 0xe000
	s_nop 0
	global_load_lds_dwordx4 v136, s[24:25]
	s_waitcnt vmcnt(8)
	s_waitcnt lgkmcnt(0)
	s_barrier
	s_waitcnt lgkmcnt(0)
	v_mfma_f32_16x16x32_bf16 v[124:127], v[144:147], v[182:185], v[124:127]
	v_mfma_f32_16x16x32_bf16 v[120:123], v[158:161], v[182:185], v[120:123]
	v_mfma_f32_16x16x32_bf16 v[108:111], v[144:147], v[190:193], v[108:111]
	v_mfma_f32_16x16x32_bf16 v[104:107], v[158:161], v[190:193], v[104:107]
	v_mfma_f32_16x16x32_bf16 v[92:95], v[144:147], v[198:201], v[92:95]
	v_mfma_f32_16x16x32_bf16 v[88:91], v[158:161], v[198:201], v[88:91]
	v_mfma_f32_16x16x32_bf16 v[76:79], v[144:147], v[208:211], v[76:79]
	v_mfma_f32_16x16x32_bf16 v[72:75], v[158:161], v[208:211], v[72:75]
	v_mfma_f32_16x16x32_bf16 v[124:127], v[154:157], v[186:189], v[124:127]
	v_mfma_f32_16x16x32_bf16 v[120:123], v[162:165], v[186:189], v[120:123]
	v_mfma_f32_16x16x32_bf16 v[108:111], v[154:157], v[194:197], v[108:111]
	v_mfma_f32_16x16x32_bf16 v[104:107], v[162:165], v[194:197], v[104:107]
	v_mfma_f32_16x16x32_bf16 v[92:95], v[154:157], v[202:205], v[92:95]
	v_mfma_f32_16x16x32_bf16 v[88:91], v[162:165], v[202:205], v[88:91]
	v_mfma_f32_16x16x32_bf16 v[76:79], v[154:157], v[212:215], v[76:79]
	v_mfma_f32_16x16x32_bf16 v[72:75], v[162:165], v[212:215], v[72:75]
	v_mfma_f32_16x16x32_bf16 v[116:119], v[166:169], v[182:185], v[116:119]
	v_mfma_f32_16x16x32_bf16 v[112:115], v[174:177], v[182:185], v[112:115]
	v_mfma_f32_16x16x32_bf16 v[100:103], v[166:169], v[190:193], v[100:103]
	v_mfma_f32_16x16x32_bf16 v[96:99], v[174:177], v[190:193], v[96:99]
	v_mfma_f32_16x16x32_bf16 v[84:87], v[166:169], v[198:201], v[84:87]
	v_mfma_f32_16x16x32_bf16 v[80:83], v[174:177], v[198:201], v[80:83]
	v_mfma_f32_16x16x32_bf16 v[68:71], v[166:169], v[208:211], v[68:71]
	v_mfma_f32_16x16x32_bf16 v[64:67], v[174:177], v[208:211], v[64:67]
	v_mfma_f32_16x16x32_bf16 v[116:119], v[170:173], v[186:189], v[116:119]
	v_mfma_f32_16x16x32_bf16 v[112:115], v[178:181], v[186:189], v[112:115]
	v_mfma_f32_16x16x32_bf16 v[100:103], v[170:173], v[194:197], v[100:103]
	v_mfma_f32_16x16x32_bf16 v[96:99], v[178:181], v[194:197], v[96:99]
	v_mfma_f32_16x16x32_bf16 v[84:87], v[170:173], v[202:205], v[84:87]
	v_mfma_f32_16x16x32_bf16 v[80:83], v[178:181], v[202:205], v[80:83]
	v_mfma_f32_16x16x32_bf16 v[68:71], v[170:173], v[212:215], v[68:71]
	v_mfma_f32_16x16x32_bf16 v[64:67], v[178:181], v[212:215], v[64:67]
	s_add_i32 s51, s43, s36
	s_mov_b32 m0, s51
	s_barrier
	ds_read_b128 v[182:185], v153 offset:16384
	ds_read_b128 v[186:189], v153 offset:17408
	ds_read_b128 v[190:193], v153 offset:18432
	ds_read_b128 v[194:197], v153 offset:19456
	ds_read_b128 v[198:201], v153 offset:20480
	ds_read_b128 v[202:205], v153 offset:21504
	ds_read_b128 v[208:211], v153 offset:22528
	ds_read_b128 v[212:215], v153 offset:23552
	global_load_lds_dwordx4 v130, s[26:27]
	s_add_i32 m0, s51, 0x2000
	s_add_u32 s52, s26, 0x20000
	s_mov_b64 s[98:99], s[26:27]
	s_addc_u32 s53, s27, 0
	s_add_i32 s51, s44, s36
	global_load_lds_dwordx4 v134, s[26:27]
	s_mov_b32 m0, s51
	s_mov_b64 s[100:101], s[28:29]
	global_load_lds_dwordx4 v130, s[52:53]
	s_add_i32 m0, s51, 0x2000
	s_nop 0
	global_load_lds_dwordx4 v134, s[52:53]
	s_mov_b32 m0, s23
	s_nop 0
	global_load_lds_dwordx4 v128, s[28:29]
	s_mov_b32 m0, s37
	s_nop 0
	global_load_lds_dwordx4 v132, s[28:29]
	s_waitcnt vmcnt(8)
	s_waitcnt lgkmcnt(0)
	s_barrier
	s_waitcnt lgkmcnt(0)
	v_mfma_f32_16x16x32_bf16 v[60:63], v[144:147], v[182:185], v[60:63]
	v_mfma_f32_16x16x32_bf16 v[56:59], v[158:161], v[182:185], v[56:59]
	v_mfma_f32_16x16x32_bf16 v[44:47], v[144:147], v[190:193], v[44:47]
	v_mfma_f32_16x16x32_bf16 v[40:43], v[158:161], v[190:193], v[40:43]
	v_mfma_f32_16x16x32_bf16 v[28:31], v[144:147], v[198:201], v[28:31]
	v_mfma_f32_16x16x32_bf16 v[24:27], v[158:161], v[198:201], v[24:27]
	v_mfma_f32_16x16x32_bf16 v[12:15], v[144:147], v[208:211], v[12:15]
	v_mfma_f32_16x16x32_bf16 v[8:11], v[158:161], v[208:211], v[8:11]
	v_mfma_f32_16x16x32_bf16 v[60:63], v[154:157], v[186:189], v[60:63]
	v_mfma_f32_16x16x32_bf16 v[56:59], v[162:165], v[186:189], v[56:59]
	v_mfma_f32_16x16x32_bf16 v[44:47], v[154:157], v[194:197], v[44:47]
	v_mfma_f32_16x16x32_bf16 v[40:43], v[162:165], v[194:197], v[40:43]
	v_mfma_f32_16x16x32_bf16 v[28:31], v[154:157], v[202:205], v[28:31]
	v_mfma_f32_16x16x32_bf16 v[24:27], v[162:165], v[202:205], v[24:27]
	v_mfma_f32_16x16x32_bf16 v[12:15], v[154:157], v[212:215], v[12:15]
	v_mfma_f32_16x16x32_bf16 v[8:11], v[162:165], v[212:215], v[8:11]
	v_mfma_f32_16x16x32_bf16 v[52:55], v[166:169], v[182:185], v[52:55]
	v_mfma_f32_16x16x32_bf16 v[48:51], v[174:177], v[182:185], v[48:51]
	v_mfma_f32_16x16x32_bf16 v[36:39], v[166:169], v[190:193], v[36:39]
	v_mfma_f32_16x16x32_bf16 v[32:35], v[174:177], v[190:193], v[32:35]
	v_mfma_f32_16x16x32_bf16 v[20:23], v[166:169], v[198:201], v[20:23]
	v_mfma_f32_16x16x32_bf16 v[16:19], v[174:177], v[198:201], v[16:19]
	v_mfma_f32_16x16x32_bf16 v[4:7], v[166:169], v[208:211], v[4:7]
	v_mfma_f32_16x16x32_bf16 v[0:3], v[174:177], v[208:211], v[0:3]
	v_mfma_f32_16x16x32_bf16 v[52:55], v[170:173], v[186:189], v[52:55]
	v_mfma_f32_16x16x32_bf16 v[48:51], v[178:181], v[186:189], v[48:51]
	v_mfma_f32_16x16x32_bf16 v[36:39], v[170:173], v[194:197], v[36:39]
	v_mfma_f32_16x16x32_bf16 v[32:35], v[178:181], v[194:197], v[32:35]
	v_mfma_f32_16x16x32_bf16 v[20:23], v[170:173], v[202:205], v[20:23]
	v_mfma_f32_16x16x32_bf16 v[16:19], v[178:181], v[202:205], v[16:19]
	v_mfma_f32_16x16x32_bf16 v[4:7], v[170:173], v[212:215], v[4:7]
	v_mfma_f32_16x16x32_bf16 v[0:3], v[178:181], v[212:215], v[0:3]
	s_add_i32 s51, 0, 0x18000
	s_add_i32 s52, 0, 0x1c000
	s_barrier
	v_add_u32_e32 v162, s51, v149
	v_add_u32_e32 v178, s52, v149
	ds_read_b128 v[144:147], v162
	ds_read_b128 v[154:157], v162 offset:1024
	ds_read_b128 v[158:161], v162 offset:2048
	ds_read_b128 v[162:165], v162 offset:3072
	ds_read_b128 v[166:169], v178
	ds_read_b128 v[170:173], v178 offset:1024
	ds_read_b128 v[174:177], v178 offset:2048
	ds_read_b128 v[178:181], v178 offset:3072
	s_add_u32 s28, s28, 0x20000
	s_addc_u32 s29, s29, 0
	s_mov_b32 m0, s38
	ds_read_b128 v[182:185], v153 offset:32768
	ds_read_b128 v[186:189], v153 offset:33792
	ds_read_b128 v[190:193], v153 offset:34816
	ds_read_b128 v[194:197], v153 offset:35840
	ds_read_b128 v[198:201], v153 offset:36864
	ds_read_b128 v[202:205], v153 offset:37888
	ds_read_b128 v[208:211], v153 offset:38912
	ds_read_b128 v[212:215], v153 offset:39936
	global_load_lds_dwordx4 v128, s[28:29]
	s_mov_b32 m0, s39
	s_nop 0
	global_load_lds_dwordx4 v132, s[28:29]
	s_waitcnt vmcnt(8)
	s_waitcnt lgkmcnt(0)
	s_barrier
	s_waitcnt lgkmcnt(0)
	v_mfma_f32_16x16x32_bf16 v[124:127], v[144:147], v[182:185], v[124:127]
	v_mfma_f32_16x16x32_bf16 v[120:123], v[158:161], v[182:185], v[120:123]
	v_mfma_f32_16x16x32_bf16 v[108:111], v[144:147], v[190:193], v[108:111]
	v_mfma_f32_16x16x32_bf16 v[104:107], v[158:161], v[190:193], v[104:107]
	v_mfma_f32_16x16x32_bf16 v[92:95], v[144:147], v[198:201], v[92:95]
	v_mfma_f32_16x16x32_bf16 v[88:91], v[158:161], v[198:201], v[88:91]
	v_mfma_f32_16x16x32_bf16 v[76:79], v[144:147], v[208:211], v[76:79]
	v_mfma_f32_16x16x32_bf16 v[72:75], v[158:161], v[208:211], v[72:75]
	v_mfma_f32_16x16x32_bf16 v[124:127], v[154:157], v[186:189], v[124:127]
	v_mfma_f32_16x16x32_bf16 v[120:123], v[162:165], v[186:189], v[120:123]
	v_mfma_f32_16x16x32_bf16 v[108:111], v[154:157], v[194:197], v[108:111]
	v_mfma_f32_16x16x32_bf16 v[104:107], v[162:165], v[194:197], v[104:107]
	v_mfma_f32_16x16x32_bf16 v[92:95], v[154:157], v[202:205], v[92:95]
	v_mfma_f32_16x16x32_bf16 v[88:91], v[162:165], v[202:205], v[88:91]
	v_mfma_f32_16x16x32_bf16 v[76:79], v[154:157], v[212:215], v[76:79]
	v_mfma_f32_16x16x32_bf16 v[72:75], v[162:165], v[212:215], v[72:75]
	v_mfma_f32_16x16x32_bf16 v[116:119], v[166:169], v[182:185], v[116:119]
	v_mfma_f32_16x16x32_bf16 v[112:115], v[174:177], v[182:185], v[112:115]
	v_mfma_f32_16x16x32_bf16 v[100:103], v[166:169], v[190:193], v[100:103]
	v_mfma_f32_16x16x32_bf16 v[96:99], v[174:177], v[190:193], v[96:99]
	v_mfma_f32_16x16x32_bf16 v[84:87], v[166:169], v[198:201], v[84:87]
	v_mfma_f32_16x16x32_bf16 v[80:83], v[174:177], v[198:201], v[80:83]
	v_mfma_f32_16x16x32_bf16 v[68:71], v[166:169], v[208:211], v[68:71]
	v_mfma_f32_16x16x32_bf16 v[64:67], v[174:177], v[208:211], v[64:67]
	v_mfma_f32_16x16x32_bf16 v[116:119], v[170:173], v[186:189], v[116:119]
	v_mfma_f32_16x16x32_bf16 v[112:115], v[178:181], v[186:189], v[112:115]
	v_mfma_f32_16x16x32_bf16 v[100:103], v[170:173], v[194:197], v[100:103]
	v_mfma_f32_16x16x32_bf16 v[96:99], v[178:181], v[194:197], v[96:99]
	v_mfma_f32_16x16x32_bf16 v[84:87], v[170:173], v[202:205], v[84:87]
	v_mfma_f32_16x16x32_bf16 v[80:83], v[178:181], v[202:205], v[80:83]
	v_mfma_f32_16x16x32_bf16 v[68:71], v[170:173], v[212:215], v[68:71]
	v_mfma_f32_16x16x32_bf16 v[64:67], v[178:181], v[212:215], v[64:67]
	s_add_i32 s28, s51, s36
	s_mov_b32 m0, s28
	s_barrier
	ds_read_b128 v[182:185], v153 offset:49152
	ds_read_b128 v[186:189], v153 offset:50176
	ds_read_b128 v[190:193], v153 offset:51200
	ds_read_b128 v[194:197], v153 offset:52224
	ds_read_b128 v[198:201], v153 offset:53248
	ds_read_b128 v[202:205], v153 offset:54272
	ds_read_b128 v[208:211], v153 offset:55296
	ds_read_b128 v[212:215], v153 offset:56320
	global_load_lds_dwordx4 v217, s[26:27]
	s_add_i32 m0, s28, 0x2000
	s_add_u32 s26, s26, 0x20080
	s_addc_u32 s27, s27, 0
	s_add_i32 s28, s52, s36
	global_load_lds_dwordx4 v219, s[98:99]
	s_mov_b32 m0, s28
	s_nop 0
	global_load_lds_dwordx4 v130, s[26:27]
	s_add_i32 m0, s28, 0x2000
	s_nop 0
	global_load_lds_dwordx4 v134, s[26:27]
	s_mov_b32 m0, s41
	s_nop 0
	global_load_lds_dwordx4 v216, s[100:101]
	s_mov_b32 m0, s42
	s_nop 0
	global_load_lds_dwordx4 v218, s[100:101]
	s_waitcnt vmcnt(8)
	s_waitcnt lgkmcnt(0)
	s_barrier
	s_waitcnt lgkmcnt(0)
	v_mfma_f32_16x16x32_bf16 v[60:63], v[144:147], v[182:185], v[60:63]
	v_mfma_f32_16x16x32_bf16 v[56:59], v[158:161], v[182:185], v[56:59]
	v_mfma_f32_16x16x32_bf16 v[44:47], v[144:147], v[190:193], v[44:47]
	v_mfma_f32_16x16x32_bf16 v[40:43], v[158:161], v[190:193], v[40:43]
	v_mfma_f32_16x16x32_bf16 v[28:31], v[144:147], v[198:201], v[28:31]
	v_mfma_f32_16x16x32_bf16 v[24:27], v[158:161], v[198:201], v[24:27]
	v_mfma_f32_16x16x32_bf16 v[12:15], v[144:147], v[208:211], v[12:15]
	v_mfma_f32_16x16x32_bf16 v[8:11], v[158:161], v[208:211], v[8:11]
	v_mfma_f32_16x16x32_bf16 v[60:63], v[154:157], v[186:189], v[60:63]
	v_mfma_f32_16x16x32_bf16 v[56:59], v[162:165], v[186:189], v[56:59]
	v_mfma_f32_16x16x32_bf16 v[44:47], v[154:157], v[194:197], v[44:47]
	v_mfma_f32_16x16x32_bf16 v[40:43], v[162:165], v[194:197], v[40:43]
	v_mfma_f32_16x16x32_bf16 v[28:31], v[154:157], v[202:205], v[28:31]
	v_mfma_f32_16x16x32_bf16 v[24:27], v[162:165], v[202:205], v[24:27]
	v_mfma_f32_16x16x32_bf16 v[12:15], v[154:157], v[212:215], v[12:15]
	v_mfma_f32_16x16x32_bf16 v[8:11], v[162:165], v[212:215], v[8:11]
	v_mfma_f32_16x16x32_bf16 v[52:55], v[166:169], v[182:185], v[52:55]
	v_mfma_f32_16x16x32_bf16 v[48:51], v[174:177], v[182:185], v[48:51]
	v_mfma_f32_16x16x32_bf16 v[36:39], v[166:169], v[190:193], v[36:39]
	v_mfma_f32_16x16x32_bf16 v[32:35], v[174:177], v[190:193], v[32:35]
	v_mfma_f32_16x16x32_bf16 v[20:23], v[166:169], v[198:201], v[20:23]
	v_mfma_f32_16x16x32_bf16 v[16:19], v[174:177], v[198:201], v[16:19]
	v_mfma_f32_16x16x32_bf16 v[4:7], v[166:169], v[208:211], v[4:7]
	v_mfma_f32_16x16x32_bf16 v[0:3], v[174:177], v[208:211], v[0:3]
	v_mfma_f32_16x16x32_bf16 v[52:55], v[170:173], v[186:189], v[52:55]
	v_mfma_f32_16x16x32_bf16 v[48:51], v[178:181], v[186:189], v[48:51]
	v_mfma_f32_16x16x32_bf16 v[36:39], v[170:173], v[194:197], v[36:39]
	v_mfma_f32_16x16x32_bf16 v[32:35], v[178:181], v[194:197], v[32:35]
	v_mfma_f32_16x16x32_bf16 v[20:23], v[170:173], v[202:205], v[20:23]
	v_mfma_f32_16x16x32_bf16 v[16:19], v[178:181], v[202:205], v[16:19]
	v_mfma_f32_16x16x32_bf16 v[4:7], v[170:173], v[212:215], v[4:7]
	v_mfma_f32_16x16x32_bf16 v[0:3], v[178:181], v[212:215], v[0:3]
	s_add_i32 s50, s50, 2
	s_add_u32 s48, s48, 0x100
	s_addc_u32 s49, s49, 0
	s_add_u32 s24, s24, 0x100
	s_addc_u32 s25, s25, 0
	s_cmp_gt_u32 s50, 5
	s_barrier
	s_cbranch_scc0 .LBB0_1193
	s_setprio 0
	s_and_b64 vcc, exec, s[12:13]
	s_cbranch_vccz .LBB0_1196
	s_barrier

.LBB0_1365:
	ds_read_b128 v[144:147], v151
	ds_read_b128 v[156:159], v151 offset:1024
	ds_read_b128 v[160:163], v151 offset:2048
	ds_read_b128 v[164:167], v151 offset:3072
	ds_read_b128 v[168:171], v152
	ds_read_b128 v[172:175], v152 offset:1024
	ds_read_b128 v[176:179], v152 offset:2048
	ds_read_b128 v[180:183], v152 offset:3072
	s_add_u32 s26, s24, 0xfffc0080
	s_addc_u32 s27, s25, -1
	s_cmp_eq_u32 s53, 12
	s_cselect_b32 s29, s19, s27
	s_cselect_b32 s28, s49, s26
	s_cselect_b32 s27, s17, s52
	s_cselect_b32 s26, s50, s51
	s_add_i32 m0, s39, 0xc000
	ds_read_b128 v[184:187], v153
	ds_read_b128 v[188:191], v153 offset:1024
	ds_read_b128 v[192:195], v153 offset:2048
	ds_read_b128 v[196:199], v153 offset:3072
	ds_read_b128 v[200:203], v153 offset:4096
	ds_read_b128 v[208:211], v153 offset:5120
	ds_read_b128 v[212:215], v153 offset:6144
	ds_read_b128 v[216:219], v153 offset:7168
	global_load_lds_dwordx4 v138, s[24:25]
	s_add_i32 m0, s39, 0xe000
	s_nop 0
	global_load_lds_dwordx4 v136, s[24:25]
	s_waitcnt vmcnt(8)
	s_waitcnt lgkmcnt(0)
	s_barrier
	s_waitcnt lgkmcnt(0)
	v_mfma_f32_16x16x32_bf16 v[124:127], v[144:147], v[184:187], v[124:127]
	v_mfma_f32_16x16x32_bf16 v[120:123], v[160:163], v[184:187], v[120:123]
	v_mfma_f32_16x16x32_bf16 v[108:111], v[144:147], v[192:195], v[108:111]
	v_mfma_f32_16x16x32_bf16 v[104:107], v[160:163], v[192:195], v[104:107]
	v_mfma_f32_16x16x32_bf16 v[92:95], v[144:147], v[200:203], v[92:95]
	v_mfma_f32_16x16x32_bf16 v[88:91], v[160:163], v[200:203], v[88:91]
	v_mfma_f32_16x16x32_bf16 v[76:79], v[144:147], v[212:215], v[76:79]
	v_mfma_f32_16x16x32_bf16 v[72:75], v[160:163], v[212:215], v[72:75]
	v_mfma_f32_16x16x32_bf16 v[124:127], v[156:159], v[188:191], v[124:127]
	v_mfma_f32_16x16x32_bf16 v[120:123], v[164:167], v[188:191], v[120:123]
	v_mfma_f32_16x16x32_bf16 v[108:111], v[156:159], v[196:199], v[108:111]
	v_mfma_f32_16x16x32_bf16 v[104:107], v[164:167], v[196:199], v[104:107]
	v_mfma_f32_16x16x32_bf16 v[92:95], v[156:159], v[208:211], v[92:95]
	v_mfma_f32_16x16x32_bf16 v[88:91], v[164:167], v[208:211], v[88:91]
	v_mfma_f32_16x16x32_bf16 v[76:79], v[156:159], v[216:219], v[76:79]
	v_mfma_f32_16x16x32_bf16 v[72:75], v[164:167], v[216:219], v[72:75]
	v_mfma_f32_16x16x32_bf16 v[116:119], v[168:171], v[184:187], v[116:119]
	v_mfma_f32_16x16x32_bf16 v[112:115], v[176:179], v[184:187], v[112:115]
	v_mfma_f32_16x16x32_bf16 v[100:103], v[168:171], v[192:195], v[100:103]
	v_mfma_f32_16x16x32_bf16 v[96:99], v[176:179], v[192:195], v[96:99]
	v_mfma_f32_16x16x32_bf16 v[84:87], v[168:171], v[200:203], v[84:87]
	v_mfma_f32_16x16x32_bf16 v[80:83], v[176:179], v[200:203], v[80:83]
	v_mfma_f32_16x16x32_bf16 v[68:71], v[168:171], v[212:215], v[68:71]
	v_mfma_f32_16x16x32_bf16 v[64:67], v[176:179], v[212:215], v[64:67]
	v_mfma_f32_16x16x32_bf16 v[116:119], v[172:175], v[188:191], v[116:119]
	v_mfma_f32_16x16x32_bf16 v[112:115], v[180:183], v[188:191], v[112:115]
	v_mfma_f32_16x16x32_bf16 v[100:103], v[172:175], v[196:199], v[100:103]
	v_mfma_f32_16x16x32_bf16 v[96:99], v[180:183], v[196:199], v[96:99]
	v_mfma_f32_16x16x32_bf16 v[84:87], v[172:175], v[208:211], v[84:87]
	v_mfma_f32_16x16x32_bf16 v[80:83], v[180:183], v[208:211], v[80:83]
	v_mfma_f32_16x16x32_bf16 v[68:71], v[172:175], v[216:219], v[68:71]
	v_mfma_f32_16x16x32_bf16 v[64:67], v[180:183], v[216:219], v[64:67]
	s_add_i32 s54, s46, s38
	s_mov_b32 m0, s54
	s_barrier
	ds_read_b128 v[184:187], v153 offset:16384
	ds_read_b128 v[188:191], v153 offset:17408
	ds_read_b128 v[192:195], v153 offset:18432
	ds_read_b128 v[196:199], v153 offset:19456
	ds_read_b128 v[200:203], v153 offset:20480
	ds_read_b128 v[208:211], v153 offset:21504
	ds_read_b128 v[212:215], v153 offset:22528
	ds_read_b128 v[216:219], v153 offset:23552
	global_load_lds_dwordx4 v130, s[26:27]
	s_add_i32 m0, s54, 0x2000
	s_add_u32 s54, s26, 0x40000
	s_mov_b64 s[98:99], s[26:27]
	s_addc_u32 s55, s27, 0
	s_add_i32 s56, s47, s38
	global_load_lds_dwordx4 v134, s[26:27]
	s_mov_b32 m0, s56
	s_mov_b64 s[100:101], s[28:29]
	global_load_lds_dwordx4 v130, s[54:55]
	s_add_i32 m0, s56, 0x2000
	s_nop 0
	global_load_lds_dwordx4 v134, s[54:55]
	s_mov_b32 m0, s39
	s_nop 0
	global_load_lds_dwordx4 v128, s[28:29]
	s_mov_b32 m0, s40
	s_nop 0
	global_load_lds_dwordx4 v132, s[28:29]
	s_waitcnt vmcnt(8)
	s_waitcnt lgkmcnt(0)
	s_barrier
	s_waitcnt lgkmcnt(0)
	v_mfma_f32_16x16x32_bf16 v[60:63], v[144:147], v[184:187], v[60:63]
	v_mfma_f32_16x16x32_bf16 v[56:59], v[160:163], v[184:187], v[56:59]
	v_mfma_f32_16x16x32_bf16 v[44:47], v[144:147], v[192:195], v[44:47]
	v_mfma_f32_16x16x32_bf16 v[40:43], v[160:163], v[192:195], v[40:43]
	v_mfma_f32_16x16x32_bf16 v[28:31], v[144:147], v[200:203], v[28:31]
	v_mfma_f32_16x16x32_bf16 v[24:27], v[160:163], v[200:203], v[24:27]
	v_mfma_f32_16x16x32_bf16 v[12:15], v[144:147], v[212:215], v[12:15]
	v_mfma_f32_16x16x32_bf16 v[8:11], v[160:163], v[212:215], v[8:11]
	v_mfma_f32_16x16x32_bf16 v[60:63], v[156:159], v[188:191], v[60:63]
	v_mfma_f32_16x16x32_bf16 v[56:59], v[164:167], v[188:191], v[56:59]
	v_mfma_f32_16x16x32_bf16 v[44:47], v[156:159], v[196:199], v[44:47]
	v_mfma_f32_16x16x32_bf16 v[40:43], v[164:167], v[196:199], v[40:43]
	v_mfma_f32_16x16x32_bf16 v[28:31], v[156:159], v[208:211], v[28:31]
	v_mfma_f32_16x16x32_bf16 v[24:27], v[164:167], v[208:211], v[24:27]
	v_mfma_f32_16x16x32_bf16 v[12:15], v[156:159], v[216:219], v[12:15]
	v_mfma_f32_16x16x32_bf16 v[8:11], v[164:167], v[216:219], v[8:11]
	v_mfma_f32_16x16x32_bf16 v[52:55], v[168:171], v[184:187], v[52:55]
	v_mfma_f32_16x16x32_bf16 v[48:51], v[176:179], v[184:187], v[48:51]
	v_mfma_f32_16x16x32_bf16 v[36:39], v[168:171], v[192:195], v[36:39]
	v_mfma_f32_16x16x32_bf16 v[32:35], v[176:179], v[192:195], v[32:35]
	v_mfma_f32_16x16x32_bf16 v[20:23], v[168:171], v[200:203], v[20:23]
	v_mfma_f32_16x16x32_bf16 v[16:19], v[176:179], v[200:203], v[16:19]
	v_mfma_f32_16x16x32_bf16 v[4:7], v[168:171], v[212:215], v[4:7]
	v_mfma_f32_16x16x32_bf16 v[0:3], v[176:179], v[212:215], v[0:3]
	v_mfma_f32_16x16x32_bf16 v[52:55], v[172:175], v[188:191], v[52:55]
	v_mfma_f32_16x16x32_bf16 v[48:51], v[180:183], v[188:191], v[48:51]
	v_mfma_f32_16x16x32_bf16 v[36:39], v[172:175], v[196:199], v[36:39]
	v_mfma_f32_16x16x32_bf16 v[32:35], v[180:183], v[196:199], v[32:35]
	v_mfma_f32_16x16x32_bf16 v[20:23], v[172:175], v[208:211], v[20:23]
	v_mfma_f32_16x16x32_bf16 v[16:19], v[180:183], v[208:211], v[16:19]
	v_mfma_f32_16x16x32_bf16 v[4:7], v[172:175], v[216:219], v[4:7]
	v_mfma_f32_16x16x32_bf16 v[0:3], v[180:183], v[216:219], v[0:3]
	s_add_i32 s54, 0, 0x18000
	s_barrier
	v_add_u32_e32 v155, s54, v149
	s_add_i32 s55, 0, 0x1c000
	ds_read_b128 v[144:147], v155
	ds_read_b128 v[156:159], v155 offset:1024
	ds_read_b128 v[160:163], v155 offset:2048
	ds_read_b128 v[164:167], v155 offset:3072
	v_add_u32_e32 v155, s55, v149
	ds_read_b128 v[168:171], v155
	ds_read_b128 v[172:175], v155 offset:1024
	ds_read_b128 v[176:179], v155 offset:2048
	ds_read_b128 v[180:183], v155 offset:3072
	s_add_u32 s28, s28, 0x40000
	s_addc_u32 s29, s29, 0
	s_mov_b32 m0, s41
	ds_read_b128 v[184:187], v153 offset:32768
	ds_read_b128 v[188:191], v153 offset:33792
	ds_read_b128 v[192:195], v153 offset:34816
	ds_read_b128 v[196:199], v153 offset:35840
	ds_read_b128 v[200:203], v153 offset:36864
	ds_read_b128 v[208:211], v153 offset:37888
	ds_read_b128 v[212:215], v153 offset:38912
	ds_read_b128 v[216:219], v153 offset:39936
	global_load_lds_dwordx4 v128, s[28:29]
	s_mov_b32 m0, s42
	s_nop 0
	global_load_lds_dwordx4 v132, s[28:29]
	s_waitcnt vmcnt(8)
	s_waitcnt lgkmcnt(0)
	s_barrier
	s_waitcnt lgkmcnt(0)
	v_mfma_f32_16x16x32_bf16 v[124:127], v[144:147], v[184:187], v[124:127]
	v_mfma_f32_16x16x32_bf16 v[120:123], v[160:163], v[184:187], v[120:123]
	v_mfma_f32_16x16x32_bf16 v[108:111], v[144:147], v[192:195], v[108:111]
	v_mfma_f32_16x16x32_bf16 v[104:107], v[160:163], v[192:195], v[104:107]
	v_mfma_f32_16x16x32_bf16 v[92:95], v[144:147], v[200:203], v[92:95]
	v_mfma_f32_16x16x32_bf16 v[88:91], v[160:163], v[200:203], v[88:91]
	v_mfma_f32_16x16x32_bf16 v[76:79], v[144:147], v[212:215], v[76:79]
	v_mfma_f32_16x16x32_bf16 v[72:75], v[160:163], v[212:215], v[72:75]
	v_mfma_f32_16x16x32_bf16 v[124:127], v[156:159], v[188:191], v[124:127]
	v_mfma_f32_16x16x32_bf16 v[120:123], v[164:167], v[188:191], v[120:123]
	v_mfma_f32_16x16x32_bf16 v[108:111], v[156:159], v[196:199], v[108:111]
	v_mfma_f32_16x16x32_bf16 v[104:107], v[164:167], v[196:199], v[104:107]
	v_mfma_f32_16x16x32_bf16 v[92:95], v[156:159], v[208:211], v[92:95]
	v_mfma_f32_16x16x32_bf16 v[88:91], v[164:167], v[208:211], v[88:91]
	v_mfma_f32_16x16x32_bf16 v[76:79], v[156:159], v[216:219], v[76:79]
	v_mfma_f32_16x16x32_bf16 v[72:75], v[164:167], v[216:219], v[72:75]
	v_mfma_f32_16x16x32_bf16 v[116:119], v[168:171], v[184:187], v[116:119]
	v_mfma_f32_16x16x32_bf16 v[112:115], v[176:179], v[184:187], v[112:115]
	v_mfma_f32_16x16x32_bf16 v[100:103], v[168:171], v[192:195], v[100:103]
	v_mfma_f32_16x16x32_bf16 v[96:99], v[176:179], v[192:195], v[96:99]
	v_mfma_f32_16x16x32_bf16 v[84:87], v[168:171], v[200:203], v[84:87]
	v_mfma_f32_16x16x32_bf16 v[80:83], v[176:179], v[200:203], v[80:83]
	v_mfma_f32_16x16x32_bf16 v[68:71], v[168:171], v[212:215], v[68:71]
	v_mfma_f32_16x16x32_bf16 v[64:67], v[176:179], v[212:215], v[64:67]
	v_mfma_f32_16x16x32_bf16 v[116:119], v[172:175], v[188:191], v[116:119]
	v_mfma_f32_16x16x32_bf16 v[112:115], v[180:183], v[188:191], v[112:115]
	v_mfma_f32_16x16x32_bf16 v[100:103], v[172:175], v[196:199], v[100:103]
	v_mfma_f32_16x16x32_bf16 v[96:99], v[180:183], v[196:199], v[96:99]
	v_mfma_f32_16x16x32_bf16 v[84:87], v[172:175], v[208:211], v[84:87]
	v_mfma_f32_16x16x32_bf16 v[80:83], v[180:183], v[208:211], v[80:83]
	v_mfma_f32_16x16x32_bf16 v[68:71], v[172:175], v[216:219], v[68:71]
	v_mfma_f32_16x16x32_bf16 v[64:67], v[180:183], v[216:219], v[64:67]
	s_add_i32 s28, s54, s38
	s_mov_b32 m0, s28
	s_barrier
	ds_read_b128 v[184:187], v153 offset:49152
	ds_read_b128 v[188:191], v153 offset:50176
	ds_read_b128 v[192:195], v153 offset:51200
	ds_read_b128 v[196:199], v153 offset:52224
	ds_read_b128 v[200:203], v153 offset:53248
	ds_read_b128 v[208:211], v153 offset:54272
	ds_read_b128 v[212:215], v153 offset:55296
	ds_read_b128 v[216:219], v153 offset:56320
	global_load_lds_dwordx4 v205, s[26:27]
	s_add_i32 m0, s28, 0x2000
	s_add_u32 s26, s26, 0x40080
	s_addc_u32 s27, s27, 0
	s_add_i32 s28, s55, s38
	global_load_lds_dwordx4 v221, s[98:99]
	s_mov_b32 m0, s28
	s_nop 0
	global_load_lds_dwordx4 v130, s[26:27]
	s_add_i32 m0, s28, 0x2000
	s_nop 0
	global_load_lds_dwordx4 v134, s[26:27]
	s_mov_b32 m0, s44
	s_nop 0
	global_load_lds_dwordx4 v204, s[100:101]
	s_mov_b32 m0, s45
	s_nop 0
	global_load_lds_dwordx4 v220, s[100:101]
	s_waitcnt vmcnt(8)
	s_waitcnt lgkmcnt(0)
	s_barrier
	s_waitcnt lgkmcnt(0)
	v_mfma_f32_16x16x32_bf16 v[60:63], v[144:147], v[184:187], v[60:63]
	v_mfma_f32_16x16x32_bf16 v[56:59], v[160:163], v[184:187], v[56:59]
	v_mfma_f32_16x16x32_bf16 v[44:47], v[144:147], v[192:195], v[44:47]
	v_mfma_f32_16x16x32_bf16 v[40:43], v[160:163], v[192:195], v[40:43]
	v_mfma_f32_16x16x32_bf16 v[28:31], v[144:147], v[200:203], v[28:31]
	v_mfma_f32_16x16x32_bf16 v[24:27], v[160:163], v[200:203], v[24:27]
	v_mfma_f32_16x16x32_bf16 v[12:15], v[144:147], v[212:215], v[12:15]
	v_mfma_f32_16x16x32_bf16 v[8:11], v[160:163], v[212:215], v[8:11]
	v_mfma_f32_16x16x32_bf16 v[60:63], v[156:159], v[188:191], v[60:63]
	v_mfma_f32_16x16x32_bf16 v[56:59], v[164:167], v[188:191], v[56:59]
	v_mfma_f32_16x16x32_bf16 v[44:47], v[156:159], v[196:199], v[44:47]
	v_mfma_f32_16x16x32_bf16 v[40:43], v[164:167], v[196:199], v[40:43]
	v_mfma_f32_16x16x32_bf16 v[28:31], v[156:159], v[208:211], v[28:31]
	v_mfma_f32_16x16x32_bf16 v[24:27], v[164:167], v[208:211], v[24:27]
	v_mfma_f32_16x16x32_bf16 v[12:15], v[156:159], v[216:219], v[12:15]
	v_mfma_f32_16x16x32_bf16 v[8:11], v[164:167], v[216:219], v[8:11]
	v_mfma_f32_16x16x32_bf16 v[52:55], v[168:171], v[184:187], v[52:55]
	v_mfma_f32_16x16x32_bf16 v[48:51], v[176:179], v[184:187], v[48:51]
	v_mfma_f32_16x16x32_bf16 v[36:39], v[168:171], v[192:195], v[36:39]
	v_mfma_f32_16x16x32_bf16 v[32:35], v[176:179], v[192:195], v[32:35]
	v_mfma_f32_16x16x32_bf16 v[20:23], v[168:171], v[200:203], v[20:23]
	v_mfma_f32_16x16x32_bf16 v[16:19], v[176:179], v[200:203], v[16:19]
	v_mfma_f32_16x16x32_bf16 v[4:7], v[168:171], v[212:215], v[4:7]
	v_mfma_f32_16x16x32_bf16 v[0:3], v[176:179], v[212:215], v[0:3]
	v_mfma_f32_16x16x32_bf16 v[52:55], v[172:175], v[188:191], v[52:55]
	v_mfma_f32_16x16x32_bf16 v[48:51], v[180:183], v[188:191], v[48:51]
	v_mfma_f32_16x16x32_bf16 v[36:39], v[172:175], v[196:199], v[36:39]
	v_mfma_f32_16x16x32_bf16 v[32:35], v[180:183], v[196:199], v[32:35]
	v_mfma_f32_16x16x32_bf16 v[20:23], v[172:175], v[208:211], v[20:23]
	v_mfma_f32_16x16x32_bf16 v[16:19], v[180:183], v[208:211], v[16:19]
	v_mfma_f32_16x16x32_bf16 v[4:7], v[172:175], v[216:219], v[4:7]
	v_mfma_f32_16x16x32_bf16 v[0:3], v[180:183], v[216:219], v[0:3]
	s_add_i32 s53, s53, 2
	s_add_u32 s51, s51, 0x100
	s_addc_u32 s52, s52, 0
	s_add_u32 s24, s24, 0x100
	s_addc_u32 s25, s25, 0
	s_cmp_gt_u32 s53, 13
	s_barrier
	s_cbranch_scc0 .LBB0_1365
	s_setprio 0
	s_and_b64 vcc, exec, s[14:15]
	s_cbranch_vccz .LBB0_1368
	s_barrier

.LBB0_1561:
	ds_read_b128 v[140:143], v151
	ds_read_b128 v[144:147], v151 offset:1024
	ds_read_b128 v[156:159], v151 offset:2048
	ds_read_b128 v[160:163], v151 offset:3072
	ds_read_b128 v[164:167], v152
	ds_read_b128 v[168:171], v152 offset:1024
	ds_read_b128 v[172:175], v152 offset:2048
	ds_read_b128 v[176:179], v152 offset:3072
	s_add_u32 s38, s36, 0xfffc0080
	s_addc_u32 s39, s37, -1
	s_cmp_eq_u32 s61, 12
	s_cselect_b32 s41, s3, s39
	s_cselect_b32 s40, s29, s38
	s_cselect_b32 s39, s27, s60
	s_cselect_b32 s38, s58, s59
	s_add_i32 m0, s46, 0xc000
	ds_read_b128 v[180:183], v153
	ds_read_b128 v[184:187], v153 offset:1024
	ds_read_b128 v[188:191], v153 offset:2048
	ds_read_b128 v[192:195], v153 offset:3072
	ds_read_b128 v[196:199], v153 offset:4096
	ds_read_b128 v[200:203], v153 offset:5120
	ds_read_b128 v[208:211], v153 offset:6144
	ds_read_b128 v[212:215], v153 offset:7168
	global_load_lds_dwordx4 v134, s[36:37]
	s_add_i32 m0, s46, 0xe000
	s_nop 0
	global_load_lds_dwordx4 v132, s[36:37]
	s_waitcnt vmcnt(8)
	s_waitcnt lgkmcnt(0)
	s_barrier
	s_waitcnt lgkmcnt(0)
	v_mfma_f32_16x16x32_bf16 v[124:127], v[140:143], v[180:183], v[124:127]
	v_mfma_f32_16x16x32_bf16 v[120:123], v[156:159], v[180:183], v[120:123]
	v_mfma_f32_16x16x32_bf16 v[108:111], v[140:143], v[188:191], v[108:111]
	v_mfma_f32_16x16x32_bf16 v[104:107], v[156:159], v[188:191], v[104:107]
	v_mfma_f32_16x16x32_bf16 v[92:95], v[140:143], v[196:199], v[92:95]
	v_mfma_f32_16x16x32_bf16 v[88:91], v[156:159], v[196:199], v[88:91]
	v_mfma_f32_16x16x32_bf16 v[76:79], v[140:143], v[208:211], v[76:79]
	v_mfma_f32_16x16x32_bf16 v[72:75], v[156:159], v[208:211], v[72:75]
	v_mfma_f32_16x16x32_bf16 v[124:127], v[144:147], v[184:187], v[124:127]
	v_mfma_f32_16x16x32_bf16 v[120:123], v[160:163], v[184:187], v[120:123]
	v_mfma_f32_16x16x32_bf16 v[108:111], v[144:147], v[192:195], v[108:111]
	v_mfma_f32_16x16x32_bf16 v[104:107], v[160:163], v[192:195], v[104:107]
	v_mfma_f32_16x16x32_bf16 v[92:95], v[144:147], v[200:203], v[92:95]
	v_mfma_f32_16x16x32_bf16 v[88:91], v[160:163], v[200:203], v[88:91]
	v_mfma_f32_16x16x32_bf16 v[76:79], v[144:147], v[212:215], v[76:79]
	v_mfma_f32_16x16x32_bf16 v[72:75], v[160:163], v[212:215], v[72:75]
	v_mfma_f32_16x16x32_bf16 v[116:119], v[164:167], v[180:183], v[116:119]
	v_mfma_f32_16x16x32_bf16 v[112:115], v[172:175], v[180:183], v[112:115]
	v_mfma_f32_16x16x32_bf16 v[100:103], v[164:167], v[188:191], v[100:103]
	v_mfma_f32_16x16x32_bf16 v[96:99], v[172:175], v[188:191], v[96:99]
	v_mfma_f32_16x16x32_bf16 v[84:87], v[164:167], v[196:199], v[84:87]
	v_mfma_f32_16x16x32_bf16 v[80:83], v[172:175], v[196:199], v[80:83]
	v_mfma_f32_16x16x32_bf16 v[68:71], v[164:167], v[208:211], v[68:71]
	v_mfma_f32_16x16x32_bf16 v[64:67], v[172:175], v[208:211], v[64:67]
	v_mfma_f32_16x16x32_bf16 v[116:119], v[168:171], v[184:187], v[116:119]
	v_mfma_f32_16x16x32_bf16 v[112:115], v[176:179], v[184:187], v[112:115]
	v_mfma_f32_16x16x32_bf16 v[100:103], v[168:171], v[192:195], v[100:103]
	v_mfma_f32_16x16x32_bf16 v[96:99], v[176:179], v[192:195], v[96:99]
	v_mfma_f32_16x16x32_bf16 v[84:87], v[168:171], v[200:203], v[84:87]
	v_mfma_f32_16x16x32_bf16 v[80:83], v[176:179], v[200:203], v[80:83]
	v_mfma_f32_16x16x32_bf16 v[68:71], v[168:171], v[212:215], v[68:71]
	v_mfma_f32_16x16x32_bf16 v[64:67], v[176:179], v[212:215], v[64:67]
	s_add_i32 s62, s54, s45
	s_mov_b32 m0, s62
	s_barrier
	ds_read_b128 v[180:183], v153 offset:16384
	ds_read_b128 v[184:187], v153 offset:17408
	ds_read_b128 v[188:191], v153 offset:18432
	ds_read_b128 v[192:195], v153 offset:19456
	ds_read_b128 v[196:199], v153 offset:20480
	ds_read_b128 v[200:203], v153 offset:21504
	ds_read_b128 v[208:211], v153 offset:22528
	ds_read_b128 v[212:215], v153 offset:23552
	global_load_lds_dwordx4 v128, s[38:39]
	s_add_i32 m0, s62, 0x2000
	s_add_u32 s62, s38, 0x40000
	s_mov_b64 s[98:99], s[38:39]
	s_addc_u32 s63, s39, 0
	s_add_i32 s64, s55, s45
	global_load_lds_dwordx4 v130, s[38:39]
	s_mov_b32 m0, s64
	s_mov_b64 s[100:101], s[40:41]
	global_load_lds_dwordx4 v128, s[62:63]
	s_add_i32 m0, s64, 0x2000
	s_nop 0
	global_load_lds_dwordx4 v130, s[62:63]
	s_mov_b32 m0, s46
	s_nop 0
	global_load_lds_dwordx4 v128, s[40:41]
	s_mov_b32 m0, s47
	s_nop 0
	global_load_lds_dwordx4 v130, s[40:41]
	s_waitcnt vmcnt(8)
	s_waitcnt lgkmcnt(0)
	s_barrier
	s_waitcnt lgkmcnt(0)
	v_mfma_f32_16x16x32_bf16 v[60:63], v[140:143], v[180:183], v[60:63]
	v_mfma_f32_16x16x32_bf16 v[56:59], v[156:159], v[180:183], v[56:59]
	v_mfma_f32_16x16x32_bf16 v[44:47], v[140:143], v[188:191], v[44:47]
	v_mfma_f32_16x16x32_bf16 v[40:43], v[156:159], v[188:191], v[40:43]
	v_mfma_f32_16x16x32_bf16 v[28:31], v[140:143], v[196:199], v[28:31]
	v_mfma_f32_16x16x32_bf16 v[24:27], v[156:159], v[196:199], v[24:27]
	v_mfma_f32_16x16x32_bf16 v[12:15], v[140:143], v[208:211], v[12:15]
	v_mfma_f32_16x16x32_bf16 v[8:11], v[156:159], v[208:211], v[8:11]
	v_mfma_f32_16x16x32_bf16 v[60:63], v[144:147], v[184:187], v[60:63]
	v_mfma_f32_16x16x32_bf16 v[56:59], v[160:163], v[184:187], v[56:59]
	v_mfma_f32_16x16x32_bf16 v[44:47], v[144:147], v[192:195], v[44:47]
	v_mfma_f32_16x16x32_bf16 v[40:43], v[160:163], v[192:195], v[40:43]
	v_mfma_f32_16x16x32_bf16 v[28:31], v[144:147], v[200:203], v[28:31]
	v_mfma_f32_16x16x32_bf16 v[24:27], v[160:163], v[200:203], v[24:27]
	v_mfma_f32_16x16x32_bf16 v[12:15], v[144:147], v[212:215], v[12:15]
	v_mfma_f32_16x16x32_bf16 v[8:11], v[160:163], v[212:215], v[8:11]
	v_mfma_f32_16x16x32_bf16 v[52:55], v[164:167], v[180:183], v[52:55]
	v_mfma_f32_16x16x32_bf16 v[48:51], v[172:175], v[180:183], v[48:51]
	v_mfma_f32_16x16x32_bf16 v[36:39], v[164:167], v[188:191], v[36:39]
	v_mfma_f32_16x16x32_bf16 v[32:35], v[172:175], v[188:191], v[32:35]
	v_mfma_f32_16x16x32_bf16 v[20:23], v[164:167], v[196:199], v[20:23]
	v_mfma_f32_16x16x32_bf16 v[16:19], v[172:175], v[196:199], v[16:19]
	v_mfma_f32_16x16x32_bf16 v[4:7], v[164:167], v[208:211], v[4:7]
	v_mfma_f32_16x16x32_bf16 v[0:3], v[172:175], v[208:211], v[0:3]
	v_mfma_f32_16x16x32_bf16 v[52:55], v[168:171], v[184:187], v[52:55]
	v_mfma_f32_16x16x32_bf16 v[48:51], v[176:179], v[184:187], v[48:51]
	v_mfma_f32_16x16x32_bf16 v[36:39], v[168:171], v[192:195], v[36:39]
	v_mfma_f32_16x16x32_bf16 v[32:35], v[176:179], v[192:195], v[32:35]
	v_mfma_f32_16x16x32_bf16 v[20:23], v[168:171], v[200:203], v[20:23]
	v_mfma_f32_16x16x32_bf16 v[16:19], v[176:179], v[200:203], v[16:19]
	v_mfma_f32_16x16x32_bf16 v[4:7], v[168:171], v[212:215], v[4:7]
	v_mfma_f32_16x16x32_bf16 v[0:3], v[176:179], v[212:215], v[0:3]
	s_add_i32 s62, 0, 0x18000
	s_barrier
	v_add_u32_e32 v155, s62, v149
	s_add_i32 s63, 0, 0x1c000
	ds_read_b128 v[140:143], v155
	ds_read_b128 v[144:147], v155 offset:1024
	ds_read_b128 v[156:159], v155 offset:2048
	ds_read_b128 v[160:163], v155 offset:3072
	v_add_u32_e32 v155, s63, v149
	ds_read_b128 v[164:167], v155
	ds_read_b128 v[168:171], v155 offset:1024
	ds_read_b128 v[172:175], v155 offset:2048
	ds_read_b128 v[176:179], v155 offset:3072
	s_add_u32 s40, s40, 0x40000
	s_addc_u32 s41, s41, 0
	s_mov_b32 m0, s48
	ds_read_b128 v[180:183], v153 offset:32768
	ds_read_b128 v[184:187], v153 offset:33792
	ds_read_b128 v[188:191], v153 offset:34816
	ds_read_b128 v[192:195], v153 offset:35840
	ds_read_b128 v[196:199], v153 offset:36864
	ds_read_b128 v[200:203], v153 offset:37888
	ds_read_b128 v[208:211], v153 offset:38912
	ds_read_b128 v[212:215], v153 offset:39936
	global_load_lds_dwordx4 v128, s[40:41]
	s_mov_b32 m0, s49
	s_nop 0
	global_load_lds_dwordx4 v130, s[40:41]
	s_waitcnt vmcnt(8)
	s_waitcnt lgkmcnt(0)
	s_barrier
	s_waitcnt lgkmcnt(0)
	v_mfma_f32_16x16x32_bf16 v[124:127], v[140:143], v[180:183], v[124:127]
	v_mfma_f32_16x16x32_bf16 v[120:123], v[156:159], v[180:183], v[120:123]
	v_mfma_f32_16x16x32_bf16 v[108:111], v[140:143], v[188:191], v[108:111]
	v_mfma_f32_16x16x32_bf16 v[104:107], v[156:159], v[188:191], v[104:107]
	v_mfma_f32_16x16x32_bf16 v[92:95], v[140:143], v[196:199], v[92:95]
	v_mfma_f32_16x16x32_bf16 v[88:91], v[156:159], v[196:199], v[88:91]
	v_mfma_f32_16x16x32_bf16 v[76:79], v[140:143], v[208:211], v[76:79]
	v_mfma_f32_16x16x32_bf16 v[72:75], v[156:159], v[208:211], v[72:75]
	v_mfma_f32_16x16x32_bf16 v[124:127], v[144:147], v[184:187], v[124:127]
	v_mfma_f32_16x16x32_bf16 v[120:123], v[160:163], v[184:187], v[120:123]
	v_mfma_f32_16x16x32_bf16 v[108:111], v[144:147], v[192:195], v[108:111]
	v_mfma_f32_16x16x32_bf16 v[104:107], v[160:163], v[192:195], v[104:107]
	v_mfma_f32_16x16x32_bf16 v[92:95], v[144:147], v[200:203], v[92:95]
	v_mfma_f32_16x16x32_bf16 v[88:91], v[160:163], v[200:203], v[88:91]
	v_mfma_f32_16x16x32_bf16 v[76:79], v[144:147], v[212:215], v[76:79]
	v_mfma_f32_16x16x32_bf16 v[72:75], v[160:163], v[212:215], v[72:75]
	v_mfma_f32_16x16x32_bf16 v[116:119], v[164:167], v[180:183], v[116:119]
	v_mfma_f32_16x16x32_bf16 v[112:115], v[172:175], v[180:183], v[112:115]
	v_mfma_f32_16x16x32_bf16 v[100:103], v[164:167], v[188:191], v[100:103]
	v_mfma_f32_16x16x32_bf16 v[96:99], v[172:175], v[188:191], v[96:99]
	v_mfma_f32_16x16x32_bf16 v[84:87], v[164:167], v[196:199], v[84:87]
	v_mfma_f32_16x16x32_bf16 v[80:83], v[172:175], v[196:199], v[80:83]
	v_mfma_f32_16x16x32_bf16 v[68:71], v[164:167], v[208:211], v[68:71]
	v_mfma_f32_16x16x32_bf16 v[64:67], v[172:175], v[208:211], v[64:67]
	v_mfma_f32_16x16x32_bf16 v[116:119], v[168:171], v[184:187], v[116:119]
	v_mfma_f32_16x16x32_bf16 v[112:115], v[176:179], v[184:187], v[112:115]
	v_mfma_f32_16x16x32_bf16 v[100:103], v[168:171], v[192:195], v[100:103]
	v_mfma_f32_16x16x32_bf16 v[96:99], v[176:179], v[192:195], v[96:99]
	v_mfma_f32_16x16x32_bf16 v[84:87], v[168:171], v[200:203], v[84:87]
	v_mfma_f32_16x16x32_bf16 v[80:83], v[176:179], v[200:203], v[80:83]
	v_mfma_f32_16x16x32_bf16 v[68:71], v[168:171], v[212:215], v[68:71]
	v_mfma_f32_16x16x32_bf16 v[64:67], v[176:179], v[212:215], v[64:67]
	s_add_i32 s40, s62, s45
	s_mov_b32 m0, s40
	s_barrier
	ds_read_b128 v[180:183], v153 offset:49152
	ds_read_b128 v[184:187], v153 offset:50176
	ds_read_b128 v[188:191], v153 offset:51200
	ds_read_b128 v[192:195], v153 offset:52224
	ds_read_b128 v[196:199], v153 offset:53248
	ds_read_b128 v[200:203], v153 offset:54272
	ds_read_b128 v[208:211], v153 offset:55296
	ds_read_b128 v[212:215], v153 offset:56320
	global_load_lds_dwordx4 v204, s[38:39]
	s_add_i32 m0, s40, 0x2000
	s_add_u32 s38, s38, 0x40080
	s_addc_u32 s39, s39, 0
	s_add_i32 s40, s63, s45
	global_load_lds_dwordx4 v205, s[98:99]
	s_mov_b32 m0, s40
	s_nop 0
	global_load_lds_dwordx4 v128, s[38:39]
	s_add_i32 m0, s40, 0x2000
	s_nop 0
	global_load_lds_dwordx4 v130, s[38:39]
	s_mov_b32 m0, s51
	s_nop 0
	global_load_lds_dwordx4 v204, s[100:101]
	s_mov_b32 m0, s52
	s_nop 0
	global_load_lds_dwordx4 v205, s[100:101]
	s_waitcnt vmcnt(8)
	s_waitcnt lgkmcnt(0)
	s_barrier
	s_waitcnt lgkmcnt(0)
	v_mfma_f32_16x16x32_bf16 v[60:63], v[140:143], v[180:183], v[60:63]
	v_mfma_f32_16x16x32_bf16 v[56:59], v[156:159], v[180:183], v[56:59]
	v_mfma_f32_16x16x32_bf16 v[44:47], v[140:143], v[188:191], v[44:47]
	v_mfma_f32_16x16x32_bf16 v[40:43], v[156:159], v[188:191], v[40:43]
	v_mfma_f32_16x16x32_bf16 v[28:31], v[140:143], v[196:199], v[28:31]
	v_mfma_f32_16x16x32_bf16 v[24:27], v[156:159], v[196:199], v[24:27]
	v_mfma_f32_16x16x32_bf16 v[12:15], v[140:143], v[208:211], v[12:15]
	v_mfma_f32_16x16x32_bf16 v[8:11], v[156:159], v[208:211], v[8:11]
	v_mfma_f32_16x16x32_bf16 v[60:63], v[144:147], v[184:187], v[60:63]
	v_mfma_f32_16x16x32_bf16 v[56:59], v[160:163], v[184:187], v[56:59]
	v_mfma_f32_16x16x32_bf16 v[44:47], v[144:147], v[192:195], v[44:47]
	v_mfma_f32_16x16x32_bf16 v[40:43], v[160:163], v[192:195], v[40:43]
	v_mfma_f32_16x16x32_bf16 v[28:31], v[144:147], v[200:203], v[28:31]
	v_mfma_f32_16x16x32_bf16 v[24:27], v[160:163], v[200:203], v[24:27]
	v_mfma_f32_16x16x32_bf16 v[12:15], v[144:147], v[212:215], v[12:15]
	v_mfma_f32_16x16x32_bf16 v[8:11], v[160:163], v[212:215], v[8:11]
	v_mfma_f32_16x16x32_bf16 v[52:55], v[164:167], v[180:183], v[52:55]
	v_mfma_f32_16x16x32_bf16 v[48:51], v[172:175], v[180:183], v[48:51]
	v_mfma_f32_16x16x32_bf16 v[36:39], v[164:167], v[188:191], v[36:39]
	v_mfma_f32_16x16x32_bf16 v[32:35], v[172:175], v[188:191], v[32:35]
	v_mfma_f32_16x16x32_bf16 v[20:23], v[164:167], v[196:199], v[20:23]
	v_mfma_f32_16x16x32_bf16 v[16:19], v[172:175], v[196:199], v[16:19]
	v_mfma_f32_16x16x32_bf16 v[4:7], v[164:167], v[208:211], v[4:7]
	v_mfma_f32_16x16x32_bf16 v[0:3], v[172:175], v[208:211], v[0:3]
	v_mfma_f32_16x16x32_bf16 v[52:55], v[168:171], v[184:187], v[52:55]
	v_mfma_f32_16x16x32_bf16 v[48:51], v[176:179], v[184:187], v[48:51]
	v_mfma_f32_16x16x32_bf16 v[36:39], v[168:171], v[192:195], v[36:39]
	v_mfma_f32_16x16x32_bf16 v[32:35], v[176:179], v[192:195], v[32:35]
	v_mfma_f32_16x16x32_bf16 v[20:23], v[168:171], v[200:203], v[20:23]
	v_mfma_f32_16x16x32_bf16 v[16:19], v[176:179], v[200:203], v[16:19]
	v_mfma_f32_16x16x32_bf16 v[4:7], v[168:171], v[212:215], v[4:7]
	v_mfma_f32_16x16x32_bf16 v[0:3], v[176:179], v[212:215], v[0:3]
	s_add_i32 s61, s61, 2
	s_add_u32 s59, s59, 0x100
	s_addc_u32 s60, s60, 0
	s_add_u32 s36, s36, 0x100
	s_addc_u32 s37, s37, 0
	s_cmp_gt_u32 s61, 13
	s_barrier
	s_cbranch_scc0 .LBB0_1561
	s_setprio 0
	s_and_b64 vcc, exec, s[24:25]
	s_cbranch_vccz .LBB0_1564
	s_barrier

.LBB0_1646:
	ds_read_b128 v[144:147], v151
	ds_read_b128 v[156:159], v151 offset:1024
	ds_read_b128 v[160:163], v151 offset:2048
	ds_read_b128 v[164:167], v151 offset:3072
	ds_read_b128 v[168:171], v152
	ds_read_b128 v[172:175], v152 offset:1024
	ds_read_b128 v[176:179], v152 offset:2048
	ds_read_b128 v[180:183], v152 offset:3072
	s_add_u32 s26, s24, 0xfffc0080
	s_addc_u32 s27, s25, -1
	s_cmp_eq_u32 s54, 12
	s_cselect_b32 s29, s19, s27
	s_cselect_b32 s28, s50, s26
	s_cselect_b32 s27, s17, s53
	s_cselect_b32 s26, s51, s52
	s_add_i32 m0, s38, 0xc000
	ds_read_b128 v[184:187], v153
	ds_read_b128 v[188:191], v153 offset:1024
	ds_read_b128 v[192:195], v153 offset:2048
	ds_read_b128 v[196:199], v153 offset:3072
	ds_read_b128 v[200:203], v153 offset:4096
	ds_read_b128 v[208:211], v153 offset:5120
	ds_read_b128 v[212:215], v153 offset:6144
	ds_read_b128 v[216:219], v153 offset:7168
	global_load_lds_dwordx4 v138, s[24:25]
	s_add_i32 m0, s38, 0xe000
	s_nop 0
	global_load_lds_dwordx4 v136, s[24:25]
	s_waitcnt vmcnt(8)
	s_waitcnt lgkmcnt(0)
	s_barrier
	s_waitcnt lgkmcnt(0)
	v_mfma_f32_16x16x32_bf16 v[124:127], v[144:147], v[184:187], v[124:127]
	v_mfma_f32_16x16x32_bf16 v[120:123], v[160:163], v[184:187], v[120:123]
	v_mfma_f32_16x16x32_bf16 v[108:111], v[144:147], v[192:195], v[108:111]
	v_mfma_f32_16x16x32_bf16 v[104:107], v[160:163], v[192:195], v[104:107]
	v_mfma_f32_16x16x32_bf16 v[92:95], v[144:147], v[200:203], v[92:95]
	v_mfma_f32_16x16x32_bf16 v[88:91], v[160:163], v[200:203], v[88:91]
	v_mfma_f32_16x16x32_bf16 v[76:79], v[144:147], v[212:215], v[76:79]
	v_mfma_f32_16x16x32_bf16 v[72:75], v[160:163], v[212:215], v[72:75]
	v_mfma_f32_16x16x32_bf16 v[124:127], v[156:159], v[188:191], v[124:127]
	v_mfma_f32_16x16x32_bf16 v[120:123], v[164:167], v[188:191], v[120:123]
	v_mfma_f32_16x16x32_bf16 v[108:111], v[156:159], v[196:199], v[108:111]
	v_mfma_f32_16x16x32_bf16 v[104:107], v[164:167], v[196:199], v[104:107]
	v_mfma_f32_16x16x32_bf16 v[92:95], v[156:159], v[208:211], v[92:95]
	v_mfma_f32_16x16x32_bf16 v[88:91], v[164:167], v[208:211], v[88:91]
	v_mfma_f32_16x16x32_bf16 v[76:79], v[156:159], v[216:219], v[76:79]
	v_mfma_f32_16x16x32_bf16 v[72:75], v[164:167], v[216:219], v[72:75]
	v_mfma_f32_16x16x32_bf16 v[116:119], v[168:171], v[184:187], v[116:119]
	v_mfma_f32_16x16x32_bf16 v[112:115], v[176:179], v[184:187], v[112:115]
	v_mfma_f32_16x16x32_bf16 v[100:103], v[168:171], v[192:195], v[100:103]
	v_mfma_f32_16x16x32_bf16 v[96:99], v[176:179], v[192:195], v[96:99]
	v_mfma_f32_16x16x32_bf16 v[84:87], v[168:171], v[200:203], v[84:87]
	v_mfma_f32_16x16x32_bf16 v[80:83], v[176:179], v[200:203], v[80:83]
	v_mfma_f32_16x16x32_bf16 v[68:71], v[168:171], v[212:215], v[68:71]
	v_mfma_f32_16x16x32_bf16 v[64:67], v[176:179], v[212:215], v[64:67]
	v_mfma_f32_16x16x32_bf16 v[116:119], v[172:175], v[188:191], v[116:119]
	v_mfma_f32_16x16x32_bf16 v[112:115], v[180:183], v[188:191], v[112:115]
	v_mfma_f32_16x16x32_bf16 v[100:103], v[172:175], v[196:199], v[100:103]
	v_mfma_f32_16x16x32_bf16 v[96:99], v[180:183], v[196:199], v[96:99]
	v_mfma_f32_16x16x32_bf16 v[84:87], v[172:175], v[208:211], v[84:87]
	v_mfma_f32_16x16x32_bf16 v[80:83], v[180:183], v[208:211], v[80:83]
	v_mfma_f32_16x16x32_bf16 v[68:71], v[172:175], v[216:219], v[68:71]
	v_mfma_f32_16x16x32_bf16 v[64:67], v[180:183], v[216:219], v[64:67]
	s_add_i32 s55, s47, s35
	s_mov_b32 m0, s55
	s_barrier
	ds_read_b128 v[184:187], v153 offset:16384
	ds_read_b128 v[188:191], v153 offset:17408
	ds_read_b128 v[192:195], v153 offset:18432
	ds_read_b128 v[196:199], v153 offset:19456
	ds_read_b128 v[200:203], v153 offset:20480
	ds_read_b128 v[208:211], v153 offset:21504
	ds_read_b128 v[212:215], v153 offset:22528
	ds_read_b128 v[216:219], v153 offset:23552
	global_load_lds_dwordx4 v132, s[26:27]
	s_add_i32 m0, s55, 0x2000
	s_add_u32 s56, s26, 0x40000
	s_mov_b64 s[98:99], s[26:27]
	s_addc_u32 s57, s27, 0
	s_add_i32 s55, s48, s35
	global_load_lds_dwordx4 v128, s[26:27]
	s_mov_b32 m0, s55
	s_mov_b64 s[100:101], s[28:29]
	global_load_lds_dwordx4 v132, s[56:57]
	s_add_i32 m0, s55, 0x2000
	s_nop 0
	global_load_lds_dwordx4 v128, s[56:57]
	s_mov_b32 m0, s38
	s_nop 0
	global_load_lds_dwordx4 v134, s[28:29]
	s_mov_b32 m0, s39
	s_nop 0
	global_load_lds_dwordx4 v130, s[28:29]
	s_waitcnt vmcnt(8)
	s_waitcnt lgkmcnt(0)
	s_barrier
	s_waitcnt lgkmcnt(0)
	v_mfma_f32_16x16x32_bf16 v[60:63], v[144:147], v[184:187], v[60:63]
	v_mfma_f32_16x16x32_bf16 v[56:59], v[160:163], v[184:187], v[56:59]
	v_mfma_f32_16x16x32_bf16 v[44:47], v[144:147], v[192:195], v[44:47]
	v_mfma_f32_16x16x32_bf16 v[40:43], v[160:163], v[192:195], v[40:43]
	v_mfma_f32_16x16x32_bf16 v[28:31], v[144:147], v[200:203], v[28:31]
	v_mfma_f32_16x16x32_bf16 v[24:27], v[160:163], v[200:203], v[24:27]
	v_mfma_f32_16x16x32_bf16 v[12:15], v[144:147], v[212:215], v[12:15]
	v_mfma_f32_16x16x32_bf16 v[8:11], v[160:163], v[212:215], v[8:11]
	v_mfma_f32_16x16x32_bf16 v[60:63], v[156:159], v[188:191], v[60:63]
	v_mfma_f32_16x16x32_bf16 v[56:59], v[164:167], v[188:191], v[56:59]
	v_mfma_f32_16x16x32_bf16 v[44:47], v[156:159], v[196:199], v[44:47]
	v_mfma_f32_16x16x32_bf16 v[40:43], v[164:167], v[196:199], v[40:43]
	v_mfma_f32_16x16x32_bf16 v[28:31], v[156:159], v[208:211], v[28:31]
	v_mfma_f32_16x16x32_bf16 v[24:27], v[164:167], v[208:211], v[24:27]
	v_mfma_f32_16x16x32_bf16 v[12:15], v[156:159], v[216:219], v[12:15]
	v_mfma_f32_16x16x32_bf16 v[8:11], v[164:167], v[216:219], v[8:11]
	v_mfma_f32_16x16x32_bf16 v[52:55], v[168:171], v[184:187], v[52:55]
	v_mfma_f32_16x16x32_bf16 v[48:51], v[176:179], v[184:187], v[48:51]
	v_mfma_f32_16x16x32_bf16 v[36:39], v[168:171], v[192:195], v[36:39]
	v_mfma_f32_16x16x32_bf16 v[32:35], v[176:179], v[192:195], v[32:35]
	v_mfma_f32_16x16x32_bf16 v[20:23], v[168:171], v[200:203], v[20:23]
	v_mfma_f32_16x16x32_bf16 v[16:19], v[176:179], v[200:203], v[16:19]
	v_mfma_f32_16x16x32_bf16 v[4:7], v[168:171], v[212:215], v[4:7]
	v_mfma_f32_16x16x32_bf16 v[0:3], v[176:179], v[212:215], v[0:3]
	v_mfma_f32_16x16x32_bf16 v[52:55], v[172:175], v[188:191], v[52:55]
	v_mfma_f32_16x16x32_bf16 v[48:51], v[180:183], v[188:191], v[48:51]
	v_mfma_f32_16x16x32_bf16 v[36:39], v[172:175], v[196:199], v[36:39]
	v_mfma_f32_16x16x32_bf16 v[32:35], v[180:183], v[196:199], v[32:35]
	v_mfma_f32_16x16x32_bf16 v[20:23], v[172:175], v[208:211], v[20:23]
	v_mfma_f32_16x16x32_bf16 v[16:19], v[180:183], v[208:211], v[16:19]
	v_mfma_f32_16x16x32_bf16 v[4:7], v[172:175], v[216:219], v[4:7]
	v_mfma_f32_16x16x32_bf16 v[0:3], v[180:183], v[216:219], v[0:3]
	s_add_i32 s55, 0, 0x18000
	s_add_i32 s56, 0, 0x1c000
	s_barrier
	v_add_u32_e32 v164, s55, v149
	v_add_u32_e32 v180, s56, v149
	ds_read_b128 v[144:147], v164
	ds_read_b128 v[156:159], v164 offset:1024
	ds_read_b128 v[160:163], v164 offset:2048
	ds_read_b128 v[164:167], v164 offset:3072
	ds_read_b128 v[168:171], v180
	ds_read_b128 v[172:175], v180 offset:1024
	ds_read_b128 v[176:179], v180 offset:2048
	ds_read_b128 v[180:183], v180 offset:3072
	s_add_u32 s28, s28, 0x40000
	s_addc_u32 s29, s29, 0
	s_mov_b32 m0, s40
	ds_read_b128 v[184:187], v153 offset:32768
	ds_read_b128 v[188:191], v153 offset:33792
	ds_read_b128 v[192:195], v153 offset:34816
	ds_read_b128 v[196:199], v153 offset:35840
	ds_read_b128 v[200:203], v153 offset:36864
	ds_read_b128 v[208:211], v153 offset:37888
	ds_read_b128 v[212:215], v153 offset:38912
	ds_read_b128 v[216:219], v153 offset:39936
	global_load_lds_dwordx4 v134, s[28:29]
	s_mov_b32 m0, s41
	s_nop 0
	global_load_lds_dwordx4 v130, s[28:29]
	s_waitcnt vmcnt(8)
	s_waitcnt lgkmcnt(0)
	s_barrier
	s_waitcnt lgkmcnt(0)
	v_mfma_f32_16x16x32_bf16 v[124:127], v[144:147], v[184:187], v[124:127]
	v_mfma_f32_16x16x32_bf16 v[120:123], v[160:163], v[184:187], v[120:123]
	v_mfma_f32_16x16x32_bf16 v[108:111], v[144:147], v[192:195], v[108:111]
	v_mfma_f32_16x16x32_bf16 v[104:107], v[160:163], v[192:195], v[104:107]
	v_mfma_f32_16x16x32_bf16 v[92:95], v[144:147], v[200:203], v[92:95]
	v_mfma_f32_16x16x32_bf16 v[88:91], v[160:163], v[200:203], v[88:91]
	v_mfma_f32_16x16x32_bf16 v[76:79], v[144:147], v[212:215], v[76:79]
	v_mfma_f32_16x16x32_bf16 v[72:75], v[160:163], v[212:215], v[72:75]
	v_mfma_f32_16x16x32_bf16 v[124:127], v[156:159], v[188:191], v[124:127]
	v_mfma_f32_16x16x32_bf16 v[120:123], v[164:167], v[188:191], v[120:123]
	v_mfma_f32_16x16x32_bf16 v[108:111], v[156:159], v[196:199], v[108:111]
	v_mfma_f32_16x16x32_bf16 v[104:107], v[164:167], v[196:199], v[104:107]
	v_mfma_f32_16x16x32_bf16 v[92:95], v[156:159], v[208:211], v[92:95]
	v_mfma_f32_16x16x32_bf16 v[88:91], v[164:167], v[208:211], v[88:91]
	v_mfma_f32_16x16x32_bf16 v[76:79], v[156:159], v[216:219], v[76:79]
	v_mfma_f32_16x16x32_bf16 v[72:75], v[164:167], v[216:219], v[72:75]
	v_mfma_f32_16x16x32_bf16 v[116:119], v[168:171], v[184:187], v[116:119]
	v_mfma_f32_16x16x32_bf16 v[112:115], v[176:179], v[184:187], v[112:115]
	v_mfma_f32_16x16x32_bf16 v[100:103], v[168:171], v[192:195], v[100:103]
	v_mfma_f32_16x16x32_bf16 v[96:99], v[176:179], v[192:195], v[96:99]
	v_mfma_f32_16x16x32_bf16 v[84:87], v[168:171], v[200:203], v[84:87]
	v_mfma_f32_16x16x32_bf16 v[80:83], v[176:179], v[200:203], v[80:83]
	v_mfma_f32_16x16x32_bf16 v[68:71], v[168:171], v[212:215], v[68:71]
	v_mfma_f32_16x16x32_bf16 v[64:67], v[176:179], v[212:215], v[64:67]
	v_mfma_f32_16x16x32_bf16 v[116:119], v[172:175], v[188:191], v[116:119]
	v_mfma_f32_16x16x32_bf16 v[112:115], v[180:183], v[188:191], v[112:115]
	v_mfma_f32_16x16x32_bf16 v[100:103], v[172:175], v[196:199], v[100:103]
	v_mfma_f32_16x16x32_bf16 v[96:99], v[180:183], v[196:199], v[96:99]
	v_mfma_f32_16x16x32_bf16 v[84:87], v[172:175], v[208:211], v[84:87]
	v_mfma_f32_16x16x32_bf16 v[80:83], v[180:183], v[208:211], v[80:83]
	v_mfma_f32_16x16x32_bf16 v[68:71], v[172:175], v[216:219], v[68:71]
	v_mfma_f32_16x16x32_bf16 v[64:67], v[180:183], v[216:219], v[64:67]
	s_add_i32 s28, s55, s35
	s_mov_b32 m0, s28
	s_barrier
	ds_read_b128 v[184:187], v153 offset:49152
	ds_read_b128 v[188:191], v153 offset:50176
	ds_read_b128 v[192:195], v153 offset:51200
	ds_read_b128 v[196:199], v153 offset:52224
	ds_read_b128 v[200:203], v153 offset:53248
	ds_read_b128 v[208:211], v153 offset:54272
	ds_read_b128 v[212:215], v153 offset:55296
	ds_read_b128 v[216:219], v153 offset:56320
	global_load_lds_dwordx4 v220, s[26:27]
	s_add_i32 m0, s28, 0x2000
	s_add_u32 s26, s26, 0x40080
	s_addc_u32 s27, s27, 0
	s_add_i32 s28, s56, s35
	global_load_lds_dwordx4 v204, s[98:99]
	s_mov_b32 m0, s28
	s_nop 0
	global_load_lds_dwordx4 v132, s[26:27]
	s_add_i32 m0, s28, 0x2000
	s_nop 0
	global_load_lds_dwordx4 v128, s[26:27]
	s_mov_b32 m0, s45
	s_nop 0
	global_load_lds_dwordx4 v221, s[100:101]
	s_mov_b32 m0, s46
	s_nop 0
	global_load_lds_dwordx4 v205, s[100:101]
	s_waitcnt vmcnt(8)
	s_waitcnt lgkmcnt(0)
	s_barrier
	s_waitcnt lgkmcnt(0)
	v_mfma_f32_16x16x32_bf16 v[60:63], v[144:147], v[184:187], v[60:63]
	v_mfma_f32_16x16x32_bf16 v[56:59], v[160:163], v[184:187], v[56:59]
	v_mfma_f32_16x16x32_bf16 v[44:47], v[144:147], v[192:195], v[44:47]
	v_mfma_f32_16x16x32_bf16 v[40:43], v[160:163], v[192:195], v[40:43]
	v_mfma_f32_16x16x32_bf16 v[28:31], v[144:147], v[200:203], v[28:31]
	v_mfma_f32_16x16x32_bf16 v[24:27], v[160:163], v[200:203], v[24:27]
	v_mfma_f32_16x16x32_bf16 v[12:15], v[144:147], v[212:215], v[12:15]
	v_mfma_f32_16x16x32_bf16 v[8:11], v[160:163], v[212:215], v[8:11]
	v_mfma_f32_16x16x32_bf16 v[60:63], v[156:159], v[188:191], v[60:63]
	v_mfma_f32_16x16x32_bf16 v[56:59], v[164:167], v[188:191], v[56:59]
	v_mfma_f32_16x16x32_bf16 v[44:47], v[156:159], v[196:199], v[44:47]
	v_mfma_f32_16x16x32_bf16 v[40:43], v[164:167], v[196:199], v[40:43]
	v_mfma_f32_16x16x32_bf16 v[28:31], v[156:159], v[208:211], v[28:31]
	v_mfma_f32_16x16x32_bf16 v[24:27], v[164:167], v[208:211], v[24:27]
	v_mfma_f32_16x16x32_bf16 v[12:15], v[156:159], v[216:219], v[12:15]
	v_mfma_f32_16x16x32_bf16 v[8:11], v[164:167], v[216:219], v[8:11]
	v_mfma_f32_16x16x32_bf16 v[52:55], v[168:171], v[184:187], v[52:55]
	v_mfma_f32_16x16x32_bf16 v[48:51], v[176:179], v[184:187], v[48:51]
	v_mfma_f32_16x16x32_bf16 v[36:39], v[168:171], v[192:195], v[36:39]
	v_mfma_f32_16x16x32_bf16 v[32:35], v[176:179], v[192:195], v[32:35]
	v_mfma_f32_16x16x32_bf16 v[20:23], v[168:171], v[200:203], v[20:23]
	v_mfma_f32_16x16x32_bf16 v[16:19], v[176:179], v[200:203], v[16:19]
	v_mfma_f32_16x16x32_bf16 v[4:7], v[168:171], v[212:215], v[4:7]
	v_mfma_f32_16x16x32_bf16 v[0:3], v[176:179], v[212:215], v[0:3]
	v_mfma_f32_16x16x32_bf16 v[52:55], v[172:175], v[188:191], v[52:55]
	v_mfma_f32_16x16x32_bf16 v[48:51], v[180:183], v[188:191], v[48:51]
	v_mfma_f32_16x16x32_bf16 v[36:39], v[172:175], v[196:199], v[36:39]
	v_mfma_f32_16x16x32_bf16 v[32:35], v[180:183], v[196:199], v[32:35]
	v_mfma_f32_16x16x32_bf16 v[20:23], v[172:175], v[208:211], v[20:23]
	v_mfma_f32_16x16x32_bf16 v[16:19], v[180:183], v[208:211], v[16:19]
	v_mfma_f32_16x16x32_bf16 v[4:7], v[172:175], v[216:219], v[4:7]
	v_mfma_f32_16x16x32_bf16 v[0:3], v[180:183], v[216:219], v[0:3]
	s_add_i32 s54, s54, 2
	s_add_u32 s52, s52, 0x100
	s_addc_u32 s53, s53, 0
	s_add_u32 s24, s24, 0x100
	s_addc_u32 s25, s25, 0
	s_cmp_gt_u32 s54, 13
	s_barrier
	s_cbranch_scc0 .LBB0_1646
	s_setprio 0
	s_and_b64 vcc, exec, s[14:15]
	s_cbranch_vccz .LBB0_1649
	s_barrier
